# saddr LDS-DMA with M0 written two SALU ops ahead of each load; dead gelu pre-products removed from the gmlp_in epilogue head
# baseline (speedup 1.0000x reference)
.LBB0_114:
	v_mov_b32_e32 v6, v181
	s_ashr_i32 s93, s92, 6
	v_lshrrev_b32_e32 v7, 4, v6
	v_lshlrev_b32_e32 v1, 6, v6
	v_xor_b32_e32 v0, v7, v6
	v_and_b32_e32 v8, 0x3c0, v1
	v_lshlrev_b32_e32 v1, 7, v6
	s_bfe_u32 s94, s92, 0x20006
	s_and_b32 s86, s91, 63
	s_and_b32 s95, s92, 63
	s_and_b32 s21, s93, -4
	v_lshlrev_b32_e32 v0, 3, v0
	v_and_b32_e32 v1, 0xfffffc00, v1
	s_lshl_b32 s20, s86, 19
	s_or_b32 s58, s21, s94
	s_lshl_b32 s21, s95, 19
	v_and_or_b32 v0, v0, 56, v1
	s_waitcnt lgkmcnt(0)
	s_add_u32 s60, s3, s21
	v_ashrrev_i32_e32 v1, 31, v0
	v_lshl_add_u32 v129, v6, 4, 0
	s_addc_u32 s61, s90, 0
	v_lshlrev_b64 v[0:1], 1, v[0:1]
	v_readfirstlane_b32 s21, v129
	v_add_u32_e32 v9, 0x2000, v129
	v_lshl_add_u64 v[2:3], s[60:61], 0, v[0:1]
	s_mov_b32 m0, s21
	v_readfirstlane_b32 s21, v9
	v_add_u32_e32 v9, 0x4000, v129
	s_barrier
	global_load_lds_dwordx4 v[2:3], off
	v_lshl_add_u64 v[4:5], v[2:3], 0, s[10:11]
	s_mov_b32 m0, s21
	v_readfirstlane_b32 s21, v9
	global_load_lds_dwordx4 v[4:5], off
	v_lshl_add_u64 v[4:5], v[2:3], 0, s[12:13]
	s_mov_b32 m0, s21
	s_ashr_i32 s59, s58, 31
	global_load_lds_dwordx4 v[4:5], off
	v_add_u32_e32 v4, 0x6000, v129
	s_lshl_b64 s[88:89], s[58:59], 19
	v_readfirstlane_b32 s21, v4
	v_lshl_add_u64 v[2:3], v[2:3], 0, s[14:15]
	s_mov_b32 m0, s21
	s_add_u32 s88, s34, s88
	global_load_lds_dwordx4 v[2:3], off
	v_add_u32_e32 v2, 0x8000, v129
	s_addc_u32 s89, s35, s89
	v_readfirstlane_b32 s21, v2
	v_add_u32_e32 v4, 0xa000, v129
	v_lshl_add_u64 v[134:135], s[88:89], 0, v[0:1]
	s_mov_b32 m0, s21
	v_readfirstlane_b32 s21, v4
	v_add_u32_e32 v4, 0xc000, v129
	global_load_lds_dwordx4 v[134:135], off
	v_lshl_add_u64 v[2:3], v[134:135], 0, s[10:11]
	s_mov_b32 m0, s21
	v_readfirstlane_b32 s21, v4
	v_add_u32_e32 v4, 0xe000, v129
	global_load_lds_dwordx4 v[2:3], off
	v_lshl_add_u64 v[2:3], v[134:135], 0, s[12:13]
	s_mov_b32 m0, s21
	v_readfirstlane_b32 s21, v4
	global_load_lds_dwordx4 v[2:3], off
	v_lshl_add_u64 v[2:3], v[134:135], 0, s[14:15]
	s_mov_b32 m0, s21
	v_ashrrev_i32_e32 v4, 6, v6
	global_load_lds_dwordx4 v[2:3], off
	v_lshrrev_b32_e32 v5, 30, v4
	v_add_u32_e32 v5, v4, v5
	v_bfe_u32 v2, v6, 4, 2
	v_bfe_u32 v3, v6, 1, 3
	v_and_b32_e32 v6, 0x7fffc, v5
	v_sub_u32_e32 v4, v4, v6
	v_lshlrev_b32_e32 v139, 13, v4
	v_bitop3_b32 v4, v7, v3, 3 bitop3:0x6c
	v_bitop3_b32 v2, v2, v3, 4 bitop3:0x36
	s_add_u32 s60, s34, s20
	v_lshlrev_b32_e32 v5, 12, v5
	v_lshlrev_b32_e32 v4, 3, v4
	v_lshlrev_b32_e32 v2, 3, v2
	s_addc_u32 s61, s35, 0
	v_and_b32_e32 v138, 0xffffc000, v5
	v_lshl_add_u64 v[136:137], s[60:61], 0, v[0:1]
	s_mov_b64 s[60:61], 0
	v_lshlrev_b32_e32 v140, 1, v8
	v_lshlrev_b32_e32 v141, 1, v4
	v_lshlrev_b32_e32 v142, 1, v2
	s_mov_b32 s87, 0
	s_mov_b32 s59, 0
	v_mov_b32_e32 v8, v128
	v_mov_b32_e32 v9, v128
	v_mov_b32_e32 v10, v128
	v_mov_b32_e32 v11, v128
	v_mov_b32_e32 v20, v128
	v_mov_b32_e32 v21, v128
	v_mov_b32_e32 v22, v128
	v_mov_b32_e32 v23, v128
	v_mov_b32_e32 v0, v128
	v_mov_b32_e32 v1, v128
	v_mov_b32_e32 v2, v128
	v_mov_b32_e32 v3, v128
	v_mov_b32_e32 v4, v128
	v_mov_b32_e32 v5, v128
	v_mov_b32_e32 v6, v128
	v_mov_b32_e32 v7, v128
	v_mov_b32_e32 v12, v128
	v_mov_b32_e32 v13, v128
	v_mov_b32_e32 v14, v128
	v_mov_b32_e32 v15, v128
	v_mov_b32_e32 v24, v128
	v_mov_b32_e32 v25, v128
	v_mov_b32_e32 v26, v128
	v_mov_b32_e32 v27, v128
	v_mov_b32_e32 v16, v128
	v_mov_b32_e32 v17, v128
	v_mov_b32_e32 v18, v128
	v_mov_b32_e32 v19, v128
	v_mov_b32_e32 v28, v128
	v_mov_b32_e32 v29, v128
	v_mov_b32_e32 v30, v128
	v_mov_b32_e32 v31, v128
	v_mov_b32_e32 v32, v128
	v_mov_b32_e32 v33, v128
	v_mov_b32_e32 v34, v128
	v_mov_b32_e32 v35, v128
	v_mov_b32_e32 v40, v128
	v_mov_b32_e32 v41, v128
	v_mov_b32_e32 v42, v128
	v_mov_b32_e32 v43, v128
	v_mov_b32_e32 v36, v128
	v_mov_b32_e32 v37, v128
	v_mov_b32_e32 v38, v128
	v_mov_b32_e32 v39, v128
	v_mov_b32_e32 v44, v128
	v_mov_b32_e32 v45, v128
	v_mov_b32_e32 v46, v128
	v_mov_b32_e32 v47, v128
	v_mov_b32_e32 v48, v128
	v_mov_b32_e32 v49, v128
	v_mov_b32_e32 v50, v128
	v_mov_b32_e32 v51, v128
	v_mov_b32_e32 v56, v128
	v_mov_b32_e32 v57, v128
	v_mov_b32_e32 v58, v128
	v_mov_b32_e32 v59, v128
	v_mov_b32_e32 v52, v128
	v_mov_b32_e32 v53, v128
	v_mov_b32_e32 v54, v128
	v_mov_b32_e32 v55, v128
	v_mov_b32_e32 v60, v128
	v_mov_b32_e32 v61, v128
	v_mov_b32_e32 v62, v128
	v_mov_b32_e32 v63, v128
	v_mov_b32_e32 v64, v128
	v_mov_b32_e32 v65, v128
	v_mov_b32_e32 v66, v128
	v_mov_b32_e32 v67, v128
	v_mov_b32_e32 v72, v128
	v_mov_b32_e32 v73, v128
	v_mov_b32_e32 v74, v128
	v_mov_b32_e32 v75, v128
	v_mov_b32_e32 v68, v128
	v_mov_b32_e32 v69, v128
	v_mov_b32_e32 v70, v128
	v_mov_b32_e32 v71, v128
	v_mov_b32_e32 v76, v128
	v_mov_b32_e32 v77, v128
	v_mov_b32_e32 v78, v128
	v_mov_b32_e32 v79, v128
	v_mov_b32_e32 v80, v128
	v_mov_b32_e32 v81, v128
	v_mov_b32_e32 v82, v128
	v_mov_b32_e32 v83, v128
	v_mov_b32_e32 v88, v128
	v_mov_b32_e32 v89, v128
	v_mov_b32_e32 v90, v128
	v_mov_b32_e32 v91, v128
	v_mov_b32_e32 v84, v128
	v_mov_b32_e32 v85, v128
	v_mov_b32_e32 v86, v128
	v_mov_b32_e32 v87, v128
	v_mov_b32_e32 v92, v128
	v_mov_b32_e32 v93, v128
	v_mov_b32_e32 v94, v128
	v_mov_b32_e32 v95, v128
	v_mov_b32_e32 v96, v128
	v_mov_b32_e32 v97, v128
	v_mov_b32_e32 v98, v128
	v_mov_b32_e32 v99, v128
	v_mov_b32_e32 v104, v128
	v_mov_b32_e32 v105, v128
	v_mov_b32_e32 v106, v128
	v_mov_b32_e32 v107, v128
	v_mov_b32_e32 v100, v128
	v_mov_b32_e32 v101, v128
	v_mov_b32_e32 v102, v128
	v_mov_b32_e32 v103, v128
	v_mov_b32_e32 v108, v128
	v_mov_b32_e32 v109, v128
	v_mov_b32_e32 v110, v128
	v_mov_b32_e32 v111, v128
	v_mov_b32_e32 v112, v128
	v_mov_b32_e32 v113, v128
	v_mov_b32_e32 v114, v128
	v_mov_b32_e32 v115, v128
	v_mov_b32_e32 v120, v128
	v_mov_b32_e32 v121, v128
	v_mov_b32_e32 v122, v128
	v_mov_b32_e32 v123, v128
	v_mov_b32_e32 v116, v128
	v_mov_b32_e32 v117, v128
	v_mov_b32_e32 v118, v128
	v_mov_b32_e32 v119, v128
	v_mov_b32_e32 v124, v128
	v_mov_b32_e32 v125, v128
	v_mov_b32_e32 v126, v128
	v_mov_b32_e32 v127, v128
	s_waitcnt vmcnt(0) lgkmcnt(0)
	s_barrier
	v_add3_u32 v143, v138, v140, v141
	v_add3_u32 v180, v139, v140, v141
	v_add3_u32 v155, v138, v140, v142
	v_add3_u32 v222, v139, v140, v142
	v_readfirstlane_b32 s87, v129
	ds_read_b128 v[156:159], v143
	ds_read_b128 v[160:163], v143 offset:2048
	ds_read_b128 v[164:167], v143 offset:4096
	ds_read_b128 v[168:171], v143 offset:6144
	ds_read_b128 v[190:193], v180 offset:32768
	ds_read_b128 v[194:197], v180 offset:34816
	ds_read_b128 v[198:201], v180 offset:36864
	ds_read_b128 v[202:205], v180 offset:38912
	s_mov_b32 s59, 0
	s_mov_b64 s[60:61], s[34:35]
	v_subrev_u32_e32 v144, s34, v136
	v_subrev_u32_e32 v145, s34, v134
	s_add_u32 s87, s87, 0x10000
	s_mov_b32 m0, s87
	s_add_u32 s88, s60, s16
	s_addc_u32 s89, s61, s17
	global_load_lds_dwordx4 v144, s[88:89]
	s_add_u32 m0, s87, 0x2000
	s_add_u32 s88, s60, s18
	s_addc_u32 s89, s61, s19
	global_load_lds_dwordx4 v144, s[88:89]
	s_add_u32 m0, s87, 0x4000
	s_add_u32 s88, s60, s22
	s_addc_u32 s89, s61, s23
	global_load_lds_dwordx4 v144, s[88:89]
	s_add_u32 m0, s87, 0x6000
	s_add_u32 s88, s60, s40
	s_addc_u32 s89, s61, s41
	global_load_lds_dwordx4 v144, s[88:89]
	s_add_u32 m0, s87, 0x8000
	s_add_u32 s88, s60, s42
	s_addc_u32 s89, s61, s43
	global_load_lds_dwordx4 v145, s[88:89]
	s_add_u32 m0, s87, 0xa000
	s_add_u32 s88, s60, s52
	s_addc_u32 s89, s61, s53
	global_load_lds_dwordx4 v145, s[88:89]
	s_add_u32 m0, s87, 0xc000
	s_add_u32 s88, s60, s54
	s_addc_u32 s89, s61, s55
	global_load_lds_dwordx4 v145, s[88:89]
	s_add_u32 m0, s87, 0xe000
	s_add_u32 s88, s60, s56
	s_addc_u32 s89, s61, s57
	global_load_lds_dwordx4 v145, s[88:89]
	s_branch .Lg0_entry
.Lg0_top:
	s_waitcnt lgkmcnt(0)
	s_waitcnt vmcnt(0)
	s_barrier
	v_xor_b32_e32 v143, 0x10000, v143
	v_xor_b32_e32 v180, 0x10000, v180
	v_xor_b32_e32 v155, 0x10000, v155
	v_xor_b32_e32 v222, 0x10000, v222
	s_xor_b32 s87, s87, 0x10000
	ds_read_b128 v[156:159], v143
	ds_read_b128 v[160:163], v143 offset:2048
	ds_read_b128 v[164:167], v143 offset:4096
	ds_read_b128 v[168:171], v143 offset:6144
	ds_read_b128 v[190:193], v180 offset:32768
	ds_read_b128 v[194:197], v180 offset:34816
	ds_read_b128 v[198:201], v180 offset:36864
	ds_read_b128 v[202:205], v180 offset:38912
	v_mfma_f32_16x16x32_bf16 v[60:63], v[172:175], v[206:209], v[60:63]
	v_mfma_f32_16x16x32_bf16 v[52:55], v[172:175], v[210:213], v[52:55]
	s_mov_b32 m0, s87
	s_add_u32 s88, s60, s16
	s_addc_u32 s89, s61, s17
	global_load_lds_dwordx4 v144, s[88:89]
	v_mfma_f32_16x16x32_bf16 v[56:59], v[172:175], v[214:217], v[56:59]
	v_mfma_f32_16x16x32_bf16 v[48:51], v[172:175], v[218:221], v[48:51]
	s_add_u32 m0, s87, 0x2000
	s_add_u32 s88, s60, s18
	s_addc_u32 s89, s61, s19
	global_load_lds_dwordx4 v144, s[88:89]
	v_mfma_f32_16x16x32_bf16 v[44:47], v[176:179], v[206:209], v[44:47]
	v_mfma_f32_16x16x32_bf16 v[36:39], v[176:179], v[210:213], v[36:39]
	s_add_u32 m0, s87, 0x4000
	s_add_u32 s88, s60, s22
	s_addc_u32 s89, s61, s23
	global_load_lds_dwordx4 v144, s[88:89]
	v_mfma_f32_16x16x32_bf16 v[40:43], v[176:179], v[214:217], v[40:43]
	v_mfma_f32_16x16x32_bf16 v[32:35], v[176:179], v[218:221], v[32:35]
	s_add_u32 m0, s87, 0x6000
	s_add_u32 s88, s60, s40
	s_addc_u32 s89, s61, s41
	global_load_lds_dwordx4 v144, s[88:89]
	v_mfma_f32_16x16x32_bf16 v[28:31], v[182:185], v[206:209], v[28:31]
	v_mfma_f32_16x16x32_bf16 v[16:19], v[182:185], v[210:213], v[16:19]
	s_add_u32 m0, s87, 0x8000
	s_add_u32 s88, s60, s42
	s_addc_u32 s89, s61, s43
	global_load_lds_dwordx4 v145, s[88:89]
	v_mfma_f32_16x16x32_bf16 v[24:27], v[182:185], v[214:217], v[24:27]
	v_mfma_f32_16x16x32_bf16 v[12:15], v[182:185], v[218:221], v[12:15]
	s_add_u32 m0, s87, 0xa000
	s_add_u32 s88, s60, s52
	s_addc_u32 s89, s61, s53
	global_load_lds_dwordx4 v145, s[88:89]
	v_mfma_f32_16x16x32_bf16 v[4:7], v[186:189], v[206:209], v[4:7]
	v_mfma_f32_16x16x32_bf16 v[0:3], v[186:189], v[210:213], v[0:3]
	s_add_u32 m0, s87, 0xc000
	s_add_u32 s88, s60, s54
	s_addc_u32 s89, s61, s55
	global_load_lds_dwordx4 v145, s[88:89]
	v_mfma_f32_16x16x32_bf16 v[20:23], v[186:189], v[214:217], v[20:23]
	v_mfma_f32_16x16x32_bf16 v[8:11], v[186:189], v[218:221], v[8:11]
	s_add_u32 m0, s87, 0xe000
	s_add_u32 s88, s60, s56
	s_addc_u32 s89, s61, s57
	global_load_lds_dwordx4 v145, s[88:89]

.LBB0_120:
	v_lshl_add_u32 v136, s58, 2, v147
	s_lshl_b32 s88, s86, 8
	v_cmp_lt_i32_e32 vcc, 63, v136
	s_and_saveexec_b64 s[58:59], vcc
	s_xor_b64 s[58:59], exec, s[58:59]
	s_cbranch_execz .LBB0_128
	v_subrev_u32_e32 v136, 64, v136
	v_add_u32_e32 v129, s88, v151
	v_lshlrev_b32_e32 v129, 8, v129
	v_lshl_add_u32 v129, v136, 3, v129
	v_lshl_add_u32 v164, s95, 1, v146
	v_ashrrev_i32_e32 v165, 31, v164
	v_lshlrev_b64 v[164:165], 19, v[164:165]
	v_lshl_add_u64 v[164:165], v[130:131], 0, v[164:165]
	v_lshl_or_b32 v166, v136, 6, v148
	v_mov_b32_e32 v167, 0
	v_lshlrev_b64 v[166:167], 8, v[166:167]
	v_lshl_add_u64 v[156:157], v[164:165], 0, v[166:167]
	s_mov_b64 s[60:61], 0x1000
	v_lshl_add_u64 v[158:159], v[156:157], 0, s[60:61]
	v_lshl_add_u64 v[160:161], v[158:159], 0, s[60:61]
	v_lshl_add_u64 v[162:163], v[160:161], 0, s[60:61]
	v_mov_b32_e32 v168, 0xc0135761
	v_mov_b32_e32 v169, 0xc0135761
	v_mov_b32_e32 v170, 0xbdd2d3e7
	v_mov_b32_e32 v171, 0xbdd2d3e7
	v_mov_b32_e32 v172, 0x3f800000
	v_mov_b32_e32 v173, 0x3f800000
	v_pk_mul_f32 v[174:175], v[124:125], v[124:125]
	v_pk_mul_f32 v[176:177], v[126:127], v[126:127]
	v_pk_fma_f32 v[174:175], v[174:175], v[170:171], v[168:169]
	v_pk_fma_f32 v[176:177], v[176:177], v[170:171], v[168:169]
	v_pk_mul_f32 v[174:175], v[124:125], v[174:175]
	v_pk_mul_f32 v[176:177], v[126:127], v[176:177]
	v_exp_f32_e32 v174, v174
	v_exp_f32_e32 v175, v175
	v_exp_f32_e32 v176, v176
	v_exp_f32_e32 v177, v177
	v_pk_add_f32 v[174:175], v[174:175], v[172:173]
	v_pk_add_f32 v[176:177], v[176:177], v[172:173]
	v_rcp_f32_e32 v174, v174
	v_rcp_f32_e32 v175, v175
	v_rcp_f32_e32 v176, v176
	v_rcp_f32_e32 v177, v177
	v_pk_mul_f32 v[174:175], v[124:125], v[174:175]
	v_pk_mul_f32 v[176:177], v[126:127], v[176:177]
	v_cvt_pk_bf16_f32 v178, v174, v175
	v_cvt_pk_bf16_f32 v179, v176, v177
	global_store_dwordx2 v[156:157], v[178:179], off
	ds_write_b16 v150, v178
	ds_write_b16_d16_hi v150, v178 offset:144
	ds_write_b16 v150, v179 offset:288
	ds_write_b16_d16_hi v150, v179 offset:432
	v_pk_mul_f32 v[174:175], v[116:117], v[116:117]
	v_pk_mul_f32 v[176:177], v[118:119], v[118:119]
	v_pk_fma_f32 v[174:175], v[174:175], v[170:171], v[168:169]
	v_pk_fma_f32 v[176:177], v[176:177], v[170:171], v[168:169]
	v_pk_mul_f32 v[174:175], v[116:117], v[174:175]
	v_pk_mul_f32 v[176:177], v[118:119], v[176:177]
	v_exp_f32_e32 v174, v174
	v_exp_f32_e32 v175, v175
	v_exp_f32_e32 v176, v176
	v_exp_f32_e32 v177, v177
	v_pk_add_f32 v[174:175], v[174:175], v[172:173]
	v_pk_add_f32 v[176:177], v[176:177], v[172:173]
	v_rcp_f32_e32 v174, v174
	v_rcp_f32_e32 v175, v175
	v_rcp_f32_e32 v176, v176
	v_rcp_f32_e32 v177, v177
	v_pk_mul_f32 v[174:175], v[116:117], v[174:175]
	v_pk_mul_f32 v[176:177], v[118:119], v[176:177]
	v_cvt_pk_bf16_f32 v182, v174, v175
	v_cvt_pk_bf16_f32 v183, v176, v177
	global_store_dwordx2 v[158:159], v[182:183], off
	ds_write_b16 v150, v182 offset:32
	ds_write_b16_d16_hi v150, v182 offset:176
	ds_write_b16 v150, v183 offset:320
	ds_write_b16_d16_hi v150, v183 offset:464
	v_pk_mul_f32 v[174:175], v[120:121], v[120:121]
	v_pk_mul_f32 v[176:177], v[122:123], v[122:123]
	v_pk_fma_f32 v[174:175], v[174:175], v[170:171], v[168:169]
	v_pk_fma_f32 v[176:177], v[176:177], v[170:171], v[168:169]
	v_pk_mul_f32 v[174:175], v[120:121], v[174:175]
	v_pk_mul_f32 v[176:177], v[122:123], v[176:177]
	v_exp_f32_e32 v174, v174
	v_exp_f32_e32 v175, v175
	v_exp_f32_e32 v176, v176
	v_exp_f32_e32 v177, v177
	v_pk_add_f32 v[174:175], v[174:175], v[172:173]
	v_pk_add_f32 v[176:177], v[176:177], v[172:173]
	v_rcp_f32_e32 v174, v174
	v_rcp_f32_e32 v175, v175
	v_rcp_f32_e32 v176, v176
	v_rcp_f32_e32 v177, v177
	v_pk_mul_f32 v[174:175], v[120:121], v[174:175]
	v_pk_mul_f32 v[176:177], v[122:123], v[176:177]
	v_cvt_pk_bf16_f32 v178, v174, v175
	v_cvt_pk_bf16_f32 v179, v176, v177
	global_store_dwordx2 v[160:161], v[178:179], off
	ds_write_b16 v150, v178 offset:64
	ds_write_b16_d16_hi v150, v178 offset:208
	ds_write_b16 v150, v179 offset:352
	ds_write_b16_d16_hi v150, v179 offset:496
	v_pk_mul_f32 v[174:175], v[112:113], v[112:113]
	v_pk_mul_f32 v[176:177], v[114:115], v[114:115]
	v_pk_fma_f32 v[174:175], v[174:175], v[170:171], v[168:169]
	v_pk_fma_f32 v[176:177], v[176:177], v[170:171], v[168:169]
	v_pk_mul_f32 v[174:175], v[112:113], v[174:175]
	v_pk_mul_f32 v[176:177], v[114:115], v[176:177]
	v_exp_f32_e32 v174, v174
	v_exp_f32_e32 v175, v175
	v_exp_f32_e32 v176, v176
	v_exp_f32_e32 v177, v177
	v_pk_add_f32 v[174:175], v[174:175], v[172:173]
	v_pk_add_f32 v[176:177], v[176:177], v[172:173]
	v_rcp_f32_e32 v174, v174
	v_rcp_f32_e32 v175, v175
	v_rcp_f32_e32 v176, v176
	v_rcp_f32_e32 v177, v177
	v_pk_mul_f32 v[174:175], v[112:113], v[174:175]
	v_pk_mul_f32 v[176:177], v[114:115], v[176:177]
	v_cvt_pk_bf16_f32 v182, v174, v175
	v_cvt_pk_bf16_f32 v183, v176, v177
	global_store_dwordx2 v[162:163], v[182:183], off
	ds_write_b16 v150, v182 offset:96
	ds_write_b16_d16_hi v150, v182 offset:240
	ds_write_b16 v150, v183 offset:384
	ds_write_b16_d16_hi v150, v183 offset:528
	v_pk_mul_f32 v[174:175], v[108:109], v[108:109]
	v_pk_mul_f32 v[176:177], v[110:111], v[110:111]
	v_pk_fma_f32 v[174:175], v[174:175], v[170:171], v[168:169]
	v_pk_fma_f32 v[176:177], v[176:177], v[170:171], v[168:169]
	v_pk_mul_f32 v[174:175], v[108:109], v[174:175]
	v_pk_mul_f32 v[176:177], v[110:111], v[176:177]
	v_exp_f32_e32 v174, v174
	v_exp_f32_e32 v175, v175
	v_exp_f32_e32 v176, v176
	v_exp_f32_e32 v177, v177
	v_pk_add_f32 v[174:175], v[174:175], v[172:173]
	v_pk_add_f32 v[176:177], v[176:177], v[172:173]
	v_rcp_f32_e32 v174, v174
	v_rcp_f32_e32 v175, v175
	v_rcp_f32_e32 v176, v176
	v_rcp_f32_e32 v177, v177
	v_pk_mul_f32 v[174:175], v[108:109], v[174:175]
	v_pk_mul_f32 v[176:177], v[110:111], v[176:177]
	v_cvt_pk_bf16_f32 v178, v174, v175
	v_cvt_pk_bf16_f32 v179, v176, v177
	global_store_dwordx2 v[156:157], v[178:179], off offset:32
	ds_write_b16 v150, v178 offset:2304
	ds_write_b16_d16_hi v150, v178 offset:2448
	ds_write_b16 v150, v179 offset:2592
	ds_write_b16_d16_hi v150, v179 offset:2736
	v_pk_mul_f32 v[174:175], v[100:101], v[100:101]
	v_pk_mul_f32 v[176:177], v[102:103], v[102:103]
	v_pk_fma_f32 v[174:175], v[174:175], v[170:171], v[168:169]
	v_pk_fma_f32 v[176:177], v[176:177], v[170:171], v[168:169]
	v_pk_mul_f32 v[174:175], v[100:101], v[174:175]
	v_pk_mul_f32 v[176:177], v[102:103], v[176:177]
	v_exp_f32_e32 v174, v174
	v_exp_f32_e32 v175, v175
	v_exp_f32_e32 v176, v176
	v_exp_f32_e32 v177, v177
	v_pk_add_f32 v[174:175], v[174:175], v[172:173]
	v_pk_add_f32 v[176:177], v[176:177], v[172:173]
	v_rcp_f32_e32 v174, v174
	v_rcp_f32_e32 v175, v175
	v_rcp_f32_e32 v176, v176
	v_rcp_f32_e32 v177, v177
	v_pk_mul_f32 v[174:175], v[100:101], v[174:175]
	v_pk_mul_f32 v[176:177], v[102:103], v[176:177]
	v_cvt_pk_bf16_f32 v182, v174, v175
	v_cvt_pk_bf16_f32 v183, v176, v177
	global_store_dwordx2 v[158:159], v[182:183], off offset:32
	ds_write_b16 v150, v182 offset:2336
	ds_write_b16_d16_hi v150, v182 offset:2480
	ds_write_b16 v150, v183 offset:2624
	ds_write_b16_d16_hi v150, v183 offset:2768
	v_pk_mul_f32 v[174:175], v[104:105], v[104:105]
	v_pk_mul_f32 v[176:177], v[106:107], v[106:107]
	v_pk_fma_f32 v[174:175], v[174:175], v[170:171], v[168:169]
	v_pk_fma_f32 v[176:177], v[176:177], v[170:171], v[168:169]
	v_pk_mul_f32 v[174:175], v[104:105], v[174:175]
	v_pk_mul_f32 v[176:177], v[106:107], v[176:177]
	v_exp_f32_e32 v174, v174
	v_exp_f32_e32 v175, v175
	v_exp_f32_e32 v176, v176
	v_exp_f32_e32 v177, v177
	v_pk_add_f32 v[174:175], v[174:175], v[172:173]
	v_pk_add_f32 v[176:177], v[176:177], v[172:173]
	v_rcp_f32_e32 v174, v174
	v_rcp_f32_e32 v175, v175
	v_rcp_f32_e32 v176, v176
	v_rcp_f32_e32 v177, v177
	v_pk_mul_f32 v[174:175], v[104:105], v[174:175]
	v_pk_mul_f32 v[176:177], v[106:107], v[176:177]
	v_cvt_pk_bf16_f32 v178, v174, v175
	v_cvt_pk_bf16_f32 v179, v176, v177
	global_store_dwordx2 v[160:161], v[178:179], off offset:32
	ds_write_b16 v150, v178 offset:2368
	ds_write_b16_d16_hi v150, v178 offset:2512
	ds_write_b16 v150, v179 offset:2656
	ds_write_b16_d16_hi v150, v179 offset:2800
	v_pk_mul_f32 v[174:175], v[96:97], v[96:97]
	v_pk_mul_f32 v[176:177], v[98:99], v[98:99]
	v_pk_fma_f32 v[174:175], v[174:175], v[170:171], v[168:169]
	v_pk_fma_f32 v[176:177], v[176:177], v[170:171], v[168:169]
	v_pk_mul_f32 v[174:175], v[96:97], v[174:175]
	v_pk_mul_f32 v[176:177], v[98:99], v[176:177]
	v_exp_f32_e32 v174, v174
	v_exp_f32_e32 v175, v175
	v_exp_f32_e32 v176, v176
	v_exp_f32_e32 v177, v177
	v_pk_add_f32 v[174:175], v[174:175], v[172:173]
	v_pk_add_f32 v[176:177], v[176:177], v[172:173]
	v_rcp_f32_e32 v174, v174
	v_rcp_f32_e32 v175, v175
	v_rcp_f32_e32 v176, v176
	v_rcp_f32_e32 v177, v177
	v_pk_mul_f32 v[174:175], v[96:97], v[174:175]
	v_pk_mul_f32 v[176:177], v[98:99], v[176:177]
	v_cvt_pk_bf16_f32 v182, v174, v175
	v_cvt_pk_bf16_f32 v183, v176, v177
	global_store_dwordx2 v[162:163], v[182:183], off offset:32
	ds_write_b16 v150, v182 offset:2400
	ds_write_b16_d16_hi v150, v182 offset:2544
	ds_write_b16 v150, v183 offset:2688
	ds_write_b16_d16_hi v150, v183 offset:2832
	v_pk_mul_f32 v[174:175], v[92:93], v[92:93]
	v_pk_mul_f32 v[176:177], v[94:95], v[94:95]
	v_pk_fma_f32 v[174:175], v[174:175], v[170:171], v[168:169]
	v_pk_fma_f32 v[176:177], v[176:177], v[170:171], v[168:169]
	v_pk_mul_f32 v[174:175], v[92:93], v[174:175]
	v_pk_mul_f32 v[176:177], v[94:95], v[176:177]
	v_exp_f32_e32 v174, v174
	v_exp_f32_e32 v175, v175
	v_exp_f32_e32 v176, v176
	v_exp_f32_e32 v177, v177
	v_pk_add_f32 v[174:175], v[174:175], v[172:173]
	v_pk_add_f32 v[176:177], v[176:177], v[172:173]
	v_rcp_f32_e32 v174, v174
	v_rcp_f32_e32 v175, v175
	v_rcp_f32_e32 v176, v176
	v_rcp_f32_e32 v177, v177
	v_pk_mul_f32 v[174:175], v[92:93], v[174:175]
	v_pk_mul_f32 v[176:177], v[94:95], v[176:177]
	v_cvt_pk_bf16_f32 v178, v174, v175
	v_cvt_pk_bf16_f32 v179, v176, v177
	global_store_dwordx2 v[156:157], v[178:179], off offset:64
	ds_write_b16 v150, v178 offset:4608
	ds_write_b16_d16_hi v150, v178 offset:4752
	ds_write_b16 v150, v179 offset:4896
	ds_write_b16_d16_hi v150, v179 offset:5040
	v_pk_mul_f32 v[174:175], v[84:85], v[84:85]
	v_pk_mul_f32 v[176:177], v[86:87], v[86:87]
	v_pk_fma_f32 v[174:175], v[174:175], v[170:171], v[168:169]
	v_pk_fma_f32 v[176:177], v[176:177], v[170:171], v[168:169]
	v_pk_mul_f32 v[174:175], v[84:85], v[174:175]
	v_pk_mul_f32 v[176:177], v[86:87], v[176:177]
	v_exp_f32_e32 v174, v174
	v_exp_f32_e32 v175, v175
	v_exp_f32_e32 v176, v176
	v_exp_f32_e32 v177, v177
	v_pk_add_f32 v[174:175], v[174:175], v[172:173]
	v_pk_add_f32 v[176:177], v[176:177], v[172:173]
	v_rcp_f32_e32 v174, v174
	v_rcp_f32_e32 v175, v175
	v_rcp_f32_e32 v176, v176
	v_rcp_f32_e32 v177, v177
	v_pk_mul_f32 v[174:175], v[84:85], v[174:175]
	v_pk_mul_f32 v[176:177], v[86:87], v[176:177]
	v_cvt_pk_bf16_f32 v182, v174, v175
	v_cvt_pk_bf16_f32 v183, v176, v177
	global_store_dwordx2 v[158:159], v[182:183], off offset:64
	ds_write_b16 v150, v182 offset:4640
	ds_write_b16_d16_hi v150, v182 offset:4784
	ds_write_b16 v150, v183 offset:4928
	ds_write_b16_d16_hi v150, v183 offset:5072
	v_pk_mul_f32 v[174:175], v[88:89], v[88:89]
	v_pk_mul_f32 v[176:177], v[90:91], v[90:91]
	v_pk_fma_f32 v[174:175], v[174:175], v[170:171], v[168:169]
	v_pk_fma_f32 v[176:177], v[176:177], v[170:171], v[168:169]
	v_pk_mul_f32 v[174:175], v[88:89], v[174:175]
	v_pk_mul_f32 v[176:177], v[90:91], v[176:177]
	v_exp_f32_e32 v174, v174
	v_exp_f32_e32 v175, v175
	v_exp_f32_e32 v176, v176
	v_exp_f32_e32 v177, v177
	v_pk_add_f32 v[174:175], v[174:175], v[172:173]
	v_pk_add_f32 v[176:177], v[176:177], v[172:173]
	v_rcp_f32_e32 v174, v174
	v_rcp_f32_e32 v175, v175
	v_rcp_f32_e32 v176, v176
	v_rcp_f32_e32 v177, v177
	v_pk_mul_f32 v[174:175], v[88:89], v[174:175]
	v_pk_mul_f32 v[176:177], v[90:91], v[176:177]
	v_cvt_pk_bf16_f32 v178, v174, v175
	v_cvt_pk_bf16_f32 v179, v176, v177
	global_store_dwordx2 v[160:161], v[178:179], off offset:64
	ds_write_b16 v150, v178 offset:4672
	ds_write_b16_d16_hi v150, v178 offset:4816
	ds_write_b16 v150, v179 offset:4960
	ds_write_b16_d16_hi v150, v179 offset:5104
	v_pk_mul_f32 v[174:175], v[80:81], v[80:81]
	v_pk_mul_f32 v[176:177], v[82:83], v[82:83]
	v_pk_fma_f32 v[174:175], v[174:175], v[170:171], v[168:169]
	v_pk_fma_f32 v[176:177], v[176:177], v[170:171], v[168:169]
	v_pk_mul_f32 v[174:175], v[80:81], v[174:175]
	v_pk_mul_f32 v[176:177], v[82:83], v[176:177]
	v_exp_f32_e32 v174, v174
	v_exp_f32_e32 v175, v175
	v_exp_f32_e32 v176, v176
	v_exp_f32_e32 v177, v177
	v_pk_add_f32 v[174:175], v[174:175], v[172:173]
	v_pk_add_f32 v[176:177], v[176:177], v[172:173]
	v_rcp_f32_e32 v174, v174
	v_rcp_f32_e32 v175, v175
	v_rcp_f32_e32 v176, v176
	v_rcp_f32_e32 v177, v177
	v_pk_mul_f32 v[174:175], v[80:81], v[174:175]
	v_pk_mul_f32 v[176:177], v[82:83], v[176:177]
	v_cvt_pk_bf16_f32 v182, v174, v175
	v_cvt_pk_bf16_f32 v183, v176, v177
	global_store_dwordx2 v[162:163], v[182:183], off offset:64
	ds_write_b16 v150, v182 offset:4704
	ds_write_b16_d16_hi v150, v182 offset:4848
	ds_write_b16 v150, v183 offset:4992
	ds_write_b16_d16_hi v150, v183 offset:5136
	v_pk_mul_f32 v[174:175], v[76:77], v[76:77]
	v_pk_mul_f32 v[176:177], v[78:79], v[78:79]
	v_pk_fma_f32 v[174:175], v[174:175], v[170:171], v[168:169]
	v_pk_fma_f32 v[176:177], v[176:177], v[170:171], v[168:169]
	v_pk_mul_f32 v[174:175], v[76:77], v[174:175]
	v_pk_mul_f32 v[176:177], v[78:79], v[176:177]
	v_exp_f32_e32 v174, v174
	v_exp_f32_e32 v175, v175
	v_exp_f32_e32 v176, v176
	v_exp_f32_e32 v177, v177
	v_pk_add_f32 v[174:175], v[174:175], v[172:173]
	v_pk_add_f32 v[176:177], v[176:177], v[172:173]
	v_rcp_f32_e32 v174, v174
	v_rcp_f32_e32 v175, v175
	v_rcp_f32_e32 v176, v176
	v_rcp_f32_e32 v177, v177
	v_pk_mul_f32 v[174:175], v[76:77], v[174:175]
	v_pk_mul_f32 v[176:177], v[78:79], v[176:177]
	v_cvt_pk_bf16_f32 v178, v174, v175
	v_cvt_pk_bf16_f32 v179, v176, v177
	global_store_dwordx2 v[156:157], v[178:179], off offset:96
	ds_write_b16 v150, v178 offset:6912
	ds_write_b16_d16_hi v150, v178 offset:7056
	ds_write_b16 v150, v179 offset:7200
	ds_write_b16_d16_hi v150, v179 offset:7344
	v_pk_mul_f32 v[174:175], v[68:69], v[68:69]
	v_pk_mul_f32 v[176:177], v[70:71], v[70:71]
	v_pk_fma_f32 v[174:175], v[174:175], v[170:171], v[168:169]
	v_pk_fma_f32 v[176:177], v[176:177], v[170:171], v[168:169]
	v_pk_mul_f32 v[174:175], v[68:69], v[174:175]
	v_pk_mul_f32 v[176:177], v[70:71], v[176:177]
	v_exp_f32_e32 v174, v174
	v_exp_f32_e32 v175, v175
	v_exp_f32_e32 v176, v176
	v_exp_f32_e32 v177, v177
	v_pk_add_f32 v[174:175], v[174:175], v[172:173]
	v_pk_add_f32 v[176:177], v[176:177], v[172:173]
	v_rcp_f32_e32 v174, v174
	v_rcp_f32_e32 v175, v175
	v_rcp_f32_e32 v176, v176
	v_rcp_f32_e32 v177, v177
	v_pk_mul_f32 v[174:175], v[68:69], v[174:175]
	v_pk_mul_f32 v[176:177], v[70:71], v[176:177]
	v_cvt_pk_bf16_f32 v182, v174, v175
	v_cvt_pk_bf16_f32 v183, v176, v177
	global_store_dwordx2 v[158:159], v[182:183], off offset:96
	ds_write_b16 v150, v182 offset:6944
	ds_write_b16_d16_hi v150, v182 offset:7088
	ds_write_b16 v150, v183 offset:7232
	ds_write_b16_d16_hi v150, v183 offset:7376
	v_pk_mul_f32 v[174:175], v[72:73], v[72:73]
	v_pk_mul_f32 v[176:177], v[74:75], v[74:75]
	v_pk_fma_f32 v[174:175], v[174:175], v[170:171], v[168:169]
	v_pk_fma_f32 v[176:177], v[176:177], v[170:171], v[168:169]
	v_pk_mul_f32 v[174:175], v[72:73], v[174:175]
	v_pk_mul_f32 v[176:177], v[74:75], v[176:177]
	v_exp_f32_e32 v174, v174
	v_exp_f32_e32 v175, v175
	v_exp_f32_e32 v176, v176
	v_exp_f32_e32 v177, v177
	v_pk_add_f32 v[174:175], v[174:175], v[172:173]
	v_pk_add_f32 v[176:177], v[176:177], v[172:173]
	v_rcp_f32_e32 v174, v174
	v_rcp_f32_e32 v175, v175
	v_rcp_f32_e32 v176, v176
	v_rcp_f32_e32 v177, v177
	v_pk_mul_f32 v[174:175], v[72:73], v[174:175]
	v_pk_mul_f32 v[176:177], v[74:75], v[176:177]
	v_cvt_pk_bf16_f32 v178, v174, v175
	v_cvt_pk_bf16_f32 v179, v176, v177
	global_store_dwordx2 v[160:161], v[178:179], off offset:96
	ds_write_b16 v150, v178 offset:6976
	ds_write_b16_d16_hi v150, v178 offset:7120
	ds_write_b16 v150, v179 offset:7264
	ds_write_b16_d16_hi v150, v179 offset:7408
	v_pk_mul_f32 v[174:175], v[64:65], v[64:65]
	v_pk_mul_f32 v[176:177], v[66:67], v[66:67]
	v_pk_fma_f32 v[174:175], v[174:175], v[170:171], v[168:169]
	v_pk_fma_f32 v[176:177], v[176:177], v[170:171], v[168:169]
	v_pk_mul_f32 v[174:175], v[64:65], v[174:175]
	v_pk_mul_f32 v[176:177], v[66:67], v[176:177]
	v_exp_f32_e32 v174, v174
	v_exp_f32_e32 v175, v175
	v_exp_f32_e32 v176, v176
	v_exp_f32_e32 v177, v177
	v_pk_add_f32 v[174:175], v[174:175], v[172:173]
	v_pk_add_f32 v[176:177], v[176:177], v[172:173]
	v_rcp_f32_e32 v174, v174
	v_rcp_f32_e32 v175, v175
	v_rcp_f32_e32 v176, v176
	v_rcp_f32_e32 v177, v177
	v_pk_mul_f32 v[174:175], v[64:65], v[174:175]
	v_pk_mul_f32 v[176:177], v[66:67], v[176:177]
	v_cvt_pk_bf16_f32 v182, v174, v175
	v_cvt_pk_bf16_f32 v183, v176, v177
	global_store_dwordx2 v[162:163], v[182:183], off offset:96
	ds_write_b16 v150, v182 offset:7008
	ds_write_b16_d16_hi v150, v182 offset:7152
	ds_write_b16 v150, v183 offset:7296
	ds_write_b16_d16_hi v150, v183 offset:7440
	v_pk_mul_f32 v[174:175], v[60:61], v[60:61]
	v_pk_mul_f32 v[176:177], v[62:63], v[62:63]
	v_pk_fma_f32 v[174:175], v[174:175], v[170:171], v[168:169]
	v_pk_fma_f32 v[176:177], v[176:177], v[170:171], v[168:169]
	v_pk_mul_f32 v[174:175], v[60:61], v[174:175]
	v_pk_mul_f32 v[176:177], v[62:63], v[176:177]
	v_exp_f32_e32 v174, v174
	v_exp_f32_e32 v175, v175
	v_exp_f32_e32 v176, v176
	v_exp_f32_e32 v177, v177
	v_pk_add_f32 v[174:175], v[174:175], v[172:173]
	v_pk_add_f32 v[176:177], v[176:177], v[172:173]
	v_rcp_f32_e32 v174, v174
	v_rcp_f32_e32 v175, v175
	v_rcp_f32_e32 v176, v176
	v_rcp_f32_e32 v177, v177
	v_pk_mul_f32 v[174:175], v[60:61], v[174:175]
	v_pk_mul_f32 v[176:177], v[62:63], v[176:177]
	v_cvt_pk_bf16_f32 v178, v174, v175
	v_cvt_pk_bf16_f32 v179, v176, v177
	global_store_dwordx2 v[156:157], v[178:179], off offset:128
	ds_write_b16 v150, v178 offset:9216
	ds_write_b16_d16_hi v150, v178 offset:9360
	ds_write_b16 v150, v179 offset:9504
	ds_write_b16_d16_hi v150, v179 offset:9648
	v_pk_mul_f32 v[174:175], v[52:53], v[52:53]
	v_pk_mul_f32 v[176:177], v[54:55], v[54:55]
	v_pk_fma_f32 v[174:175], v[174:175], v[170:171], v[168:169]
	v_pk_fma_f32 v[176:177], v[176:177], v[170:171], v[168:169]
	v_pk_mul_f32 v[174:175], v[52:53], v[174:175]
	v_pk_mul_f32 v[176:177], v[54:55], v[176:177]
	v_exp_f32_e32 v174, v174
	v_exp_f32_e32 v175, v175
	v_exp_f32_e32 v176, v176
	v_exp_f32_e32 v177, v177
	v_pk_add_f32 v[174:175], v[174:175], v[172:173]
	v_pk_add_f32 v[176:177], v[176:177], v[172:173]
	v_rcp_f32_e32 v174, v174
	v_rcp_f32_e32 v175, v175
	v_rcp_f32_e32 v176, v176
	v_rcp_f32_e32 v177, v177
	v_pk_mul_f32 v[174:175], v[52:53], v[174:175]
	v_pk_mul_f32 v[176:177], v[54:55], v[176:177]
	v_cvt_pk_bf16_f32 v182, v174, v175
	v_cvt_pk_bf16_f32 v183, v176, v177
	global_store_dwordx2 v[158:159], v[182:183], off offset:128
	ds_write_b16 v150, v182 offset:9248
	ds_write_b16_d16_hi v150, v182 offset:9392
	ds_write_b16 v150, v183 offset:9536
	ds_write_b16_d16_hi v150, v183 offset:9680
	v_pk_mul_f32 v[174:175], v[56:57], v[56:57]
	v_pk_mul_f32 v[176:177], v[58:59], v[58:59]
	v_pk_fma_f32 v[174:175], v[174:175], v[170:171], v[168:169]
	v_pk_fma_f32 v[176:177], v[176:177], v[170:171], v[168:169]
	v_pk_mul_f32 v[174:175], v[56:57], v[174:175]
	v_pk_mul_f32 v[176:177], v[58:59], v[176:177]
	v_exp_f32_e32 v174, v174
	v_exp_f32_e32 v175, v175
	v_exp_f32_e32 v176, v176
	v_exp_f32_e32 v177, v177
	v_pk_add_f32 v[174:175], v[174:175], v[172:173]
	v_pk_add_f32 v[176:177], v[176:177], v[172:173]
	v_rcp_f32_e32 v174, v174
	v_rcp_f32_e32 v175, v175
	v_rcp_f32_e32 v176, v176
	v_rcp_f32_e32 v177, v177
	v_pk_mul_f32 v[174:175], v[56:57], v[174:175]
	v_pk_mul_f32 v[176:177], v[58:59], v[176:177]
	v_cvt_pk_bf16_f32 v178, v174, v175
	v_cvt_pk_bf16_f32 v179, v176, v177
	global_store_dwordx2 v[160:161], v[178:179], off offset:128
	ds_write_b16 v150, v178 offset:9280
	ds_write_b16_d16_hi v150, v178 offset:9424
	ds_write_b16 v150, v179 offset:9568
	ds_write_b16_d16_hi v150, v179 offset:9712
	v_pk_mul_f32 v[174:175], v[48:49], v[48:49]
	v_pk_mul_f32 v[176:177], v[50:51], v[50:51]
	v_pk_fma_f32 v[174:175], v[174:175], v[170:171], v[168:169]
	v_pk_fma_f32 v[176:177], v[176:177], v[170:171], v[168:169]
	v_pk_mul_f32 v[174:175], v[48:49], v[174:175]
	v_pk_mul_f32 v[176:177], v[50:51], v[176:177]
	v_exp_f32_e32 v174, v174
	v_exp_f32_e32 v175, v175
	v_exp_f32_e32 v176, v176
	v_exp_f32_e32 v177, v177
	v_pk_add_f32 v[174:175], v[174:175], v[172:173]
	v_pk_add_f32 v[176:177], v[176:177], v[172:173]
	v_rcp_f32_e32 v174, v174
	v_rcp_f32_e32 v175, v175
	v_rcp_f32_e32 v176, v176
	v_rcp_f32_e32 v177, v177
	v_pk_mul_f32 v[174:175], v[48:49], v[174:175]
	v_pk_mul_f32 v[176:177], v[50:51], v[176:177]
	v_cvt_pk_bf16_f32 v182, v174, v175
	v_cvt_pk_bf16_f32 v183, v176, v177
	global_store_dwordx2 v[162:163], v[182:183], off offset:128
	ds_write_b16 v150, v182 offset:9312
	ds_write_b16_d16_hi v150, v182 offset:9456
	ds_write_b16 v150, v183 offset:9600
	ds_write_b16_d16_hi v150, v183 offset:9744
	v_pk_mul_f32 v[174:175], v[44:45], v[44:45]
	v_pk_mul_f32 v[176:177], v[46:47], v[46:47]
	v_pk_fma_f32 v[174:175], v[174:175], v[170:171], v[168:169]
	v_pk_fma_f32 v[176:177], v[176:177], v[170:171], v[168:169]
	v_pk_mul_f32 v[174:175], v[44:45], v[174:175]
	v_pk_mul_f32 v[176:177], v[46:47], v[176:177]
	v_exp_f32_e32 v174, v174
	v_exp_f32_e32 v175, v175
	v_exp_f32_e32 v176, v176
	v_exp_f32_e32 v177, v177
	v_pk_add_f32 v[174:175], v[174:175], v[172:173]
	v_pk_add_f32 v[176:177], v[176:177], v[172:173]
	v_rcp_f32_e32 v174, v174
	v_rcp_f32_e32 v175, v175
	v_rcp_f32_e32 v176, v176
	v_rcp_f32_e32 v177, v177
	v_pk_mul_f32 v[174:175], v[44:45], v[174:175]
	v_pk_mul_f32 v[176:177], v[46:47], v[176:177]
	v_cvt_pk_bf16_f32 v178, v174, v175
	v_cvt_pk_bf16_f32 v179, v176, v177
	global_store_dwordx2 v[156:157], v[178:179], off offset:160
	ds_write_b16 v150, v178 offset:11520
	ds_write_b16_d16_hi v150, v178 offset:11664
	ds_write_b16 v150, v179 offset:11808
	ds_write_b16_d16_hi v150, v179 offset:11952
	v_pk_mul_f32 v[174:175], v[36:37], v[36:37]
	v_pk_mul_f32 v[176:177], v[38:39], v[38:39]
	v_pk_fma_f32 v[174:175], v[174:175], v[170:171], v[168:169]
	v_pk_fma_f32 v[176:177], v[176:177], v[170:171], v[168:169]
	v_pk_mul_f32 v[174:175], v[36:37], v[174:175]
	v_pk_mul_f32 v[176:177], v[38:39], v[176:177]
	v_exp_f32_e32 v174, v174
	v_exp_f32_e32 v175, v175
	v_exp_f32_e32 v176, v176
	v_exp_f32_e32 v177, v177
	v_pk_add_f32 v[174:175], v[174:175], v[172:173]
	v_pk_add_f32 v[176:177], v[176:177], v[172:173]
	v_rcp_f32_e32 v174, v174
	v_rcp_f32_e32 v175, v175
	v_rcp_f32_e32 v176, v176
	v_rcp_f32_e32 v177, v177
	v_pk_mul_f32 v[174:175], v[36:37], v[174:175]
	v_pk_mul_f32 v[176:177], v[38:39], v[176:177]
	v_cvt_pk_bf16_f32 v182, v174, v175
	v_cvt_pk_bf16_f32 v183, v176, v177
	global_store_dwordx2 v[158:159], v[182:183], off offset:160
	ds_write_b16 v150, v182 offset:11552
	ds_write_b16_d16_hi v150, v182 offset:11696
	ds_write_b16 v150, v183 offset:11840
	ds_write_b16_d16_hi v150, v183 offset:11984
	v_pk_mul_f32 v[174:175], v[40:41], v[40:41]
	v_pk_mul_f32 v[176:177], v[42:43], v[42:43]
	v_pk_fma_f32 v[174:175], v[174:175], v[170:171], v[168:169]
	v_pk_fma_f32 v[176:177], v[176:177], v[170:171], v[168:169]
	v_pk_mul_f32 v[174:175], v[40:41], v[174:175]
	v_pk_mul_f32 v[176:177], v[42:43], v[176:177]
	v_exp_f32_e32 v174, v174
	v_exp_f32_e32 v175, v175
	v_exp_f32_e32 v176, v176
	v_exp_f32_e32 v177, v177
	v_pk_add_f32 v[174:175], v[174:175], v[172:173]
	v_pk_add_f32 v[176:177], v[176:177], v[172:173]
	v_rcp_f32_e32 v174, v174
	v_rcp_f32_e32 v175, v175
	v_rcp_f32_e32 v176, v176
	v_rcp_f32_e32 v177, v177
	v_pk_mul_f32 v[174:175], v[40:41], v[174:175]
	v_pk_mul_f32 v[176:177], v[42:43], v[176:177]
	v_cvt_pk_bf16_f32 v178, v174, v175
	v_cvt_pk_bf16_f32 v179, v176, v177
	global_store_dwordx2 v[160:161], v[178:179], off offset:160
	ds_write_b16 v150, v178 offset:11584
	ds_write_b16_d16_hi v150, v178 offset:11728
	ds_write_b16 v150, v179 offset:11872
	ds_write_b16_d16_hi v150, v179 offset:12016
	v_pk_mul_f32 v[174:175], v[32:33], v[32:33]
	v_pk_mul_f32 v[176:177], v[34:35], v[34:35]
	v_pk_fma_f32 v[174:175], v[174:175], v[170:171], v[168:169]
	v_pk_fma_f32 v[176:177], v[176:177], v[170:171], v[168:169]
	v_pk_mul_f32 v[174:175], v[32:33], v[174:175]
	v_pk_mul_f32 v[176:177], v[34:35], v[176:177]
	v_exp_f32_e32 v174, v174
	v_exp_f32_e32 v175, v175
	v_exp_f32_e32 v176, v176
	v_exp_f32_e32 v177, v177
	v_pk_add_f32 v[174:175], v[174:175], v[172:173]
	v_pk_add_f32 v[176:177], v[176:177], v[172:173]
	v_rcp_f32_e32 v174, v174
	v_rcp_f32_e32 v175, v175
	v_rcp_f32_e32 v176, v176
	v_rcp_f32_e32 v177, v177
	v_pk_mul_f32 v[174:175], v[32:33], v[174:175]
	v_pk_mul_f32 v[176:177], v[34:35], v[176:177]
	v_cvt_pk_bf16_f32 v182, v174, v175
	v_cvt_pk_bf16_f32 v183, v176, v177
	global_store_dwordx2 v[162:163], v[182:183], off offset:160
	ds_write_b16 v150, v182 offset:11616
	ds_write_b16_d16_hi v150, v182 offset:11760
	ds_write_b16 v150, v183 offset:11904
	ds_write_b16_d16_hi v150, v183 offset:12048
	v_pk_mul_f32 v[174:175], v[28:29], v[28:29]
	v_pk_mul_f32 v[176:177], v[30:31], v[30:31]
	v_pk_fma_f32 v[174:175], v[174:175], v[170:171], v[168:169]
	v_pk_fma_f32 v[176:177], v[176:177], v[170:171], v[168:169]
	v_pk_mul_f32 v[174:175], v[28:29], v[174:175]
	v_pk_mul_f32 v[176:177], v[30:31], v[176:177]
	v_exp_f32_e32 v174, v174
	v_exp_f32_e32 v175, v175
	v_exp_f32_e32 v176, v176
	v_exp_f32_e32 v177, v177
	v_pk_add_f32 v[174:175], v[174:175], v[172:173]
	v_pk_add_f32 v[176:177], v[176:177], v[172:173]
	v_rcp_f32_e32 v174, v174
	v_rcp_f32_e32 v175, v175
	v_rcp_f32_e32 v176, v176
	v_rcp_f32_e32 v177, v177
	v_pk_mul_f32 v[174:175], v[28:29], v[174:175]
	v_pk_mul_f32 v[176:177], v[30:31], v[176:177]
	v_cvt_pk_bf16_f32 v178, v174, v175
	v_cvt_pk_bf16_f32 v179, v176, v177
	global_store_dwordx2 v[156:157], v[178:179], off offset:192
	ds_write_b16 v150, v178 offset:13824
	ds_write_b16_d16_hi v150, v178 offset:13968
	ds_write_b16 v150, v179 offset:14112
	ds_write_b16_d16_hi v150, v179 offset:14256
	v_pk_mul_f32 v[174:175], v[16:17], v[16:17]
	v_pk_mul_f32 v[176:177], v[18:19], v[18:19]
	v_pk_fma_f32 v[174:175], v[174:175], v[170:171], v[168:169]
	v_pk_fma_f32 v[176:177], v[176:177], v[170:171], v[168:169]
	v_pk_mul_f32 v[174:175], v[16:17], v[174:175]
	v_pk_mul_f32 v[176:177], v[18:19], v[176:177]
	v_exp_f32_e32 v174, v174
	v_exp_f32_e32 v175, v175
	v_exp_f32_e32 v176, v176
	v_exp_f32_e32 v177, v177
	v_pk_add_f32 v[174:175], v[174:175], v[172:173]
	v_pk_add_f32 v[176:177], v[176:177], v[172:173]
	v_rcp_f32_e32 v174, v174
	v_rcp_f32_e32 v175, v175
	v_rcp_f32_e32 v176, v176
	v_rcp_f32_e32 v177, v177
	v_pk_mul_f32 v[174:175], v[16:17], v[174:175]
	v_pk_mul_f32 v[176:177], v[18:19], v[176:177]
	v_cvt_pk_bf16_f32 v182, v174, v175
	v_cvt_pk_bf16_f32 v183, v176, v177
	global_store_dwordx2 v[158:159], v[182:183], off offset:192
	ds_write_b16 v150, v182 offset:13856
	ds_write_b16_d16_hi v150, v182 offset:14000
	ds_write_b16 v150, v183 offset:14144
	ds_write_b16_d16_hi v150, v183 offset:14288
	v_pk_mul_f32 v[174:175], v[24:25], v[24:25]
	v_pk_mul_f32 v[176:177], v[26:27], v[26:27]
	v_pk_fma_f32 v[174:175], v[174:175], v[170:171], v[168:169]
	v_pk_fma_f32 v[176:177], v[176:177], v[170:171], v[168:169]
	v_pk_mul_f32 v[174:175], v[24:25], v[174:175]
	v_pk_mul_f32 v[176:177], v[26:27], v[176:177]
	v_exp_f32_e32 v174, v174
	v_exp_f32_e32 v175, v175
	v_exp_f32_e32 v176, v176
	v_exp_f32_e32 v177, v177
	v_pk_add_f32 v[174:175], v[174:175], v[172:173]
	v_pk_add_f32 v[176:177], v[176:177], v[172:173]
	v_rcp_f32_e32 v174, v174
	v_rcp_f32_e32 v175, v175
	v_rcp_f32_e32 v176, v176
	v_rcp_f32_e32 v177, v177
	v_pk_mul_f32 v[174:175], v[24:25], v[174:175]
	v_pk_mul_f32 v[176:177], v[26:27], v[176:177]
	v_cvt_pk_bf16_f32 v178, v174, v175
	v_cvt_pk_bf16_f32 v179, v176, v177
	global_store_dwordx2 v[160:161], v[178:179], off offset:192
	ds_write_b16 v150, v178 offset:13888
	ds_write_b16_d16_hi v150, v178 offset:14032
	ds_write_b16 v150, v179 offset:14176
	ds_write_b16_d16_hi v150, v179 offset:14320
	v_pk_mul_f32 v[174:175], v[12:13], v[12:13]
	v_pk_mul_f32 v[176:177], v[14:15], v[14:15]
	v_pk_fma_f32 v[174:175], v[174:175], v[170:171], v[168:169]
	v_pk_fma_f32 v[176:177], v[176:177], v[170:171], v[168:169]
	v_pk_mul_f32 v[174:175], v[12:13], v[174:175]
	v_pk_mul_f32 v[176:177], v[14:15], v[176:177]
	v_exp_f32_e32 v174, v174
	v_exp_f32_e32 v175, v175
	v_exp_f32_e32 v176, v176
	v_exp_f32_e32 v177, v177
	v_pk_add_f32 v[174:175], v[174:175], v[172:173]
	v_pk_add_f32 v[176:177], v[176:177], v[172:173]
	v_rcp_f32_e32 v174, v174
	v_rcp_f32_e32 v175, v175
	v_rcp_f32_e32 v176, v176
	v_rcp_f32_e32 v177, v177
	v_pk_mul_f32 v[174:175], v[12:13], v[174:175]
	v_pk_mul_f32 v[176:177], v[14:15], v[176:177]
	v_cvt_pk_bf16_f32 v182, v174, v175
	v_cvt_pk_bf16_f32 v183, v176, v177
	global_store_dwordx2 v[162:163], v[182:183], off offset:192
	ds_write_b16 v150, v182 offset:13920
	ds_write_b16_d16_hi v150, v182 offset:14064
	ds_write_b16 v150, v183 offset:14208
	ds_write_b16_d16_hi v150, v183 offset:14352
	v_pk_mul_f32 v[174:175], v[4:5], v[4:5]
	v_pk_mul_f32 v[176:177], v[6:7], v[6:7]
	v_pk_fma_f32 v[174:175], v[174:175], v[170:171], v[168:169]
	v_pk_fma_f32 v[176:177], v[176:177], v[170:171], v[168:169]
	v_pk_mul_f32 v[174:175], v[4:5], v[174:175]
	v_pk_mul_f32 v[176:177], v[6:7], v[176:177]
	v_exp_f32_e32 v174, v174
	v_exp_f32_e32 v175, v175
	v_exp_f32_e32 v176, v176
	v_exp_f32_e32 v177, v177
	v_pk_add_f32 v[174:175], v[174:175], v[172:173]
	v_pk_add_f32 v[176:177], v[176:177], v[172:173]
	v_rcp_f32_e32 v174, v174
	v_rcp_f32_e32 v175, v175
	v_rcp_f32_e32 v176, v176
	v_rcp_f32_e32 v177, v177
	v_pk_mul_f32 v[174:175], v[4:5], v[174:175]
	v_pk_mul_f32 v[176:177], v[6:7], v[176:177]
	v_cvt_pk_bf16_f32 v178, v174, v175
	v_cvt_pk_bf16_f32 v179, v176, v177
	global_store_dwordx2 v[156:157], v[178:179], off offset:224
	ds_write_b16 v150, v178 offset:16128
	ds_write_b16_d16_hi v150, v178 offset:16272
	ds_write_b16 v150, v179 offset:16416
	ds_write_b16_d16_hi v150, v179 offset:16560
	v_pk_mul_f32 v[174:175], v[0:1], v[0:1]
	v_pk_mul_f32 v[176:177], v[2:3], v[2:3]
	v_pk_fma_f32 v[174:175], v[174:175], v[170:171], v[168:169]
	v_pk_fma_f32 v[176:177], v[176:177], v[170:171], v[168:169]
	v_pk_mul_f32 v[174:175], v[0:1], v[174:175]
	v_pk_mul_f32 v[176:177], v[2:3], v[176:177]
	v_exp_f32_e32 v174, v174
	v_exp_f32_e32 v175, v175
	v_exp_f32_e32 v176, v176
	v_exp_f32_e32 v177, v177
	v_pk_add_f32 v[174:175], v[174:175], v[172:173]
	v_pk_add_f32 v[176:177], v[176:177], v[172:173]
	v_rcp_f32_e32 v174, v174
	v_rcp_f32_e32 v175, v175
	v_rcp_f32_e32 v176, v176
	v_rcp_f32_e32 v177, v177
	v_pk_mul_f32 v[174:175], v[0:1], v[174:175]
	v_pk_mul_f32 v[176:177], v[2:3], v[176:177]
	v_cvt_pk_bf16_f32 v182, v174, v175
	v_cvt_pk_bf16_f32 v183, v176, v177
	global_store_dwordx2 v[158:159], v[182:183], off offset:224
	ds_write_b16 v150, v182 offset:16160
	ds_write_b16_d16_hi v150, v182 offset:16304
	ds_write_b16 v150, v183 offset:16448
	ds_write_b16_d16_hi v150, v183 offset:16592
	v_pk_mul_f32 v[174:175], v[20:21], v[20:21]
	v_pk_mul_f32 v[176:177], v[22:23], v[22:23]
	v_pk_fma_f32 v[174:175], v[174:175], v[170:171], v[168:169]
	v_pk_fma_f32 v[176:177], v[176:177], v[170:171], v[168:169]
	v_pk_mul_f32 v[174:175], v[20:21], v[174:175]
	v_pk_mul_f32 v[176:177], v[22:23], v[176:177]
	v_exp_f32_e32 v174, v174
	v_exp_f32_e32 v175, v175
	v_exp_f32_e32 v176, v176
	v_exp_f32_e32 v177, v177
	v_pk_add_f32 v[174:175], v[174:175], v[172:173]
	v_pk_add_f32 v[176:177], v[176:177], v[172:173]
	v_rcp_f32_e32 v174, v174
	v_rcp_f32_e32 v175, v175
	v_rcp_f32_e32 v176, v176
	v_rcp_f32_e32 v177, v177
	v_pk_mul_f32 v[174:175], v[20:21], v[174:175]
	v_pk_mul_f32 v[176:177], v[22:23], v[176:177]
	v_cvt_pk_bf16_f32 v178, v174, v175
	v_cvt_pk_bf16_f32 v179, v176, v177
	global_store_dwordx2 v[160:161], v[178:179], off offset:224
	ds_write_b16 v150, v178 offset:16192
	ds_write_b16_d16_hi v150, v178 offset:16336
	ds_write_b16 v150, v179 offset:16480
	ds_write_b16_d16_hi v150, v179 offset:16624
	v_pk_mul_f32 v[174:175], v[8:9], v[8:9]
	v_pk_mul_f32 v[176:177], v[10:11], v[10:11]
	v_pk_fma_f32 v[174:175], v[174:175], v[170:171], v[168:169]
	v_pk_fma_f32 v[176:177], v[176:177], v[170:171], v[168:169]
	v_pk_mul_f32 v[174:175], v[8:9], v[174:175]
	v_pk_mul_f32 v[176:177], v[10:11], v[176:177]
	v_exp_f32_e32 v174, v174
	v_exp_f32_e32 v175, v175
	v_exp_f32_e32 v176, v176
	v_exp_f32_e32 v177, v177
	v_pk_add_f32 v[174:175], v[174:175], v[172:173]
	v_pk_add_f32 v[176:177], v[176:177], v[172:173]
	v_rcp_f32_e32 v174, v174
	v_rcp_f32_e32 v175, v175
	v_rcp_f32_e32 v176, v176
	v_rcp_f32_e32 v177, v177
	v_pk_mul_f32 v[174:175], v[8:9], v[174:175]
	v_pk_mul_f32 v[176:177], v[10:11], v[176:177]
	v_cvt_pk_bf16_f32 v182, v174, v175
	v_cvt_pk_bf16_f32 v183, v176, v177
	global_store_dwordx2 v[162:163], v[182:183], off offset:224
	ds_write_b16 v150, v182 offset:16224
	ds_write_b16_d16_hi v150, v182 offset:16368
	ds_write_b16 v150, v183 offset:16512
	ds_write_b16_d16_hi v150, v183 offset:16656
	s_waitcnt lgkmcnt(0)
	ds_read_b128 v[184:187], v152
	ds_read_b128 v[188:191], v152 offset:1152
	ds_read_b128 v[192:195], v152 offset:2304
	ds_read_b128 v[196:199], v152 offset:3456
	ds_read_b128 v[200:203], v152 offset:4608
	ds_read_b128 v[204:207], v152 offset:5760
	ds_read_b128 v[208:211], v152 offset:6912
	ds_read_b128 v[212:215], v152 offset:8064
	s_waitcnt lgkmcnt(7)
	v_lshlrev_b32_e32 v134, 16, v184
	v_and_b32_e32 v135, 0xffff0000, v184
	v_lshlrev_b32_e32 v136, 16, v185
	v_and_b32_e32 v137, 0xffff0000, v185
	v_lshlrev_b32_e32 v138, 16, v186
	v_and_b32_e32 v139, 0xffff0000, v186
	v_lshlrev_b32_e32 v140, 16, v187
	v_and_b32_e32 v141, 0xffff0000, v187
	v_pk_mul_f32 v[142:143], v[134:135], v[134:135]
	v_pk_mul_f32 v[144:145], v[136:137], v[136:137]
	v_pk_mul_f32 v[248:249], v[138:139], v[138:139]
	v_pk_mul_f32 v[250:251], v[140:141], v[140:141]
	v_add_f32_e32 v184, v134, v135
	v_add_f32_e32 v185, v142, v143
	v_add_f32_e32 v158, v136, v137
	v_add_f32_e32 v159, v144, v145
	v_add_f32_e32 v160, v138, v139
	v_add_f32_e32 v161, v248, v249
	v_add_f32_e32 v162, v140, v141
	v_add_f32_e32 v163, v250, v251
	v_pk_add_f32 v[184:185], v[184:185], v[158:159]
	v_pk_add_f32 v[184:185], v[184:185], v[160:161]
	v_pk_add_f32 v[184:185], v[184:185], v[162:163]
	ds_read_b128 v[216:219], v152 offset:9216
	s_waitcnt lgkmcnt(7)
	v_lshlrev_b32_e32 v134, 16, v188
	v_and_b32_e32 v135, 0xffff0000, v188
	v_lshlrev_b32_e32 v136, 16, v189
	v_and_b32_e32 v137, 0xffff0000, v189
	v_lshlrev_b32_e32 v138, 16, v190
	v_and_b32_e32 v139, 0xffff0000, v190
	v_lshlrev_b32_e32 v140, 16, v191
	v_and_b32_e32 v141, 0xffff0000, v191
	v_pk_mul_f32 v[142:143], v[134:135], v[134:135]
	v_pk_mul_f32 v[144:145], v[136:137], v[136:137]
	v_pk_mul_f32 v[248:249], v[138:139], v[138:139]
	v_pk_mul_f32 v[250:251], v[140:141], v[140:141]
	v_add_f32_e32 v188, v134, v135
	v_add_f32_e32 v189, v142, v143
	v_add_f32_e32 v158, v136, v137
	v_add_f32_e32 v159, v144, v145
	v_add_f32_e32 v160, v138, v139
	v_add_f32_e32 v161, v248, v249
	v_add_f32_e32 v162, v140, v141
	v_add_f32_e32 v163, v250, v251
	v_pk_add_f32 v[188:189], v[188:189], v[158:159]
	v_pk_add_f32 v[188:189], v[188:189], v[160:161]
	v_pk_add_f32 v[188:189], v[188:189], v[162:163]
	ds_read_b128 v[220:223], v152 offset:10368
	s_nop 1
	v_add_f32_dpp v184, v184, v184 quad_perm:[1,0,3,2] row_mask:0xf bank_mask:0xf
	v_add_f32_dpp v185, v185, v185 quad_perm:[1,0,3,2] row_mask:0xf bank_mask:0xf
	v_add_f32_dpp v188, v188, v188 quad_perm:[1,0,3,2] row_mask:0xf bank_mask:0xf
	v_add_f32_dpp v189, v189, v189 quad_perm:[1,0,3,2] row_mask:0xf bank_mask:0xf
	v_add_f32_dpp v184, v184, v184 quad_perm:[2,3,0,1] row_mask:0xf bank_mask:0xf
	v_add_f32_dpp v185, v185, v185 quad_perm:[2,3,0,1] row_mask:0xf bank_mask:0xf
	v_add_f32_dpp v188, v188, v188 quad_perm:[2,3,0,1] row_mask:0xf bank_mask:0xf
	v_add_f32_dpp v189, v189, v189 quad_perm:[2,3,0,1] row_mask:0xf bank_mask:0xf
	v_add_f32_dpp v184, v184, v184 row_half_mirror row_mask:0xf bank_mask:0xf
	v_add_f32_dpp v185, v185, v185 row_half_mirror row_mask:0xf bank_mask:0xf
	v_add_f32_dpp v188, v188, v188 row_half_mirror row_mask:0xf bank_mask:0xf
	v_add_f32_dpp v189, v189, v189 row_half_mirror row_mask:0xf bank_mask:0xf
	s_waitcnt lgkmcnt(7)
	v_lshlrev_b32_e32 v134, 16, v192
	v_and_b32_e32 v135, 0xffff0000, v192
	v_lshlrev_b32_e32 v136, 16, v193
	v_and_b32_e32 v137, 0xffff0000, v193
	v_lshlrev_b32_e32 v138, 16, v194
	v_and_b32_e32 v139, 0xffff0000, v194
	v_lshlrev_b32_e32 v140, 16, v195
	v_and_b32_e32 v141, 0xffff0000, v195
	v_pk_mul_f32 v[142:143], v[134:135], v[134:135]
	v_pk_mul_f32 v[144:145], v[136:137], v[136:137]
	v_pk_mul_f32 v[248:249], v[138:139], v[138:139]
	v_pk_mul_f32 v[250:251], v[140:141], v[140:141]
	v_add_f32_e32 v192, v134, v135
	v_add_f32_e32 v193, v142, v143
	v_add_f32_e32 v158, v136, v137
	v_add_f32_e32 v159, v144, v145
	v_add_f32_e32 v160, v138, v139
	v_add_f32_e32 v161, v248, v249
	v_add_f32_e32 v162, v140, v141
	v_add_f32_e32 v163, v250, v251
	v_pk_add_f32 v[192:193], v[192:193], v[158:159]
	v_pk_add_f32 v[192:193], v[192:193], v[160:161]
	v_pk_add_f32 v[192:193], v[192:193], v[162:163]
	ds_read_b128 v[224:227], v152 offset:11520
	s_waitcnt lgkmcnt(7)
	v_lshlrev_b32_e32 v134, 16, v196
	v_and_b32_e32 v135, 0xffff0000, v196
	v_lshlrev_b32_e32 v136, 16, v197
	v_and_b32_e32 v137, 0xffff0000, v197
	v_lshlrev_b32_e32 v138, 16, v198
	v_and_b32_e32 v139, 0xffff0000, v198
	v_lshlrev_b32_e32 v140, 16, v199
	v_and_b32_e32 v141, 0xffff0000, v199
	v_pk_mul_f32 v[142:143], v[134:135], v[134:135]
	v_pk_mul_f32 v[144:145], v[136:137], v[136:137]
	v_pk_mul_f32 v[248:249], v[138:139], v[138:139]
	v_pk_mul_f32 v[250:251], v[140:141], v[140:141]
	v_add_f32_e32 v196, v134, v135
	v_add_f32_e32 v197, v142, v143
	v_add_f32_e32 v158, v136, v137
	v_add_f32_e32 v159, v144, v145
	v_add_f32_e32 v160, v138, v139
	v_add_f32_e32 v161, v248, v249
	v_add_f32_e32 v162, v140, v141
	v_add_f32_e32 v163, v250, v251
	v_pk_add_f32 v[196:197], v[196:197], v[158:159]
	v_pk_add_f32 v[196:197], v[196:197], v[160:161]
	v_pk_add_f32 v[196:197], v[196:197], v[162:163]
	ds_read_b128 v[228:231], v152 offset:12672
	s_nop 1
	v_add_f32_dpp v192, v192, v192 quad_perm:[1,0,3,2] row_mask:0xf bank_mask:0xf
	v_add_f32_dpp v193, v193, v193 quad_perm:[1,0,3,2] row_mask:0xf bank_mask:0xf
	v_add_f32_dpp v196, v196, v196 quad_perm:[1,0,3,2] row_mask:0xf bank_mask:0xf
	v_add_f32_dpp v197, v197, v197 quad_perm:[1,0,3,2] row_mask:0xf bank_mask:0xf
	v_add_f32_dpp v192, v192, v192 quad_perm:[2,3,0,1] row_mask:0xf bank_mask:0xf
	v_add_f32_dpp v193, v193, v193 quad_perm:[2,3,0,1] row_mask:0xf bank_mask:0xf
	v_add_f32_dpp v196, v196, v196 quad_perm:[2,3,0,1] row_mask:0xf bank_mask:0xf
	v_add_f32_dpp v197, v197, v197 quad_perm:[2,3,0,1] row_mask:0xf bank_mask:0xf
	v_add_f32_dpp v192, v192, v192 row_half_mirror row_mask:0xf bank_mask:0xf
	v_add_f32_dpp v193, v193, v193 row_half_mirror row_mask:0xf bank_mask:0xf
	v_add_f32_dpp v196, v196, v196 row_half_mirror row_mask:0xf bank_mask:0xf
	v_add_f32_dpp v197, v197, v197 row_half_mirror row_mask:0xf bank_mask:0xf
	s_waitcnt lgkmcnt(7)
	v_lshlrev_b32_e32 v134, 16, v200
	v_and_b32_e32 v135, 0xffff0000, v200
	v_lshlrev_b32_e32 v136, 16, v201
	v_and_b32_e32 v137, 0xffff0000, v201
	v_lshlrev_b32_e32 v138, 16, v202
	v_and_b32_e32 v139, 0xffff0000, v202
	v_lshlrev_b32_e32 v140, 16, v203
	v_and_b32_e32 v141, 0xffff0000, v203
	v_pk_mul_f32 v[142:143], v[134:135], v[134:135]
	v_pk_mul_f32 v[144:145], v[136:137], v[136:137]
	v_pk_mul_f32 v[248:249], v[138:139], v[138:139]
	v_pk_mul_f32 v[250:251], v[140:141], v[140:141]
	v_add_f32_e32 v200, v134, v135
	v_add_f32_e32 v201, v142, v143
	v_add_f32_e32 v158, v136, v137
	v_add_f32_e32 v159, v144, v145
	v_add_f32_e32 v160, v138, v139
	v_add_f32_e32 v161, v248, v249
	v_add_f32_e32 v162, v140, v141
	v_add_f32_e32 v163, v250, v251
	v_pk_add_f32 v[200:201], v[200:201], v[158:159]
	v_pk_add_f32 v[200:201], v[200:201], v[160:161]
	v_pk_add_f32 v[200:201], v[200:201], v[162:163]
	ds_read_b128 v[232:235], v152 offset:13824
	s_waitcnt lgkmcnt(7)
	v_lshlrev_b32_e32 v134, 16, v204
	v_and_b32_e32 v135, 0xffff0000, v204
	v_lshlrev_b32_e32 v136, 16, v205
	v_and_b32_e32 v137, 0xffff0000, v205
	v_lshlrev_b32_e32 v138, 16, v206
	v_and_b32_e32 v139, 0xffff0000, v206
	v_lshlrev_b32_e32 v140, 16, v207
	v_and_b32_e32 v141, 0xffff0000, v207
	v_pk_mul_f32 v[142:143], v[134:135], v[134:135]
	v_pk_mul_f32 v[144:145], v[136:137], v[136:137]
	v_pk_mul_f32 v[248:249], v[138:139], v[138:139]
	v_pk_mul_f32 v[250:251], v[140:141], v[140:141]
	v_add_f32_e32 v204, v134, v135
	v_add_f32_e32 v205, v142, v143
	v_add_f32_e32 v158, v136, v137
	v_add_f32_e32 v159, v144, v145
	v_add_f32_e32 v160, v138, v139
	v_add_f32_e32 v161, v248, v249
	v_add_f32_e32 v162, v140, v141
	v_add_f32_e32 v163, v250, v251
	v_pk_add_f32 v[204:205], v[204:205], v[158:159]
	v_pk_add_f32 v[204:205], v[204:205], v[160:161]
	v_pk_add_f32 v[204:205], v[204:205], v[162:163]
	ds_read_b128 v[236:239], v152 offset:14976
	s_nop 1
	v_add_f32_dpp v200, v200, v200 quad_perm:[1,0,3,2] row_mask:0xf bank_mask:0xf
	v_add_f32_dpp v201, v201, v201 quad_perm:[1,0,3,2] row_mask:0xf bank_mask:0xf
	v_add_f32_dpp v204, v204, v204 quad_perm:[1,0,3,2] row_mask:0xf bank_mask:0xf
	v_add_f32_dpp v205, v205, v205 quad_perm:[1,0,3,2] row_mask:0xf bank_mask:0xf
	v_add_f32_dpp v200, v200, v200 quad_perm:[2,3,0,1] row_mask:0xf bank_mask:0xf
	v_add_f32_dpp v201, v201, v201 quad_perm:[2,3,0,1] row_mask:0xf bank_mask:0xf
	v_add_f32_dpp v204, v204, v204 quad_perm:[2,3,0,1] row_mask:0xf bank_mask:0xf
	v_add_f32_dpp v205, v205, v205 quad_perm:[2,3,0,1] row_mask:0xf bank_mask:0xf
	v_add_f32_dpp v200, v200, v200 row_half_mirror row_mask:0xf bank_mask:0xf
	v_add_f32_dpp v201, v201, v201 row_half_mirror row_mask:0xf bank_mask:0xf
	v_add_f32_dpp v204, v204, v204 row_half_mirror row_mask:0xf bank_mask:0xf
	v_add_f32_dpp v205, v205, v205 row_half_mirror row_mask:0xf bank_mask:0xf
	s_waitcnt lgkmcnt(7)
	v_lshlrev_b32_e32 v134, 16, v208
	v_and_b32_e32 v135, 0xffff0000, v208
	v_lshlrev_b32_e32 v136, 16, v209
	v_and_b32_e32 v137, 0xffff0000, v209
	v_lshlrev_b32_e32 v138, 16, v210
	v_and_b32_e32 v139, 0xffff0000, v210
	v_lshlrev_b32_e32 v140, 16, v211
	v_and_b32_e32 v141, 0xffff0000, v211
	v_pk_mul_f32 v[142:143], v[134:135], v[134:135]
	v_pk_mul_f32 v[144:145], v[136:137], v[136:137]
	v_pk_mul_f32 v[248:249], v[138:139], v[138:139]
	v_pk_mul_f32 v[250:251], v[140:141], v[140:141]
	v_add_f32_e32 v208, v134, v135
	v_add_f32_e32 v209, v142, v143
	v_add_f32_e32 v158, v136, v137
	v_add_f32_e32 v159, v144, v145
	v_add_f32_e32 v160, v138, v139
	v_add_f32_e32 v161, v248, v249
	v_add_f32_e32 v162, v140, v141
	v_add_f32_e32 v163, v250, v251
	v_pk_add_f32 v[208:209], v[208:209], v[158:159]
	v_pk_add_f32 v[208:209], v[208:209], v[160:161]
	v_pk_add_f32 v[208:209], v[208:209], v[162:163]
	ds_read_b128 v[240:243], v152 offset:16128
	s_waitcnt lgkmcnt(7)
	v_lshlrev_b32_e32 v134, 16, v212
	v_and_b32_e32 v135, 0xffff0000, v212
	v_lshlrev_b32_e32 v136, 16, v213
	v_and_b32_e32 v137, 0xffff0000, v213
	v_lshlrev_b32_e32 v138, 16, v214
	v_and_b32_e32 v139, 0xffff0000, v214
	v_lshlrev_b32_e32 v140, 16, v215
	v_and_b32_e32 v141, 0xffff0000, v215
	v_pk_mul_f32 v[142:143], v[134:135], v[134:135]
	v_pk_mul_f32 v[144:145], v[136:137], v[136:137]
	v_pk_mul_f32 v[248:249], v[138:139], v[138:139]
	v_pk_mul_f32 v[250:251], v[140:141], v[140:141]
	v_add_f32_e32 v212, v134, v135
	v_add_f32_e32 v213, v142, v143
	v_add_f32_e32 v158, v136, v137
	v_add_f32_e32 v159, v144, v145
	v_add_f32_e32 v160, v138, v139
	v_add_f32_e32 v161, v248, v249
	v_add_f32_e32 v162, v140, v141
	v_add_f32_e32 v163, v250, v251
	v_pk_add_f32 v[212:213], v[212:213], v[158:159]
	v_pk_add_f32 v[212:213], v[212:213], v[160:161]
	v_pk_add_f32 v[212:213], v[212:213], v[162:163]
	ds_read_b128 v[244:247], v152 offset:17280
	s_nop 1
	v_add_f32_dpp v208, v208, v208 quad_perm:[1,0,3,2] row_mask:0xf bank_mask:0xf
	v_add_f32_dpp v209, v209, v209 quad_perm:[1,0,3,2] row_mask:0xf bank_mask:0xf
	v_add_f32_dpp v212, v212, v212 quad_perm:[1,0,3,2] row_mask:0xf bank_mask:0xf
	v_add_f32_dpp v213, v213, v213 quad_perm:[1,0,3,2] row_mask:0xf bank_mask:0xf
	v_add_f32_dpp v208, v208, v208 quad_perm:[2,3,0,1] row_mask:0xf bank_mask:0xf
	v_add_f32_dpp v209, v209, v209 quad_perm:[2,3,0,1] row_mask:0xf bank_mask:0xf
	v_add_f32_dpp v212, v212, v212 quad_perm:[2,3,0,1] row_mask:0xf bank_mask:0xf
	v_add_f32_dpp v213, v213, v213 quad_perm:[2,3,0,1] row_mask:0xf bank_mask:0xf
	v_add_f32_dpp v208, v208, v208 row_half_mirror row_mask:0xf bank_mask:0xf
	v_add_f32_dpp v209, v209, v209 row_half_mirror row_mask:0xf bank_mask:0xf
	v_add_f32_dpp v212, v212, v212 row_half_mirror row_mask:0xf bank_mask:0xf
	v_add_f32_dpp v213, v213, v213 row_half_mirror row_mask:0xf bank_mask:0xf
	s_waitcnt lgkmcnt(7)
	v_lshlrev_b32_e32 v134, 16, v216
	v_and_b32_e32 v135, 0xffff0000, v216
	v_lshlrev_b32_e32 v136, 16, v217
	v_and_b32_e32 v137, 0xffff0000, v217
	v_lshlrev_b32_e32 v138, 16, v218
	v_and_b32_e32 v139, 0xffff0000, v218
	v_lshlrev_b32_e32 v140, 16, v219
	v_and_b32_e32 v141, 0xffff0000, v219
	v_pk_mul_f32 v[142:143], v[134:135], v[134:135]
	v_pk_mul_f32 v[144:145], v[136:137], v[136:137]
	v_pk_mul_f32 v[248:249], v[138:139], v[138:139]
	v_pk_mul_f32 v[250:251], v[140:141], v[140:141]
	v_add_f32_e32 v216, v134, v135
	v_add_f32_e32 v217, v142, v143
	v_add_f32_e32 v158, v136, v137
	v_add_f32_e32 v159, v144, v145
	v_add_f32_e32 v160, v138, v139
	v_add_f32_e32 v161, v248, v249
	v_add_f32_e32 v162, v140, v141
	v_add_f32_e32 v163, v250, v251
	v_pk_add_f32 v[216:217], v[216:217], v[158:159]
	v_pk_add_f32 v[216:217], v[216:217], v[160:161]
	v_pk_add_f32 v[216:217], v[216:217], v[162:163]
	s_waitcnt lgkmcnt(6)
	v_lshlrev_b32_e32 v134, 16, v220
	v_and_b32_e32 v135, 0xffff0000, v220
	v_lshlrev_b32_e32 v136, 16, v221
	v_and_b32_e32 v137, 0xffff0000, v221
	v_lshlrev_b32_e32 v138, 16, v222
	v_and_b32_e32 v139, 0xffff0000, v222
	v_lshlrev_b32_e32 v140, 16, v223
	v_and_b32_e32 v141, 0xffff0000, v223
	v_pk_mul_f32 v[142:143], v[134:135], v[134:135]
	v_pk_mul_f32 v[144:145], v[136:137], v[136:137]
	v_pk_mul_f32 v[248:249], v[138:139], v[138:139]
	v_pk_mul_f32 v[250:251], v[140:141], v[140:141]
	v_add_f32_e32 v220, v134, v135
	v_add_f32_e32 v221, v142, v143
	v_add_f32_e32 v158, v136, v137
	v_add_f32_e32 v159, v144, v145
	v_add_f32_e32 v160, v138, v139
	v_add_f32_e32 v161, v248, v249
	v_add_f32_e32 v162, v140, v141
	v_add_f32_e32 v163, v250, v251
	v_pk_add_f32 v[220:221], v[220:221], v[158:159]
	v_pk_add_f32 v[220:221], v[220:221], v[160:161]
	v_pk_add_f32 v[220:221], v[220:221], v[162:163]
	s_nop 1
	v_add_f32_dpp v216, v216, v216 quad_perm:[1,0,3,2] row_mask:0xf bank_mask:0xf
	v_add_f32_dpp v217, v217, v217 quad_perm:[1,0,3,2] row_mask:0xf bank_mask:0xf
	v_add_f32_dpp v220, v220, v220 quad_perm:[1,0,3,2] row_mask:0xf bank_mask:0xf
	v_add_f32_dpp v221, v221, v221 quad_perm:[1,0,3,2] row_mask:0xf bank_mask:0xf
	v_add_f32_dpp v216, v216, v216 quad_perm:[2,3,0,1] row_mask:0xf bank_mask:0xf
	v_add_f32_dpp v217, v217, v217 quad_perm:[2,3,0,1] row_mask:0xf bank_mask:0xf
	v_add_f32_dpp v220, v220, v220 quad_perm:[2,3,0,1] row_mask:0xf bank_mask:0xf
	v_add_f32_dpp v221, v221, v221 quad_perm:[2,3,0,1] row_mask:0xf bank_mask:0xf
	v_add_f32_dpp v216, v216, v216 row_half_mirror row_mask:0xf bank_mask:0xf
	v_add_f32_dpp v217, v217, v217 row_half_mirror row_mask:0xf bank_mask:0xf
	v_add_f32_dpp v220, v220, v220 row_half_mirror row_mask:0xf bank_mask:0xf
	v_add_f32_dpp v221, v221, v221 row_half_mirror row_mask:0xf bank_mask:0xf
	s_waitcnt lgkmcnt(5)
	v_lshlrev_b32_e32 v134, 16, v224
	v_and_b32_e32 v135, 0xffff0000, v224
	v_lshlrev_b32_e32 v136, 16, v225
	v_and_b32_e32 v137, 0xffff0000, v225
	v_lshlrev_b32_e32 v138, 16, v226
	v_and_b32_e32 v139, 0xffff0000, v226
	v_lshlrev_b32_e32 v140, 16, v227
	v_and_b32_e32 v141, 0xffff0000, v227
	v_pk_mul_f32 v[142:143], v[134:135], v[134:135]
	v_pk_mul_f32 v[144:145], v[136:137], v[136:137]
	v_pk_mul_f32 v[248:249], v[138:139], v[138:139]
	v_pk_mul_f32 v[250:251], v[140:141], v[140:141]
	v_add_f32_e32 v224, v134, v135
	v_add_f32_e32 v225, v142, v143
	v_add_f32_e32 v158, v136, v137
	v_add_f32_e32 v159, v144, v145
	v_add_f32_e32 v160, v138, v139
	v_add_f32_e32 v161, v248, v249
	v_add_f32_e32 v162, v140, v141
	v_add_f32_e32 v163, v250, v251
	v_pk_add_f32 v[224:225], v[224:225], v[158:159]
	v_pk_add_f32 v[224:225], v[224:225], v[160:161]
	v_pk_add_f32 v[224:225], v[224:225], v[162:163]
	s_waitcnt lgkmcnt(4)
	v_lshlrev_b32_e32 v134, 16, v228
	v_and_b32_e32 v135, 0xffff0000, v228
	v_lshlrev_b32_e32 v136, 16, v229
	v_and_b32_e32 v137, 0xffff0000, v229
	v_lshlrev_b32_e32 v138, 16, v230
	v_and_b32_e32 v139, 0xffff0000, v230
	v_lshlrev_b32_e32 v140, 16, v231
	v_and_b32_e32 v141, 0xffff0000, v231
	v_pk_mul_f32 v[142:143], v[134:135], v[134:135]
	v_pk_mul_f32 v[144:145], v[136:137], v[136:137]
	v_pk_mul_f32 v[248:249], v[138:139], v[138:139]
	v_pk_mul_f32 v[250:251], v[140:141], v[140:141]
	v_add_f32_e32 v228, v134, v135
	v_add_f32_e32 v229, v142, v143
	v_add_f32_e32 v158, v136, v137
	v_add_f32_e32 v159, v144, v145
	v_add_f32_e32 v160, v138, v139
	v_add_f32_e32 v161, v248, v249
	v_add_f32_e32 v162, v140, v141
	v_add_f32_e32 v163, v250, v251
	v_pk_add_f32 v[228:229], v[228:229], v[158:159]
	v_pk_add_f32 v[228:229], v[228:229], v[160:161]
	v_pk_add_f32 v[228:229], v[228:229], v[162:163]
	s_nop 1
	v_add_f32_dpp v224, v224, v224 quad_perm:[1,0,3,2] row_mask:0xf bank_mask:0xf
	v_add_f32_dpp v225, v225, v225 quad_perm:[1,0,3,2] row_mask:0xf bank_mask:0xf
	v_add_f32_dpp v228, v228, v228 quad_perm:[1,0,3,2] row_mask:0xf bank_mask:0xf
	v_add_f32_dpp v229, v229, v229 quad_perm:[1,0,3,2] row_mask:0xf bank_mask:0xf
	v_add_f32_dpp v224, v224, v224 quad_perm:[2,3,0,1] row_mask:0xf bank_mask:0xf
	v_add_f32_dpp v225, v225, v225 quad_perm:[2,3,0,1] row_mask:0xf bank_mask:0xf
	v_add_f32_dpp v228, v228, v228 quad_perm:[2,3,0,1] row_mask:0xf bank_mask:0xf
	v_add_f32_dpp v229, v229, v229 quad_perm:[2,3,0,1] row_mask:0xf bank_mask:0xf
	v_add_f32_dpp v224, v224, v224 row_half_mirror row_mask:0xf bank_mask:0xf
	v_add_f32_dpp v225, v225, v225 row_half_mirror row_mask:0xf bank_mask:0xf
	v_add_f32_dpp v228, v228, v228 row_half_mirror row_mask:0xf bank_mask:0xf
	v_add_f32_dpp v229, v229, v229 row_half_mirror row_mask:0xf bank_mask:0xf
	s_waitcnt lgkmcnt(3)
	v_lshlrev_b32_e32 v134, 16, v232
	v_and_b32_e32 v135, 0xffff0000, v232
	v_lshlrev_b32_e32 v136, 16, v233
	v_and_b32_e32 v137, 0xffff0000, v233
	v_lshlrev_b32_e32 v138, 16, v234
	v_and_b32_e32 v139, 0xffff0000, v234
	v_lshlrev_b32_e32 v140, 16, v235
	v_and_b32_e32 v141, 0xffff0000, v235
	v_pk_mul_f32 v[142:143], v[134:135], v[134:135]
	v_pk_mul_f32 v[144:145], v[136:137], v[136:137]
	v_pk_mul_f32 v[248:249], v[138:139], v[138:139]
	v_pk_mul_f32 v[250:251], v[140:141], v[140:141]
	v_add_f32_e32 v232, v134, v135
	v_add_f32_e32 v233, v142, v143
	v_add_f32_e32 v158, v136, v137
	v_add_f32_e32 v159, v144, v145
	v_add_f32_e32 v160, v138, v139
	v_add_f32_e32 v161, v248, v249
	v_add_f32_e32 v162, v140, v141
	v_add_f32_e32 v163, v250, v251
	v_pk_add_f32 v[232:233], v[232:233], v[158:159]
	v_pk_add_f32 v[232:233], v[232:233], v[160:161]
	v_pk_add_f32 v[232:233], v[232:233], v[162:163]
	s_waitcnt lgkmcnt(2)
	v_lshlrev_b32_e32 v134, 16, v236
	v_and_b32_e32 v135, 0xffff0000, v236
	v_lshlrev_b32_e32 v136, 16, v237
	v_and_b32_e32 v137, 0xffff0000, v237
	v_lshlrev_b32_e32 v138, 16, v238
	v_and_b32_e32 v139, 0xffff0000, v238
	v_lshlrev_b32_e32 v140, 16, v239
	v_and_b32_e32 v141, 0xffff0000, v239
	v_pk_mul_f32 v[142:143], v[134:135], v[134:135]
	v_pk_mul_f32 v[144:145], v[136:137], v[136:137]
	v_pk_mul_f32 v[248:249], v[138:139], v[138:139]
	v_pk_mul_f32 v[250:251], v[140:141], v[140:141]
	v_add_f32_e32 v236, v134, v135
	v_add_f32_e32 v237, v142, v143
	v_add_f32_e32 v158, v136, v137
	v_add_f32_e32 v159, v144, v145
	v_add_f32_e32 v160, v138, v139
	v_add_f32_e32 v161, v248, v249
	v_add_f32_e32 v162, v140, v141
	v_add_f32_e32 v163, v250, v251
	v_pk_add_f32 v[236:237], v[236:237], v[158:159]
	v_pk_add_f32 v[236:237], v[236:237], v[160:161]
	v_pk_add_f32 v[236:237], v[236:237], v[162:163]
	s_nop 1
	v_add_f32_dpp v232, v232, v232 quad_perm:[1,0,3,2] row_mask:0xf bank_mask:0xf
	v_add_f32_dpp v233, v233, v233 quad_perm:[1,0,3,2] row_mask:0xf bank_mask:0xf
	v_add_f32_dpp v236, v236, v236 quad_perm:[1,0,3,2] row_mask:0xf bank_mask:0xf
	v_add_f32_dpp v237, v237, v237 quad_perm:[1,0,3,2] row_mask:0xf bank_mask:0xf
	v_add_f32_dpp v232, v232, v232 quad_perm:[2,3,0,1] row_mask:0xf bank_mask:0xf
	v_add_f32_dpp v233, v233, v233 quad_perm:[2,3,0,1] row_mask:0xf bank_mask:0xf
	v_add_f32_dpp v236, v236, v236 quad_perm:[2,3,0,1] row_mask:0xf bank_mask:0xf
	v_add_f32_dpp v237, v237, v237 quad_perm:[2,3,0,1] row_mask:0xf bank_mask:0xf
	v_add_f32_dpp v232, v232, v232 row_half_mirror row_mask:0xf bank_mask:0xf
	v_add_f32_dpp v233, v233, v233 row_half_mirror row_mask:0xf bank_mask:0xf
	v_add_f32_dpp v236, v236, v236 row_half_mirror row_mask:0xf bank_mask:0xf
	v_add_f32_dpp v237, v237, v237 row_half_mirror row_mask:0xf bank_mask:0xf
	s_waitcnt lgkmcnt(1)
	v_lshlrev_b32_e32 v134, 16, v240
	v_and_b32_e32 v135, 0xffff0000, v240
	v_lshlrev_b32_e32 v136, 16, v241
	v_and_b32_e32 v137, 0xffff0000, v241
	v_lshlrev_b32_e32 v138, 16, v242
	v_and_b32_e32 v139, 0xffff0000, v242
	v_lshlrev_b32_e32 v140, 16, v243
	v_and_b32_e32 v141, 0xffff0000, v243
	v_pk_mul_f32 v[142:143], v[134:135], v[134:135]
	v_pk_mul_f32 v[144:145], v[136:137], v[136:137]
	v_pk_mul_f32 v[248:249], v[138:139], v[138:139]
	v_pk_mul_f32 v[250:251], v[140:141], v[140:141]
	v_add_f32_e32 v240, v134, v135
	v_add_f32_e32 v241, v142, v143
	v_add_f32_e32 v158, v136, v137
	v_add_f32_e32 v159, v144, v145
	v_add_f32_e32 v160, v138, v139
	v_add_f32_e32 v161, v248, v249
	v_add_f32_e32 v162, v140, v141
	v_add_f32_e32 v163, v250, v251
	v_pk_add_f32 v[240:241], v[240:241], v[158:159]
	v_pk_add_f32 v[240:241], v[240:241], v[160:161]
	v_pk_add_f32 v[240:241], v[240:241], v[162:163]
	s_waitcnt lgkmcnt(0)
	v_lshlrev_b32_e32 v134, 16, v244
	v_and_b32_e32 v135, 0xffff0000, v244
	v_lshlrev_b32_e32 v136, 16, v245
	v_and_b32_e32 v137, 0xffff0000, v245
	v_lshlrev_b32_e32 v138, 16, v246
	v_and_b32_e32 v139, 0xffff0000, v246
	v_lshlrev_b32_e32 v140, 16, v247
	v_and_b32_e32 v141, 0xffff0000, v247
	v_pk_mul_f32 v[142:143], v[134:135], v[134:135]
	v_pk_mul_f32 v[144:145], v[136:137], v[136:137]
	v_pk_mul_f32 v[248:249], v[138:139], v[138:139]
	v_pk_mul_f32 v[250:251], v[140:141], v[140:141]
	v_add_f32_e32 v244, v134, v135
	v_add_f32_e32 v245, v142, v143
	v_add_f32_e32 v158, v136, v137
	v_add_f32_e32 v159, v144, v145
	v_add_f32_e32 v160, v138, v139
	v_add_f32_e32 v161, v248, v249
	v_add_f32_e32 v162, v140, v141
	v_add_f32_e32 v163, v250, v251
	v_pk_add_f32 v[244:245], v[244:245], v[158:159]
	v_pk_add_f32 v[244:245], v[244:245], v[160:161]
	v_pk_add_f32 v[244:245], v[244:245], v[162:163]
	s_nop 1
	v_add_f32_dpp v240, v240, v240 quad_perm:[1,0,3,2] row_mask:0xf bank_mask:0xf
	v_add_f32_dpp v241, v241, v241 quad_perm:[1,0,3,2] row_mask:0xf bank_mask:0xf
	v_add_f32_dpp v244, v244, v244 quad_perm:[1,0,3,2] row_mask:0xf bank_mask:0xf
	v_add_f32_dpp v245, v245, v245 quad_perm:[1,0,3,2] row_mask:0xf bank_mask:0xf
	v_add_f32_dpp v240, v240, v240 quad_perm:[2,3,0,1] row_mask:0xf bank_mask:0xf
	v_add_f32_dpp v241, v241, v241 quad_perm:[2,3,0,1] row_mask:0xf bank_mask:0xf
	v_add_f32_dpp v244, v244, v244 quad_perm:[2,3,0,1] row_mask:0xf bank_mask:0xf
	v_add_f32_dpp v245, v245, v245 quad_perm:[2,3,0,1] row_mask:0xf bank_mask:0xf
	v_add_f32_dpp v240, v240, v240 row_half_mirror row_mask:0xf bank_mask:0xf
	v_add_f32_dpp v241, v241, v241 row_half_mirror row_mask:0xf bank_mask:0xf
	v_add_f32_dpp v244, v244, v244 row_half_mirror row_mask:0xf bank_mask:0xf
	v_add_f32_dpp v245, v245, v245 row_half_mirror row_mask:0xf bank_mask:0xf
	s_and_saveexec_b64 s[60:61], s[4:5]
	global_store_dwordx2 v129, v[184:185], s[8:9]
	v_add_u32_e32 v129, 0x800, v129
	global_store_dwordx2 v129, v[188:189], s[8:9]
	v_add_u32_e32 v129, 0x800, v129
	global_store_dwordx2 v129, v[192:193], s[8:9]
	v_add_u32_e32 v129, 0x800, v129
	global_store_dwordx2 v129, v[196:197], s[8:9]
	v_add_u32_e32 v129, 0x800, v129
	global_store_dwordx2 v129, v[200:201], s[8:9]
	v_add_u32_e32 v129, 0x800, v129
	global_store_dwordx2 v129, v[204:205], s[8:9]
	v_add_u32_e32 v129, 0x800, v129
	global_store_dwordx2 v129, v[208:209], s[8:9]
	v_add_u32_e32 v129, 0x800, v129
	global_store_dwordx2 v129, v[212:213], s[8:9]
	v_add_u32_e32 v129, 0x800, v129
	global_store_dwordx2 v129, v[216:217], s[8:9]
	v_add_u32_e32 v129, 0x800, v129
	global_store_dwordx2 v129, v[220:221], s[8:9]
	v_add_u32_e32 v129, 0x800, v129
	global_store_dwordx2 v129, v[224:225], s[8:9]
	v_add_u32_e32 v129, 0x800, v129
	global_store_dwordx2 v129, v[228:229], s[8:9]
	v_add_u32_e32 v129, 0x800, v129
	global_store_dwordx2 v129, v[232:233], s[8:9]
	v_add_u32_e32 v129, 0x800, v129
	global_store_dwordx2 v129, v[236:237], s[8:9]
	v_add_u32_e32 v129, 0x800, v129
	global_store_dwordx2 v129, v[240:241], s[8:9]
	v_add_u32_e32 v129, 0x800, v129
	global_store_dwordx2 v129, v[244:245], s[8:9]
	s_or_b64 exec, exec, s[60:61]
	s_waitcnt lgkmcnt(0)

.LBB0_263:
	s_ashr_i32 s21, s58, 2
	v_mov_b32_e32 v6, v181
	s_and_b32 s6, s58, 7
	s_and_b32 s21, s21, -8
	s_or_b32 s48, s21, s6
	v_lshrrev_b32_e32 v7, 4, v6
	v_lshlrev_b32_e32 v1, 6, v6
	v_xor_b32_e32 v0, v7, v6
	v_and_b32_e32 v8, 0x3c0, v1
	v_lshlrev_b32_e32 v1, 8, v6
	s_ashr_i32 s49, s48, 31
	v_lshlrev_b32_e32 v0, 3, v0
	v_and_b32_e32 v1, 0xfffff800, v1
	s_and_b32 s20, s57, 7
	s_bfe_u32 s6, s58, 0x20003
	s_lshl_b64 s[50:51], s[48:49], 20
	v_and_or_b32 v0, v0, 56, v1
	s_add_u32 s50, s3, s50
	v_ashrrev_i32_e32 v1, 31, v0
	s_addc_u32 s51, s54, s51
	v_lshlrev_b64 v[0:1], 1, v[0:1]
	v_lshl_add_u32 v135, v6, 4, 0
	v_lshl_add_u64 v[2:3], s[50:51], 0, v[0:1]
	v_readfirstlane_b32 s50, v135
	v_add_u32_e32 v9, 0x2000, v135
	s_mov_b32 m0, s50
	v_readfirstlane_b32 s50, v9
	v_add_u32_e32 v9, 0x4000, v135
	s_waitcnt lgkmcnt(0)
	s_barrier
	global_load_lds_dwordx4 v[2:3], off
	v_lshl_add_u64 v[4:5], v[2:3], 0, s[8:9]
	s_mov_b32 m0, s50
	v_readfirstlane_b32 s50, v9
	global_load_lds_dwordx4 v[4:5], off
	v_lshl_add_u64 v[4:5], v[2:3], 0, s[10:11]
	s_mov_b32 m0, s50
	s_lshl_b32 s49, s6, 20
	global_load_lds_dwordx4 v[4:5], off
	v_add_u32_e32 v4, 0x6000, v135
	s_add_u32 s52, s55, s49
	v_readfirstlane_b32 s50, v4
	v_add_u32_e32 v4, 0x8000, v135
	s_addc_u32 s53, s56, 0
	v_lshl_add_u64 v[2:3], v[2:3], 0, s[12:13]
	s_mov_b32 m0, s50
	v_readfirstlane_b32 s50, v4
	v_add_u32_e32 v9, 0xa000, v135
	global_load_lds_dwordx4 v[2:3], off
	v_lshl_add_u64 v[2:3], s[52:53], 0, v[0:1]
	s_mov_b32 m0, s50
	v_readfirstlane_b32 s50, v9
	v_add_u32_e32 v9, 0xc000, v135
	global_load_lds_dwordx4 v[2:3], off
	v_lshl_add_u64 v[4:5], v[2:3], 0, s[8:9]
	s_mov_b32 m0, s50
	v_readfirstlane_b32 s50, v9
	global_load_lds_dwordx4 v[4:5], off
	v_lshl_add_u64 v[4:5], v[2:3], 0, s[10:11]
	s_mov_b32 m0, s50
	v_lshl_add_u64 v[2:3], v[2:3], 0, s[12:13]
	global_load_lds_dwordx4 v[4:5], off
	v_add_u32_e32 v4, 0xe000, v135
	v_mov_b32_e32 v12, 0
	v_readfirstlane_b32 s50, v4
	s_mov_b32 m0, s50
	v_ashrrev_i32_e32 v4, 6, v6
	global_load_lds_dwordx4 v[2:3], off
	s_or_b32 s50, s21, s20
	v_lshrrev_b32_e32 v5, 30, v4
	s_ashr_i32 s51, s50, 31
	v_add_u32_e32 v5, v4, v5
	s_lshl_b64 s[50:51], s[50:51], 20
	v_bfe_u32 v2, v6, 4, 2
	v_bfe_u32 v3, v6, 1, 3
	v_and_b32_e32 v6, 0x7fffc, v5
	s_add_u32 s50, s34, s50
	v_sub_u32_e32 v4, v4, v6
	s_addc_u32 s51, s35, s51
	v_lshlrev_b32_e32 v137, 13, v4
	v_bitop3_b32 v4, v7, v3, 3 bitop3:0x6c
	v_bitop3_b32 v2, v2, v3, 4 bitop3:0x36
	v_lshl_add_u64 v[130:131], s[50:51], 0, v[0:1]
	s_add_u32 s50, s34, s49
	v_lshlrev_b32_e32 v5, 12, v5
	v_lshlrev_b32_e32 v4, 3, v4
	v_lshlrev_b32_e32 v2, 3, v2
	s_addc_u32 s51, s35, 0
	v_and_b32_e32 v136, 0xffffc000, v5
	v_lshl_add_u64 v[132:133], s[50:51], 0, v[0:1]
	s_mov_b64 s[50:51], 0
	v_lshlrev_b32_e32 v138, 1, v8
	v_lshlrev_b32_e32 v139, 1, v4
	v_lshlrev_b32_e32 v140, 1, v2
	s_mov_b32 s59, 0
	s_mov_b32 s49, 0
	v_mov_b32_e32 v13, v12
	v_mov_b32_e32 v14, v12
	v_mov_b32_e32 v15, v12
	v_mov_b32_e32 v24, v12
	v_mov_b32_e32 v25, v12
	v_mov_b32_e32 v26, v12
	v_mov_b32_e32 v27, v12
	v_mov_b32_e32 v0, v12
	v_mov_b32_e32 v1, v12
	v_mov_b32_e32 v2, v12
	v_mov_b32_e32 v3, v12
	v_mov_b32_e32 v4, v12
	v_mov_b32_e32 v5, v12
	v_mov_b32_e32 v6, v12
	v_mov_b32_e32 v7, v12
	v_mov_b32_e32 v8, v12
	v_mov_b32_e32 v9, v12
	v_mov_b32_e32 v10, v12
	v_mov_b32_e32 v11, v12
	v_mov_b32_e32 v16, v12
	v_mov_b32_e32 v17, v12
	v_mov_b32_e32 v18, v12
	v_mov_b32_e32 v19, v12
	v_mov_b32_e32 v20, v12
	v_mov_b32_e32 v21, v12
	v_mov_b32_e32 v22, v12
	v_mov_b32_e32 v23, v12
	v_mov_b32_e32 v28, v12
	v_mov_b32_e32 v29, v12
	v_mov_b32_e32 v30, v12
	v_mov_b32_e32 v31, v12
	v_mov_b32_e32 v32, v12
	v_mov_b32_e32 v33, v12
	v_mov_b32_e32 v34, v12
	v_mov_b32_e32 v35, v12
	v_mov_b32_e32 v36, v12
	v_mov_b32_e32 v37, v12
	v_mov_b32_e32 v38, v12
	v_mov_b32_e32 v39, v12
	v_mov_b32_e32 v40, v12
	v_mov_b32_e32 v41, v12
	v_mov_b32_e32 v42, v12
	v_mov_b32_e32 v43, v12
	v_mov_b32_e32 v44, v12
	v_mov_b32_e32 v45, v12
	v_mov_b32_e32 v46, v12
	v_mov_b32_e32 v47, v12
	v_mov_b32_e32 v48, v12
	v_mov_b32_e32 v49, v12
	v_mov_b32_e32 v50, v12
	v_mov_b32_e32 v51, v12
	v_mov_b32_e32 v52, v12
	v_mov_b32_e32 v53, v12
	v_mov_b32_e32 v54, v12
	v_mov_b32_e32 v55, v12
	v_mov_b32_e32 v56, v12
	v_mov_b32_e32 v57, v12
	v_mov_b32_e32 v58, v12
	v_mov_b32_e32 v59, v12
	v_mov_b32_e32 v60, v12
	v_mov_b32_e32 v61, v12
	v_mov_b32_e32 v62, v12
	v_mov_b32_e32 v63, v12
	v_mov_b32_e32 v64, v12
	v_mov_b32_e32 v65, v12
	v_mov_b32_e32 v66, v12
	v_mov_b32_e32 v67, v12
	v_mov_b32_e32 v68, v12
	v_mov_b32_e32 v69, v12
	v_mov_b32_e32 v70, v12
	v_mov_b32_e32 v71, v12
	v_mov_b32_e32 v72, v12
	v_mov_b32_e32 v73, v12
	v_mov_b32_e32 v74, v12
	v_mov_b32_e32 v75, v12
	v_mov_b32_e32 v76, v12
	v_mov_b32_e32 v77, v12
	v_mov_b32_e32 v78, v12
	v_mov_b32_e32 v79, v12
	v_mov_b32_e32 v80, v12
	v_mov_b32_e32 v81, v12
	v_mov_b32_e32 v82, v12
	v_mov_b32_e32 v83, v12
	v_mov_b32_e32 v84, v12
	v_mov_b32_e32 v85, v12
	v_mov_b32_e32 v86, v12
	v_mov_b32_e32 v87, v12
	v_mov_b32_e32 v88, v12
	v_mov_b32_e32 v89, v12
	v_mov_b32_e32 v90, v12
	v_mov_b32_e32 v91, v12
	v_mov_b32_e32 v92, v12
	v_mov_b32_e32 v93, v12
	v_mov_b32_e32 v94, v12
	v_mov_b32_e32 v95, v12
	v_mov_b32_e32 v96, v12
	v_mov_b32_e32 v97, v12
	v_mov_b32_e32 v98, v12
	v_mov_b32_e32 v99, v12
	v_mov_b32_e32 v100, v12
	v_mov_b32_e32 v101, v12
	v_mov_b32_e32 v102, v12
	v_mov_b32_e32 v103, v12
	v_mov_b32_e32 v104, v12
	v_mov_b32_e32 v105, v12
	v_mov_b32_e32 v106, v12
	v_mov_b32_e32 v107, v12
	v_mov_b32_e32 v108, v12
	v_mov_b32_e32 v109, v12
	v_mov_b32_e32 v110, v12
	v_mov_b32_e32 v111, v12
	v_mov_b32_e32 v112, v12
	v_mov_b32_e32 v113, v12
	v_mov_b32_e32 v114, v12
	v_mov_b32_e32 v115, v12
	v_mov_b32_e32 v116, v12
	v_mov_b32_e32 v117, v12
	v_mov_b32_e32 v118, v12
	v_mov_b32_e32 v119, v12
	v_mov_b32_e32 v120, v12
	v_mov_b32_e32 v121, v12
	v_mov_b32_e32 v122, v12
	v_mov_b32_e32 v123, v12
	v_mov_b32_e32 v124, v12
	v_mov_b32_e32 v125, v12
	v_mov_b32_e32 v126, v12
	v_mov_b32_e32 v127, v12
	s_waitcnt vmcnt(0) lgkmcnt(0)
	s_barrier
	v_add3_u32 v141, v136, v138, v139
	v_add3_u32 v210, v137, v138, v139
	v_add3_u32 v180, v136, v138, v140
	v_add3_u32 v211, v137, v138, v140
	v_readfirstlane_b32 s59, v135
	ds_read_b128 v[142:145], v141
	ds_read_b128 v[146:149], v141 offset:2048
	ds_read_b128 v[150:153], v141 offset:4096
	ds_read_b128 v[154:157], v141 offset:6144
	ds_read_b128 v[174:177], v210 offset:32768
	ds_read_b128 v[182:185], v210 offset:34816
	ds_read_b128 v[186:189], v210 offset:36864
	ds_read_b128 v[190:193], v210 offset:38912
	s_mov_b32 s49, 0
	s_mov_b64 s[50:51], s[34:35]
	v_subrev_u32_e32 v178, s34, v130
	v_subrev_u32_e32 v179, s34, v132
	s_add_u32 s59, s59, 0x10000
	s_mov_b32 m0, s59
	s_add_u32 s52, s50, s14
	s_addc_u32 s53, s51, s15
	global_load_lds_dwordx4 v178, s[52:53]
	s_add_u32 m0, s59, 0x2000
	s_add_u32 s52, s50, s16
	s_addc_u32 s53, s51, s17
	global_load_lds_dwordx4 v178, s[52:53]
	s_add_u32 m0, s59, 0x4000
	s_add_u32 s52, s50, s18
	s_addc_u32 s53, s51, s19
	global_load_lds_dwordx4 v178, s[52:53]
	s_add_u32 m0, s59, 0x6000
	s_add_u32 s52, s50, s22
	s_addc_u32 s53, s51, s23
	global_load_lds_dwordx4 v178, s[52:53]
	s_add_u32 m0, s59, 0x8000
	s_add_u32 s52, s50, s40
	s_addc_u32 s53, s51, s41
	global_load_lds_dwordx4 v179, s[52:53]
	s_add_u32 m0, s59, 0xa000
	s_add_u32 s52, s50, s42
	s_addc_u32 s53, s51, s43
	global_load_lds_dwordx4 v179, s[52:53]
	s_add_u32 m0, s59, 0xc000
	s_add_u32 s52, s50, s44
	s_addc_u32 s53, s51, s45
	global_load_lds_dwordx4 v179, s[52:53]
	s_add_u32 m0, s59, 0xe000
	s_add_u32 s52, s50, s46
	s_addc_u32 s53, s51, s47
	global_load_lds_dwordx4 v179, s[52:53]
	s_branch .Lg1_entry
.Lg1_top:
	s_waitcnt lgkmcnt(0)
	s_waitcnt vmcnt(0)
	s_barrier
	v_xor_b32_e32 v141, 0x10000, v141
	v_xor_b32_e32 v210, 0x10000, v210
	v_xor_b32_e32 v180, 0x10000, v180
	v_xor_b32_e32 v211, 0x10000, v211
	s_xor_b32 s59, s59, 0x10000
	ds_read_b128 v[142:145], v141
	ds_read_b128 v[146:149], v141 offset:2048
	ds_read_b128 v[150:153], v141 offset:4096
	ds_read_b128 v[154:157], v141 offset:6144
	ds_read_b128 v[174:177], v210 offset:32768
	ds_read_b128 v[182:185], v210 offset:34816
	ds_read_b128 v[186:189], v210 offset:36864
	ds_read_b128 v[190:193], v210 offset:38912
	v_mfma_f32_16x16x32_bf16 v[60:63], v[158:161], v[194:197], v[60:63]
	v_mfma_f32_16x16x32_bf16 v[56:59], v[158:161], v[198:201], v[56:59]
	s_mov_b32 m0, s59
	s_add_u32 s52, s50, s14
	s_addc_u32 s53, s51, s15
	global_load_lds_dwordx4 v178, s[52:53]
	v_mfma_f32_16x16x32_bf16 v[52:55], v[158:161], v[202:205], v[52:55]
	v_mfma_f32_16x16x32_bf16 v[48:51], v[158:161], v[206:209], v[48:51]
	s_add_u32 m0, s59, 0x2000
	s_add_u32 s52, s50, s16
	s_addc_u32 s53, s51, s17
	global_load_lds_dwordx4 v178, s[52:53]
	v_mfma_f32_16x16x32_bf16 v[44:47], v[162:165], v[194:197], v[44:47]
	v_mfma_f32_16x16x32_bf16 v[40:43], v[162:165], v[198:201], v[40:43]
	s_add_u32 m0, s59, 0x4000
	s_add_u32 s52, s50, s18
	s_addc_u32 s53, s51, s19
	global_load_lds_dwordx4 v178, s[52:53]
	v_mfma_f32_16x16x32_bf16 v[36:39], v[162:165], v[202:205], v[36:39]
	v_mfma_f32_16x16x32_bf16 v[32:35], v[162:165], v[206:209], v[32:35]
	s_add_u32 m0, s59, 0x6000
	s_add_u32 s52, s50, s22
	s_addc_u32 s53, s51, s23
	global_load_lds_dwordx4 v178, s[52:53]
	v_mfma_f32_16x16x32_bf16 v[28:31], v[166:169], v[194:197], v[28:31]
	v_mfma_f32_16x16x32_bf16 v[20:23], v[166:169], v[198:201], v[20:23]
	s_add_u32 m0, s59, 0x8000
	s_add_u32 s52, s50, s40
	s_addc_u32 s53, s51, s41
	global_load_lds_dwordx4 v179, s[52:53]
	v_mfma_f32_16x16x32_bf16 v[16:19], v[166:169], v[202:205], v[16:19]
	v_mfma_f32_16x16x32_bf16 v[8:11], v[166:169], v[206:209], v[8:11]
	s_add_u32 m0, s59, 0xa000
	s_add_u32 s52, s50, s42
	s_addc_u32 s53, s51, s43
	global_load_lds_dwordx4 v179, s[52:53]
	v_mfma_f32_16x16x32_bf16 v[4:7], v[170:173], v[194:197], v[4:7]
	v_mfma_f32_16x16x32_bf16 v[0:3], v[170:173], v[198:201], v[0:3]
	s_add_u32 m0, s59, 0xc000
	s_add_u32 s52, s50, s44
	s_addc_u32 s53, s51, s45
	global_load_lds_dwordx4 v179, s[52:53]
	v_mfma_f32_16x16x32_bf16 v[24:27], v[170:173], v[202:205], v[24:27]
	v_mfma_f32_16x16x32_bf16 v[12:15], v[170:173], v[206:209], v[12:15]
	s_add_u32 m0, s59, 0xe000
	s_add_u32 s52, s50, s46
	s_addc_u32 s53, s51, s47
	global_load_lds_dwordx4 v179, s[52:53]

.LBB0_452:
	s_ashr_i32 s46, s60, 3
	s_and_b32 s21, s60, 7
	s_and_b32 s62, s46, -8
	v_mov_b32_e32 v6, v181
	s_or_b32 s46, s62, s21
	s_ashr_i32 s47, s46, 31
	v_lshrrev_b32_e32 v7, 4, v6
	v_lshlrev_b32_e32 v1, 6, v6
	v_xor_b32_e32 v0, v7, v6
	v_and_b32_e32 v8, 0x3c0, v1
	v_lshlrev_b32_e32 v1, 7, v6
	s_and_b32 s20, s55, 7
	s_bfe_u32 s61, s60, 0x30003
	s_lshl_b64 s[48:49], s[46:47], 19
	v_lshlrev_b32_e32 v0, 3, v0
	v_and_b32_e32 v1, 0xfffffc00, v1
	s_add_u32 s48, s3, s48
	v_and_or_b32 v0, v0, 56, v1
	s_addc_u32 s49, s54, s49
	s_lshl_b32 s21, s61, 19
	v_ashrrev_i32_e32 v1, 31, v0
	v_lshl_add_u32 v140, v6, 4, 0
	s_add_u32 s50, s34, s21
	v_lshlrev_b64 v[0:1], 1, v[0:1]
	v_readfirstlane_b32 s21, v140
	v_add_u32_e32 v9, 0x2000, v140
	v_lshl_add_u64 v[2:3], s[48:49], 0, v[0:1]
	s_mov_b32 m0, s21
	v_readfirstlane_b32 s21, v9
	v_add_u32_e32 v9, 0x4000, v140
	s_barrier
	global_load_lds_dwordx4 v[2:3], off
	v_lshl_add_u64 v[4:5], v[2:3], 0, s[6:7]
	s_mov_b32 m0, s21
	v_readfirstlane_b32 s21, v9
	global_load_lds_dwordx4 v[4:5], off
	v_lshl_add_u64 v[4:5], v[2:3], 0, s[8:9]
	s_mov_b32 m0, s21
	v_lshl_add_u64 v[2:3], v[2:3], 0, s[10:11]
	global_load_lds_dwordx4 v[4:5], off
	v_add_u32_e32 v4, 0x6000, v140
	s_addc_u32 s51, s35, 0
	v_readfirstlane_b32 s21, v4
	s_mov_b32 m0, s21
	v_add_u32_e32 v4, 0xa000, v140
	global_load_lds_dwordx4 v[2:3], off
	v_add_u32_e32 v2, 0x8000, v140
	v_lshl_add_u64 v[132:133], s[50:51], 0, v[0:1]
	v_readfirstlane_b32 s21, v2
	s_mov_b32 m0, s21
	v_readfirstlane_b32 s21, v4
	v_add_u32_e32 v4, 0xc000, v140
	global_load_lds_dwordx4 v[132:133], off
	v_lshl_add_u64 v[2:3], v[132:133], 0, s[6:7]
	s_mov_b32 m0, s21
	v_readfirstlane_b32 s21, v4
	v_add_u32_e32 v4, 0xe000, v140
	global_load_lds_dwordx4 v[2:3], off
	v_lshl_add_u64 v[2:3], v[132:133], 0, s[8:9]
	s_mov_b32 m0, s21
	v_readfirstlane_b32 s21, v4
	global_load_lds_dwordx4 v[2:3], off
	v_lshl_add_u64 v[2:3], v[132:133], 0, s[10:11]
	s_mov_b32 m0, s21
	v_ashrrev_i32_e32 v4, 6, v6
	global_load_lds_dwordx4 v[2:3], off
	v_lshrrev_b32_e32 v5, 30, v4
	v_add_u32_e32 v5, v4, v5
	s_or_b32 s48, s62, s20
	v_bfe_u32 v2, v6, 4, 2
	v_bfe_u32 v3, v6, 1, 3
	v_and_b32_e32 v6, 0x7fffc, v5
	s_ashr_i32 s49, s48, 31
	v_sub_u32_e32 v4, v4, v6
	s_lshl_b64 s[48:49], s[48:49], 19
	v_lshlrev_b32_e32 v142, 13, v4
	v_bitop3_b32 v4, v7, v3, 3 bitop3:0x6c
	v_bitop3_b32 v2, v2, v3, 4 bitop3:0x36
	s_add_u32 s48, s34, s48
	v_lshlrev_b32_e32 v5, 12, v5
	v_lshlrev_b32_e32 v4, 3, v4
	v_lshlrev_b32_e32 v2, 3, v2
	s_addc_u32 s49, s35, s49
	v_and_b32_e32 v141, 0xffffc000, v5
	v_lshl_add_u64 v[134:135], s[48:49], 0, v[0:1]
	s_mov_b64 s[48:49], 0
	v_lshlrev_b32_e32 v143, 1, v8
	v_lshlrev_b32_e32 v144, 1, v4
	v_lshlrev_b32_e32 v145, 1, v2
	s_mov_b32 s62, 0
	s_mov_b32 s47, 0
	v_mov_b32_e32 v40, 0
	v_mov_b32_e32 v41, v129
	v_mov_b32_e32 v42, v129
	v_mov_b32_e32 v43, v129
	v_mov_b32_e32 v48, 0
	v_mov_b32_e32 v49, v129
	v_mov_b32_e32 v50, v129
	v_mov_b32_e32 v51, v129
	v_mov_b32_e32 v0, 0
	v_mov_b32_e32 v1, v129
	v_mov_b32_e32 v2, v129
	v_mov_b32_e32 v3, v129
	v_mov_b32_e32 v4, 0
	v_mov_b32_e32 v5, v129
	v_mov_b32_e32 v6, v129
	v_mov_b32_e32 v7, v129
	v_mov_b32_e32 v8, 0
	v_mov_b32_e32 v9, v129
	v_mov_b32_e32 v10, v129
	v_mov_b32_e32 v11, v129
	v_mov_b32_e32 v12, 0
	v_mov_b32_e32 v13, v129
	v_mov_b32_e32 v14, v129
	v_mov_b32_e32 v15, v129
	v_mov_b32_e32 v16, 0
	v_mov_b32_e32 v17, v129
	v_mov_b32_e32 v18, v129
	v_mov_b32_e32 v19, v129
	v_mov_b32_e32 v20, 0
	v_mov_b32_e32 v21, v129
	v_mov_b32_e32 v22, v129
	v_mov_b32_e32 v23, v129
	v_mov_b32_e32 v24, 0
	v_mov_b32_e32 v25, v129
	v_mov_b32_e32 v26, v129
	v_mov_b32_e32 v27, v129
	v_mov_b32_e32 v28, 0
	v_mov_b32_e32 v29, v129
	v_mov_b32_e32 v30, v129
	v_mov_b32_e32 v31, v129
	v_mov_b32_e32 v32, 0
	v_mov_b32_e32 v33, v129
	v_mov_b32_e32 v34, v129
	v_mov_b32_e32 v35, v129
	v_mov_b32_e32 v36, 0
	v_mov_b32_e32 v37, v129
	v_mov_b32_e32 v38, v129
	v_mov_b32_e32 v39, v129
	v_mov_b32_e32 v44, 0
	v_mov_b32_e32 v45, v129
	v_mov_b32_e32 v46, v129
	v_mov_b32_e32 v47, v129
	v_mov_b32_e32 v52, 0
	v_mov_b32_e32 v53, v129
	v_mov_b32_e32 v54, v129
	v_mov_b32_e32 v55, v129
	v_mov_b32_e32 v56, 0
	v_mov_b32_e32 v57, v129
	v_mov_b32_e32 v58, v129
	v_mov_b32_e32 v59, v129
	v_mov_b32_e32 v60, 0
	v_mov_b32_e32 v61, v129
	v_mov_b32_e32 v62, v129
	v_mov_b32_e32 v63, v129
	v_mov_b32_e32 v64, 0
	v_mov_b32_e32 v65, v129
	v_mov_b32_e32 v66, v129
	v_mov_b32_e32 v67, v129
	v_mov_b32_e32 v68, 0
	v_mov_b32_e32 v69, v129
	v_mov_b32_e32 v70, v129
	v_mov_b32_e32 v71, v129
	v_mov_b32_e32 v72, 0
	v_mov_b32_e32 v73, v129
	v_mov_b32_e32 v74, v129
	v_mov_b32_e32 v75, v129
	v_mov_b32_e32 v76, 0
	v_mov_b32_e32 v77, v129
	v_mov_b32_e32 v78, v129
	v_mov_b32_e32 v79, v129
	v_mov_b32_e32 v80, 0
	v_mov_b32_e32 v81, v129
	v_mov_b32_e32 v82, v129
	v_mov_b32_e32 v83, v129
	v_mov_b32_e32 v84, 0
	v_mov_b32_e32 v85, v129
	v_mov_b32_e32 v86, v129
	v_mov_b32_e32 v87, v129
	v_mov_b32_e32 v88, 0
	v_mov_b32_e32 v89, v129
	v_mov_b32_e32 v90, v129
	v_mov_b32_e32 v91, v129
	v_mov_b32_e32 v92, 0
	v_mov_b32_e32 v93, v129
	v_mov_b32_e32 v94, v129
	v_mov_b32_e32 v95, v129
	v_mov_b32_e32 v96, 0
	v_mov_b32_e32 v97, v129
	v_mov_b32_e32 v98, v129
	v_mov_b32_e32 v99, v129
	v_mov_b32_e32 v100, 0
	v_mov_b32_e32 v101, v129
	v_mov_b32_e32 v102, v129
	v_mov_b32_e32 v103, v129
	v_mov_b32_e32 v104, 0
	v_mov_b32_e32 v105, v129
	v_mov_b32_e32 v106, v129
	v_mov_b32_e32 v107, v129
	v_mov_b32_e32 v108, 0
	v_mov_b32_e32 v109, v129
	v_mov_b32_e32 v110, v129
	v_mov_b32_e32 v111, v129
	v_mov_b32_e32 v112, 0
	v_mov_b32_e32 v113, v129
	v_mov_b32_e32 v114, v129
	v_mov_b32_e32 v115, v129
	v_mov_b32_e32 v116, 0
	v_mov_b32_e32 v117, v129
	v_mov_b32_e32 v118, v129
	v_mov_b32_e32 v119, v129
	v_mov_b32_e32 v120, 0
	v_mov_b32_e32 v121, v129
	v_mov_b32_e32 v122, v129
	v_mov_b32_e32 v123, v129
	v_mov_b32_e32 v124, 0
	v_mov_b32_e32 v125, v129
	v_mov_b32_e32 v126, v129
	v_mov_b32_e32 v127, v129
	s_waitcnt vmcnt(0) lgkmcnt(0)
	s_barrier
	v_add3_u32 v180, v141, v143, v144
	v_add3_u32 v215, v142, v143, v144
	v_add3_u32 v214, v141, v143, v145
	v_add3_u32 v216, v142, v143, v145
	v_readfirstlane_b32 s62, v140
	ds_read_b128 v[146:149], v180
	ds_read_b128 v[150:153], v180 offset:2048
	ds_read_b128 v[154:157], v180 offset:4096
	ds_read_b128 v[158:161], v180 offset:6144
	ds_read_b128 v[182:185], v215 offset:32768
	ds_read_b128 v[186:189], v215 offset:34816
	ds_read_b128 v[190:193], v215 offset:36864
	ds_read_b128 v[194:197], v215 offset:38912
	s_mov_b32 s47, 0
	s_mov_b64 s[48:49], s[34:35]
	v_subrev_u32_e32 v178, s34, v134
	v_subrev_u32_e32 v179, s34, v132
	s_add_u32 s62, s62, 0x10000
	s_mov_b32 m0, s62
	s_add_u32 s50, s48, s12
	s_addc_u32 s51, s49, s13
	global_load_lds_dwordx4 v178, s[50:51]
	s_add_u32 m0, s62, 0x2000
	s_add_u32 s50, s48, s14
	s_addc_u32 s51, s49, s15
	global_load_lds_dwordx4 v178, s[50:51]
	s_add_u32 m0, s62, 0x4000
	s_add_u32 s50, s48, s16
	s_addc_u32 s51, s49, s17
	global_load_lds_dwordx4 v178, s[50:51]
	s_add_u32 m0, s62, 0x6000
	s_add_u32 s50, s48, s18
	s_addc_u32 s51, s49, s19
	global_load_lds_dwordx4 v178, s[50:51]
	s_add_u32 m0, s62, 0x8000
	s_add_u32 s50, s48, s22
	s_addc_u32 s51, s49, s23
	global_load_lds_dwordx4 v179, s[50:51]
	s_add_u32 m0, s62, 0xa000
	s_add_u32 s50, s48, s36
	s_addc_u32 s51, s49, s37
	global_load_lds_dwordx4 v179, s[50:51]
	s_add_u32 m0, s62, 0xc000
	s_add_u32 s50, s48, s40
	s_addc_u32 s51, s49, s41
	global_load_lds_dwordx4 v179, s[50:51]
	s_add_u32 m0, s62, 0xe000
	s_add_u32 s50, s48, s42
	s_addc_u32 s51, s49, s43
	global_load_lds_dwordx4 v179, s[50:51]
	s_branch .Lg2_entry
.Lg2_top:
	s_waitcnt lgkmcnt(0)
	s_waitcnt vmcnt(0)
	s_barrier
	v_xor_b32_e32 v180, 0x10000, v180
	v_xor_b32_e32 v215, 0x10000, v215
	v_xor_b32_e32 v214, 0x10000, v214
	v_xor_b32_e32 v216, 0x10000, v216
	s_xor_b32 s62, s62, 0x10000
	ds_read_b128 v[146:149], v180
	ds_read_b128 v[150:153], v180 offset:2048
	ds_read_b128 v[154:157], v180 offset:4096
	ds_read_b128 v[158:161], v180 offset:6144
	ds_read_b128 v[182:185], v215 offset:32768
	ds_read_b128 v[186:189], v215 offset:34816
	ds_read_b128 v[190:193], v215 offset:36864
	ds_read_b128 v[194:197], v215 offset:38912
	v_mfma_f32_16x16x32_bf16 v[60:63], v[162:165], v[198:201], v[60:63]
	v_mfma_f32_16x16x32_bf16 v[56:59], v[162:165], v[202:205], v[56:59]
	s_mov_b32 m0, s62
	s_add_u32 s50, s48, s12
	s_addc_u32 s51, s49, s13
	global_load_lds_dwordx4 v178, s[50:51]
	v_mfma_f32_16x16x32_bf16 v[52:55], v[162:165], v[206:209], v[52:55]
	v_mfma_f32_16x16x32_bf16 v[44:47], v[162:165], v[210:213], v[44:47]
	s_add_u32 m0, s62, 0x2000
	s_add_u32 s50, s48, s14
	s_addc_u32 s51, s49, s15
	global_load_lds_dwordx4 v178, s[50:51]
	v_mfma_f32_16x16x32_bf16 v[36:39], v[166:169], v[198:201], v[36:39]
	v_mfma_f32_16x16x32_bf16 v[32:35], v[166:169], v[202:205], v[32:35]
	s_add_u32 m0, s62, 0x4000
	s_add_u32 s50, s48, s16
	s_addc_u32 s51, s49, s17
	global_load_lds_dwordx4 v178, s[50:51]
	v_mfma_f32_16x16x32_bf16 v[28:31], v[166:169], v[206:209], v[28:31]
	v_mfma_f32_16x16x32_bf16 v[24:27], v[166:169], v[210:213], v[24:27]
	s_add_u32 m0, s62, 0x6000
	s_add_u32 s50, s48, s18
	s_addc_u32 s51, s49, s19
	global_load_lds_dwordx4 v178, s[50:51]
	v_mfma_f32_16x16x32_bf16 v[20:23], v[170:173], v[198:201], v[20:23]
	v_mfma_f32_16x16x32_bf16 v[16:19], v[170:173], v[202:205], v[16:19]
	s_add_u32 m0, s62, 0x8000
	s_add_u32 s50, s48, s22
	s_addc_u32 s51, s49, s23
	global_load_lds_dwordx4 v179, s[50:51]
	v_mfma_f32_16x16x32_bf16 v[12:15], v[170:173], v[206:209], v[12:15]
	v_mfma_f32_16x16x32_bf16 v[8:11], v[170:173], v[210:213], v[8:11]
	s_add_u32 m0, s62, 0xa000
	s_add_u32 s50, s48, s36
	s_addc_u32 s51, s49, s37
	global_load_lds_dwordx4 v179, s[50:51]
	v_mfma_f32_16x16x32_bf16 v[4:7], v[174:177], v[198:201], v[4:7]
	v_mfma_f32_16x16x32_bf16 v[0:3], v[174:177], v[202:205], v[0:3]
	s_add_u32 m0, s62, 0xc000
	s_add_u32 s50, s48, s40
	s_addc_u32 s51, s49, s41
	global_load_lds_dwordx4 v179, s[50:51]
	v_mfma_f32_16x16x32_bf16 v[48:51], v[174:177], v[206:209], v[48:51]
	v_mfma_f32_16x16x32_bf16 v[40:43], v[174:177], v[210:213], v[40:43]
	s_add_u32 m0, s62, 0xe000
	s_add_u32 s50, s48, s42
	s_addc_u32 s51, s49, s43
	global_load_lds_dwordx4 v179, s[50:51]

.LBB0_660:
	s_ashr_i32 s96, s94, 3
	s_and_b32 s21, s94, 7
	s_and_b32 s70, s96, -8
	s_or_b32 s64, s70, s21
	s_lshl_b32 s20, s91, 11
	s_ashr_i32 s65, s64, 31
	v_mov_b32_e32 v6, v181
	s_and_b32 s97, s93, 7
	s_bfe_u32 s6, s91, 0x30008
	s_and_b32 s20, s20, 0x380000
	s_lshl_b64 s[66:67], s[64:65], 19
	s_add_u32 s66, s3, s66
	v_lshrrev_b32_e32 v7, 4, v6
	v_lshlrev_b32_e32 v1, 6, v6
	v_xor_b32_e32 v0, v7, v6
	v_and_b32_e32 v8, 0x3c0, v1
	v_lshlrev_b32_e32 v1, 7, v6
	s_addc_u32 s67, s72, s67
	s_lshl_b32 s21, s94, 5
	v_lshlrev_b32_e32 v0, 3, v0
	v_and_b32_e32 v1, 0xfffffc00, v1
	s_and_b32 s95, s21, 0x700
	v_and_or_b32 v0, v0, 56, v1
	s_lshl_b32 s21, s95, 11
	v_ashrrev_i32_e32 v1, 31, v0
	v_lshl_add_u32 v142, v6, 4, 0
	s_add_u32 s68, s73, s21
	v_lshlrev_b64 v[0:1], 1, v[0:1]
	v_readfirstlane_b32 s21, v142
	v_add_u32_e32 v9, 0x2000, v142
	v_lshl_add_u64 v[2:3], s[66:67], 0, v[0:1]
	s_mov_b32 m0, s21
	v_readfirstlane_b32 s21, v9
	v_add_u32_e32 v9, 0x4000, v142
	s_waitcnt vmcnt(63) expcnt(7) lgkmcnt(15)
	s_barrier
	global_load_lds_dwordx4 v[2:3], off
	v_lshl_add_u64 v[4:5], v[2:3], 0, s[8:9]
	s_mov_b32 m0, s21
	v_readfirstlane_b32 s21, v9
	global_load_lds_dwordx4 v[4:5], off
	v_lshl_add_u64 v[4:5], v[2:3], 0, s[10:11]
	s_mov_b32 m0, s21
	s_addc_u32 s69, s74, 0
	global_load_lds_dwordx4 v[4:5], off
	v_add_u32_e32 v4, 0x6000, v142
	v_lshl_add_u64 v[2:3], v[2:3], 0, s[12:13]
	v_readfirstlane_b32 s21, v4
	v_add_u32_e32 v4, 0x8000, v142
	s_mov_b32 m0, s21
	v_readfirstlane_b32 s21, v4
	v_add_u32_e32 v9, 0xa000, v142
	global_load_lds_dwordx4 v[2:3], off
	v_lshl_add_u64 v[2:3], s[68:69], 0, v[0:1]
	s_mov_b32 m0, s21
	v_readfirstlane_b32 s21, v9
	v_add_u32_e32 v9, 0xc000, v142
	global_load_lds_dwordx4 v[2:3], off
	v_lshl_add_u64 v[4:5], v[2:3], 0, s[8:9]
	s_mov_b32 m0, s21
	v_readfirstlane_b32 s21, v9
	global_load_lds_dwordx4 v[4:5], off
	v_lshl_add_u64 v[4:5], v[2:3], 0, s[10:11]
	s_mov_b32 m0, s21
	v_lshl_add_u64 v[2:3], v[2:3], 0, s[12:13]
	global_load_lds_dwordx4 v[4:5], off
	v_add_u32_e32 v4, 0xe000, v142
	s_or_b32 s66, s70, s97
	v_readfirstlane_b32 s21, v4
	s_mov_b32 m0, s21
	v_ashrrev_i32_e32 v4, 6, v6
	global_load_lds_dwordx4 v[2:3], off
	v_lshrrev_b32_e32 v5, 30, v4
	s_ashr_i32 s67, s66, 31
	v_add_u32_e32 v5, v4, v5
	s_lshl_b64 s[68:69], s[66:67], 19
	v_bfe_u32 v2, v6, 4, 2
	v_bfe_u32 v3, v6, 1, 3
	v_and_b32_e32 v6, 0x7fffc, v5
	s_add_u32 s68, s34, s68
	v_sub_u32_e32 v4, v4, v6
	s_addc_u32 s69, s35, s69
	v_lshlrev_b32_e32 v144, 13, v4
	v_bitop3_b32 v4, v7, v3, 3 bitop3:0x6c
	v_bitop3_b32 v2, v2, v3, 4 bitop3:0x36
	v_lshl_add_u64 v[138:139], s[68:69], 0, v[0:1]
	s_add_u32 s68, s34, s20
	v_lshlrev_b32_e32 v5, 12, v5
	v_lshlrev_b32_e32 v4, 3, v4
	v_lshlrev_b32_e32 v2, 3, v2
	s_addc_u32 s69, s35, 0
	v_and_b32_e32 v143, 0xffffc000, v5
	v_lshl_add_u64 v[140:141], s[68:69], 0, v[0:1]
	s_mov_b64 s[68:69], 0
	v_lshlrev_b32_e32 v145, 1, v8
	v_lshlrev_b32_e32 v174, 1, v4
	v_lshlrev_b32_e32 v175, 1, v2
	s_mov_b32 vcc_lo, 0
	s_mov_b32 s86, 0
	v_mov_b32_e32 v4, 0
	v_mov_b32_e32 v5, v131
	v_mov_b32_e32 v6, v131
	v_mov_b32_e32 v7, v131
	v_mov_b32_e32 v12, 0
	v_mov_b32_e32 v13, v131
	v_mov_b32_e32 v14, v131
	v_mov_b32_e32 v15, v131
	v_mov_b32_e32 v0, 0
	v_mov_b32_e32 v1, v131
	v_mov_b32_e32 v2, v131
	v_mov_b32_e32 v3, v131
	v_mov_b32_e32 v8, 0
	v_mov_b32_e32 v9, v131
	v_mov_b32_e32 v10, v131
	v_mov_b32_e32 v11, v131
	v_mov_b32_e32 v16, 0
	v_mov_b32_e32 v17, v131
	v_mov_b32_e32 v18, v131
	v_mov_b32_e32 v19, v131
	v_mov_b32_e32 v20, 0
	v_mov_b32_e32 v21, v131
	v_mov_b32_e32 v22, v131
	v_mov_b32_e32 v23, v131
	v_mov_b32_e32 v24, 0
	v_mov_b32_e32 v25, v131
	v_mov_b32_e32 v26, v131
	v_mov_b32_e32 v27, v131
	v_mov_b32_e32 v28, 0
	v_mov_b32_e32 v29, v131
	v_mov_b32_e32 v30, v131
	v_mov_b32_e32 v31, v131
	v_mov_b32_e32 v32, 0
	v_mov_b32_e32 v33, v131
	v_mov_b32_e32 v34, v131
	v_mov_b32_e32 v35, v131
	v_mov_b32_e32 v36, 0
	v_mov_b32_e32 v37, v131
	v_mov_b32_e32 v38, v131
	v_mov_b32_e32 v39, v131
	v_mov_b32_e32 v40, 0
	v_mov_b32_e32 v41, v131
	v_mov_b32_e32 v42, v131
	v_mov_b32_e32 v43, v131
	v_mov_b32_e32 v44, 0
	v_mov_b32_e32 v45, v131
	v_mov_b32_e32 v46, v131
	v_mov_b32_e32 v47, v131
	v_mov_b32_e32 v48, 0
	v_mov_b32_e32 v49, v131
	v_mov_b32_e32 v50, v131
	v_mov_b32_e32 v51, v131
	v_mov_b32_e32 v52, 0
	v_mov_b32_e32 v53, v131
	v_mov_b32_e32 v54, v131
	v_mov_b32_e32 v55, v131
	v_mov_b32_e32 v56, 0
	v_mov_b32_e32 v57, v131
	v_mov_b32_e32 v58, v131
	v_mov_b32_e32 v59, v131
	v_mov_b32_e32 v60, 0
	v_mov_b32_e32 v61, v131
	v_mov_b32_e32 v62, v131
	v_mov_b32_e32 v63, v131
	v_mov_b32_e32 v64, 0
	v_mov_b32_e32 v65, v131
	v_mov_b32_e32 v66, v131
	v_mov_b32_e32 v67, v131
	v_mov_b32_e32 v68, 0
	v_mov_b32_e32 v69, v131
	v_mov_b32_e32 v70, v131
	v_mov_b32_e32 v71, v131
	v_mov_b32_e32 v72, 0
	v_mov_b32_e32 v73, v131
	v_mov_b32_e32 v74, v131
	v_mov_b32_e32 v75, v131
	v_mov_b32_e32 v76, 0
	v_mov_b32_e32 v77, v131
	v_mov_b32_e32 v78, v131
	v_mov_b32_e32 v79, v131
	v_mov_b32_e32 v80, 0
	v_mov_b32_e32 v81, v131
	v_mov_b32_e32 v82, v131
	v_mov_b32_e32 v83, v131
	v_mov_b32_e32 v84, 0
	v_mov_b32_e32 v85, v131
	v_mov_b32_e32 v86, v131
	v_mov_b32_e32 v87, v131
	v_mov_b32_e32 v88, 0
	v_mov_b32_e32 v89, v131
	v_mov_b32_e32 v90, v131
	v_mov_b32_e32 v91, v131
	v_mov_b32_e32 v92, 0
	v_mov_b32_e32 v93, v131
	v_mov_b32_e32 v94, v131
	v_mov_b32_e32 v95, v131
	v_mov_b32_e32 v96, 0
	v_mov_b32_e32 v97, v131
	v_mov_b32_e32 v98, v131
	v_mov_b32_e32 v99, v131
	v_mov_b32_e32 v100, 0
	v_mov_b32_e32 v101, v131
	v_mov_b32_e32 v102, v131
	v_mov_b32_e32 v103, v131
	v_mov_b32_e32 v104, 0
	v_mov_b32_e32 v105, v131
	v_mov_b32_e32 v106, v131
	v_mov_b32_e32 v107, v131
	v_mov_b32_e32 v108, 0
	v_mov_b32_e32 v109, v131
	v_mov_b32_e32 v110, v131
	v_mov_b32_e32 v111, v131
	v_mov_b32_e32 v112, 0
	v_mov_b32_e32 v113, v131
	v_mov_b32_e32 v114, v131
	v_mov_b32_e32 v115, v131
	v_mov_b32_e32 v116, 0
	v_mov_b32_e32 v117, v131
	v_mov_b32_e32 v118, v131
	v_mov_b32_e32 v119, v131
	v_mov_b32_e32 v120, 0
	v_mov_b32_e32 v121, v131
	v_mov_b32_e32 v122, v131
	v_mov_b32_e32 v123, v131
	v_mov_b32_e32 v124, 0
	v_mov_b32_e32 v125, v131
	v_mov_b32_e32 v126, v131
	v_mov_b32_e32 v127, v131
	s_waitcnt vmcnt(0) lgkmcnt(0)
	s_barrier
	v_add3_u32 v180, v143, v145, v174
	v_add3_u32 v245, v144, v145, v174
	v_add3_u32 v244, v143, v145, v175
	v_add3_u32 v246, v144, v145, v175
	v_readfirstlane_b32 s87, v142
	ds_read_b128 v[176:179], v180
	ds_read_b128 v[182:185], v180 offset:2048
	ds_read_b128 v[186:189], v180 offset:4096
	ds_read_b128 v[190:193], v180 offset:6144
	ds_read_b128 v[210:213], v245 offset:32768
	ds_read_b128 v[214:217], v245 offset:34816
	ds_read_b128 v[218:221], v245 offset:36864
	ds_read_b128 v[222:225], v245 offset:38912
	s_mov_b32 s86, 0
	s_mov_b64 s[68:69], s[34:35]
	v_subrev_u32_e32 v242, s34, v138
	v_subrev_u32_e32 v243, s34, v140
	s_add_u32 s87, s87, 0x10000
	s_mov_b32 m0, s87
	s_add_u32 s70, s68, 0x4000080
	s_addc_u32 s71, s69, 0
	global_load_lds_dwordx4 v242, s[70:71]
	s_add_u32 m0, s87, 0x2000
	s_add_u32 s70, s68, 0x4020080
	s_addc_u32 s71, s69, 0
	global_load_lds_dwordx4 v242, s[70:71]
	s_add_u32 m0, s87, 0x4000
	s_add_u32 s70, s68, 0x4040080
	s_addc_u32 s71, s69, 0
	global_load_lds_dwordx4 v242, s[70:71]
	s_add_u32 m0, s87, 0x6000
	s_add_u32 s70, s68, s14
	s_addc_u32 s71, s69, s15
	global_load_lds_dwordx4 v242, s[70:71]
	s_add_u32 m0, s87, 0x8000
	s_add_u32 s70, s68, s16
	s_addc_u32 s71, s69, s17
	global_load_lds_dwordx4 v243, s[70:71]
	s_add_u32 m0, s87, 0xa000
	s_add_u32 s70, s68, s18
	s_addc_u32 s71, s69, s19
	global_load_lds_dwordx4 v243, s[70:71]
	s_add_u32 m0, s87, 0xc000
	s_add_u32 s70, s68, s22
	s_addc_u32 s71, s69, s23
	global_load_lds_dwordx4 v243, s[70:71]
	s_add_u32 m0, s87, 0xe000
	s_add_u32 s70, s68, s36
	s_addc_u32 s71, s69, s37
	global_load_lds_dwordx4 v243, s[70:71]
	s_branch .Lg5_entry
.Lg5_top:
	s_waitcnt lgkmcnt(0)
	s_waitcnt vmcnt(0)
	s_barrier
	v_xor_b32_e32 v180, 0x10000, v180
	v_xor_b32_e32 v245, 0x10000, v245
	v_xor_b32_e32 v244, 0x10000, v244
	v_xor_b32_e32 v246, 0x10000, v246
	s_xor_b32 s87, s87, 0x10000
	ds_read_b128 v[176:179], v180
	ds_read_b128 v[182:185], v180 offset:2048
	ds_read_b128 v[186:189], v180 offset:4096
	ds_read_b128 v[190:193], v180 offset:6144
	ds_read_b128 v[210:213], v245 offset:32768
	ds_read_b128 v[214:217], v245 offset:34816
	ds_read_b128 v[218:221], v245 offset:36864
	ds_read_b128 v[222:225], v245 offset:38912
	v_mfma_f32_16x16x32_bf16 v[60:63], v[194:197], v[226:229], v[60:63]
	v_mfma_f32_16x16x32_bf16 v[56:59], v[194:197], v[230:233], v[56:59]
	s_mov_b32 m0, s87
	s_add_u32 s70, s68, 0x4000080
	s_addc_u32 s71, s69, 0
	global_load_lds_dwordx4 v242, s[70:71]
	v_mfma_f32_16x16x32_bf16 v[52:55], v[194:197], v[234:237], v[52:55]
	v_mfma_f32_16x16x32_bf16 v[48:51], v[194:197], v[238:241], v[48:51]
	s_add_u32 m0, s87, 0x2000
	s_add_u32 s70, s68, 0x4020080
	s_addc_u32 s71, s69, 0
	global_load_lds_dwordx4 v242, s[70:71]
	v_mfma_f32_16x16x32_bf16 v[44:47], v[198:201], v[226:229], v[44:47]
	v_mfma_f32_16x16x32_bf16 v[40:43], v[198:201], v[230:233], v[40:43]
	s_add_u32 m0, s87, 0x4000
	s_add_u32 s70, s68, 0x4040080
	s_addc_u32 s71, s69, 0
	global_load_lds_dwordx4 v242, s[70:71]
	v_mfma_f32_16x16x32_bf16 v[36:39], v[198:201], v[234:237], v[36:39]
	v_mfma_f32_16x16x32_bf16 v[32:35], v[198:201], v[238:241], v[32:35]
	s_add_u32 m0, s87, 0x6000
	s_add_u32 s70, s68, s14
	s_addc_u32 s71, s69, s15
	global_load_lds_dwordx4 v242, s[70:71]
	v_mfma_f32_16x16x32_bf16 v[28:31], v[202:205], v[226:229], v[28:31]
	v_mfma_f32_16x16x32_bf16 v[24:27], v[202:205], v[230:233], v[24:27]
	s_add_u32 m0, s87, 0x8000
	s_add_u32 s70, s68, s16
	s_addc_u32 s71, s69, s17
	global_load_lds_dwordx4 v243, s[70:71]
	v_mfma_f32_16x16x32_bf16 v[20:23], v[202:205], v[234:237], v[20:23]
	v_mfma_f32_16x16x32_bf16 v[16:19], v[202:205], v[238:241], v[16:19]
	s_add_u32 m0, s87, 0xa000
	s_add_u32 s70, s68, s18
	s_addc_u32 s71, s69, s19
	global_load_lds_dwordx4 v243, s[70:71]
	v_mfma_f32_16x16x32_bf16 v[8:11], v[206:209], v[226:229], v[8:11]
	v_mfma_f32_16x16x32_bf16 v[0:3], v[206:209], v[230:233], v[0:3]
	s_add_u32 m0, s87, 0xc000
	s_add_u32 s70, s68, s22
	s_addc_u32 s71, s69, s23
	global_load_lds_dwordx4 v243, s[70:71]
	v_mfma_f32_16x16x32_bf16 v[12:15], v[206:209], v[234:237], v[12:15]
	v_mfma_f32_16x16x32_bf16 v[4:7], v[206:209], v[238:241], v[4:7]
	s_add_u32 m0, s87, 0xe000
	s_add_u32 s70, s68, s36
	s_addc_u32 s71, s69, s37
	global_load_lds_dwordx4 v243, s[70:71]

.LBB0_667:
	ds_read_b128 v[2:5], v0
	v_lshl_add_u64 v[6:7], v[138:139], 0, s[68:69]
	v_add_co_u32_e32 v8, vcc, 0x6000000, v6
	s_add_u32 s68, s68, 0x20000
	s_nop 0
	v_addc_co_u32_e32 v9, vcc, 0, v7, vcc
	s_waitcnt lgkmcnt(0)
	global_store_dwordx4 v[8:9], v[2:5], off sc1
	ds_read_b128 v[2:5], v0 offset:1152
	v_add_co_u32_e32 v8, vcc, 0x6008000, v6
	s_addc_u32 s69, s69, 0
	s_nop 0
	v_addc_co_u32_e32 v9, vcc, 0, v7, vcc
	s_waitcnt lgkmcnt(0)
	global_store_dwordx4 v[8:9], v[2:5], off sc1
	ds_read_b128 v[2:5], v0 offset:2304
	v_add_co_u32_e32 v8, vcc, 0x6010000, v6
	s_cmp_lg_u32 s68, 0x80000
	s_nop 0
	v_addc_co_u32_e32 v9, vcc, 0, v7, vcc
	s_waitcnt lgkmcnt(0)
	global_store_dwordx4 v[8:9], v[2:5], off sc1
	ds_read_b128 v[2:5], v0 offset:3456
	v_add_co_u32_e32 v6, vcc, 0x6018000, v6
	v_add_u32_e32 v0, 0x1200, v0
	s_nop 0
	v_addc_co_u32_e32 v7, vcc, 0, v7, vcc
	s_waitcnt lgkmcnt(0)
	global_store_dwordx4 v[6:7], v[2:5], off sc1
	s_cbranch_scc1 .LBB0_667
	v_mov_b32_e32 v6, v181
	s_waitcnt lgkmcnt(0)
	s_lshl_b32 s68, s6, 20
	v_lshrrev_b32_e32 v7, 4, v6
	v_lshlrev_b32_e32 v1, 6, v6
	v_xor_b32_e32 v0, v7, v6
	v_and_b32_e32 v8, 0x3c0, v1
	v_lshlrev_b32_e32 v1, 8, v6
	v_lshlrev_b32_e32 v0, 3, v0
	v_and_b32_e32 v1, 0xfffff800, v1
	s_lshl_b64 s[20:21], s[64:65], 20
	v_and_or_b32 v0, v0, 56, v1
	s_add_u32 s20, s75, s20
	v_ashrrev_i32_e32 v1, 31, v0
	s_addc_u32 s21, s88, s21
	v_lshlrev_b64 v[0:1], 1, v[0:1]
	v_lshl_add_u32 v174, v6, 4, 0
	v_lshl_add_u64 v[2:3], s[20:21], 0, v[0:1]
	v_readfirstlane_b32 s20, v174
	v_add_u32_e32 v9, 0x2000, v174
	s_mov_b32 m0, s20
	v_readfirstlane_b32 s20, v9
	v_add_u32_e32 v9, 0x4000, v174
	s_barrier
	global_load_lds_dwordx4 v[2:3], off
	v_lshl_add_u64 v[4:5], v[2:3], 0, s[10:11]
	s_mov_b32 m0, s20
	v_readfirstlane_b32 s20, v9
	global_load_lds_dwordx4 v[4:5], off
	v_lshl_add_u64 v[4:5], v[2:3], 0, s[40:41]
	s_mov_b32 m0, s20
	s_lshl_b32 s64, s95, 12
	global_load_lds_dwordx4 v[4:5], off
	v_add_u32_e32 v4, 0x6000, v174
	s_add_u32 s64, s89, s64
	v_readfirstlane_b32 s20, v4
	v_add_u32_e32 v4, 0x8000, v174
	s_addc_u32 s65, s90, 0
	v_lshl_add_u64 v[2:3], v[2:3], 0, s[42:43]
	s_mov_b32 m0, s20
	v_readfirstlane_b32 s20, v4
	v_add_u32_e32 v9, 0xa000, v174
	global_load_lds_dwordx4 v[2:3], off
	v_lshl_add_u64 v[2:3], s[64:65], 0, v[0:1]
	s_mov_b32 m0, s20
	v_readfirstlane_b32 s20, v9
	v_add_u32_e32 v9, 0xc000, v174
	global_load_lds_dwordx4 v[2:3], off
	v_lshl_add_u64 v[4:5], v[2:3], 0, s[10:11]
	s_mov_b32 m0, s20
	v_readfirstlane_b32 s20, v9
	global_load_lds_dwordx4 v[4:5], off
	v_lshl_add_u64 v[4:5], v[2:3], 0, s[40:41]
	s_mov_b32 m0, s20
	v_lshl_add_u64 v[2:3], v[2:3], 0, s[42:43]
	global_load_lds_dwordx4 v[4:5], off
	v_add_u32_e32 v4, 0xe000, v174
	s_mov_b32 s69, 0
	v_readfirstlane_b32 s20, v4
	s_mov_b32 m0, s20
	v_ashrrev_i32_e32 v4, 6, v6
	global_load_lds_dwordx4 v[2:3], off
	v_lshrrev_b32_e32 v5, 30, v4
	v_add_u32_e32 v5, v4, v5
	s_lshl_b64 s[20:21], s[66:67], 20
	v_bfe_u32 v2, v6, 4, 2
	v_bfe_u32 v3, v6, 1, 3
	v_and_b32_e32 v6, 0x7fffc, v5
	s_add_u32 s20, s34, s20
	v_sub_u32_e32 v4, v4, v6
	s_addc_u32 s21, s35, s21
	v_lshlrev_b32_e32 v5, 12, v5
	v_lshlrev_b32_e32 v176, 13, v4
	v_bitop3_b32 v4, v7, v3, 3 bitop3:0x6c
	v_bitop3_b32 v2, v2, v3, 4 bitop3:0x36
	v_lshl_add_u64 v[142:143], s[20:21], 0, v[0:1]
	s_add_u32 s20, s34, s68
	v_and_b32_e32 v175, 0xffffc000, v5
	v_lshlrev_b32_e32 v5, 3, v4
	v_lshlrev_b32_e32 v2, 3, v2
	s_addc_u32 s21, s35, 0
	v_mov_b32_e32 v4, 0
	v_lshl_add_u64 v[144:145], s[20:21], 0, v[0:1]
	s_mov_b64 s[64:65], 0
	v_lshlrev_b32_e32 v177, 1, v8
	v_lshlrev_b32_e32 v178, 1, v5
	v_lshlrev_b32_e32 v179, 1, v2
	s_mov_b32 s68, 0
	v_mov_b32_e32 v5, v4
	v_mov_b32_e32 v6, v4
	v_mov_b32_e32 v7, v4
	v_mov_b32_e32 v8, v4
	v_mov_b32_e32 v9, v4
	v_mov_b32_e32 v10, v4
	v_mov_b32_e32 v11, v4
	v_mov_b32_e32 v0, v4
	v_mov_b32_e32 v1, v4
	v_mov_b32_e32 v2, v4
	v_mov_b32_e32 v3, v4
	v_mov_b32_e32 v12, v4
	v_mov_b32_e32 v13, v4
	v_mov_b32_e32 v14, v4
	v_mov_b32_e32 v15, v4
	v_mov_b32_e32 v16, v4
	v_mov_b32_e32 v17, v4
	v_mov_b32_e32 v18, v4
	v_mov_b32_e32 v19, v4
	v_mov_b32_e32 v20, v4
	v_mov_b32_e32 v21, v4
	v_mov_b32_e32 v22, v4
	v_mov_b32_e32 v23, v4
	v_mov_b32_e32 v24, v4
	v_mov_b32_e32 v25, v4
	v_mov_b32_e32 v26, v4
	v_mov_b32_e32 v27, v4
	v_mov_b32_e32 v28, v4
	v_mov_b32_e32 v29, v4
	v_mov_b32_e32 v30, v4
	v_mov_b32_e32 v31, v4
	v_mov_b32_e32 v32, v4
	v_mov_b32_e32 v33, v4
	v_mov_b32_e32 v34, v4
	v_mov_b32_e32 v35, v4
	v_mov_b32_e32 v36, v4
	v_mov_b32_e32 v37, v4
	v_mov_b32_e32 v38, v4
	v_mov_b32_e32 v39, v4
	v_mov_b32_e32 v40, v4
	v_mov_b32_e32 v41, v4
	v_mov_b32_e32 v42, v4
	v_mov_b32_e32 v43, v4
	v_mov_b32_e32 v44, v4
	v_mov_b32_e32 v45, v4
	v_mov_b32_e32 v46, v4
	v_mov_b32_e32 v47, v4
	v_mov_b32_e32 v48, v4
	v_mov_b32_e32 v49, v4
	v_mov_b32_e32 v50, v4
	v_mov_b32_e32 v51, v4
	v_mov_b32_e32 v52, v4
	v_mov_b32_e32 v53, v4
	v_mov_b32_e32 v54, v4
	v_mov_b32_e32 v55, v4
	v_mov_b32_e32 v56, v4
	v_mov_b32_e32 v57, v4
	v_mov_b32_e32 v58, v4
	v_mov_b32_e32 v59, v4
	v_mov_b32_e32 v60, v4
	v_mov_b32_e32 v61, v4
	v_mov_b32_e32 v62, v4
	v_mov_b32_e32 v63, v4
	v_mov_b32_e32 v64, v4
	v_mov_b32_e32 v65, v4
	v_mov_b32_e32 v66, v4
	v_mov_b32_e32 v67, v4
	v_mov_b32_e32 v68, v4
	v_mov_b32_e32 v69, v4
	v_mov_b32_e32 v70, v4
	v_mov_b32_e32 v71, v4
	v_mov_b32_e32 v72, v4
	v_mov_b32_e32 v73, v4
	v_mov_b32_e32 v74, v4
	v_mov_b32_e32 v75, v4
	v_mov_b32_e32 v76, v4
	v_mov_b32_e32 v77, v4
	v_mov_b32_e32 v78, v4
	v_mov_b32_e32 v79, v4
	v_mov_b32_e32 v80, v4
	v_mov_b32_e32 v81, v4
	v_mov_b32_e32 v82, v4
	v_mov_b32_e32 v83, v4
	v_mov_b32_e32 v84, v4
	v_mov_b32_e32 v85, v4
	v_mov_b32_e32 v86, v4
	v_mov_b32_e32 v87, v4
	v_mov_b32_e32 v88, v4
	v_mov_b32_e32 v89, v4
	v_mov_b32_e32 v90, v4
	v_mov_b32_e32 v91, v4
	v_mov_b32_e32 v92, v4
	v_mov_b32_e32 v93, v4
	v_mov_b32_e32 v94, v4
	v_mov_b32_e32 v95, v4
	v_mov_b32_e32 v96, v4
	v_mov_b32_e32 v97, v4
	v_mov_b32_e32 v98, v4
	v_mov_b32_e32 v99, v4
	v_mov_b32_e32 v100, v4
	v_mov_b32_e32 v101, v4
	v_mov_b32_e32 v102, v4
	v_mov_b32_e32 v103, v4
	v_mov_b32_e32 v104, v4
	v_mov_b32_e32 v105, v4
	v_mov_b32_e32 v106, v4
	v_mov_b32_e32 v107, v4
	v_mov_b32_e32 v108, v4
	v_mov_b32_e32 v109, v4
	v_mov_b32_e32 v110, v4
	v_mov_b32_e32 v111, v4
	v_mov_b32_e32 v112, v4
	v_mov_b32_e32 v113, v4
	v_mov_b32_e32 v114, v4
	v_mov_b32_e32 v115, v4
	v_mov_b32_e32 v116, v4
	v_mov_b32_e32 v117, v4
	v_mov_b32_e32 v118, v4
	v_mov_b32_e32 v119, v4
	v_mov_b32_e32 v120, v4
	v_mov_b32_e32 v121, v4
	v_mov_b32_e32 v122, v4
	v_mov_b32_e32 v123, v4
	v_mov_b32_e32 v124, v4
	v_mov_b32_e32 v125, v4
	v_mov_b32_e32 v126, v4
	v_mov_b32_e32 v127, v4
	s_waitcnt vmcnt(0) lgkmcnt(0)
	s_barrier
	v_add3_u32 v180, v175, v177, v178
	v_add3_u32 v249, v176, v177, v178
	v_add3_u32 v248, v175, v177, v179
	v_add3_u32 v250, v176, v177, v179
	v_readfirstlane_b32 s69, v174
	ds_read_b128 v[182:185], v180
	ds_read_b128 v[186:189], v180 offset:2048
	ds_read_b128 v[190:193], v180 offset:4096
	ds_read_b128 v[194:197], v180 offset:6144
	ds_read_b128 v[214:217], v249 offset:32768
	ds_read_b128 v[218:221], v249 offset:34816
	ds_read_b128 v[222:225], v249 offset:36864
	ds_read_b128 v[226:229], v249 offset:38912
	s_mov_b32 s68, 0
	s_mov_b64 s[64:65], s[34:35]
	v_subrev_u32_e32 v246, s34, v142
	v_subrev_u32_e32 v247, s34, v144
	s_add_u32 s69, s69, 0x10000
	s_mov_b32 m0, s69
	s_add_u32 s66, s64, s44
	s_addc_u32 s67, s65, s45
	global_load_lds_dwordx4 v246, s[66:67]
	s_add_u32 m0, s69, 0x2000
	s_add_u32 s66, s64, s46
	s_addc_u32 s67, s65, s47
	global_load_lds_dwordx4 v246, s[66:67]
	s_add_u32 m0, s69, 0x4000
	s_add_u32 s66, s64, s48
	s_addc_u32 s67, s65, s49
	global_load_lds_dwordx4 v246, s[66:67]
	s_add_u32 m0, s69, 0x6000
	s_add_u32 s66, s64, s50
	s_addc_u32 s67, s65, s51
	global_load_lds_dwordx4 v246, s[66:67]
	s_add_u32 m0, s69, 0x8000
	s_add_u32 s66, s64, s52
	s_addc_u32 s67, s65, s53
	global_load_lds_dwordx4 v247, s[66:67]
	s_add_u32 m0, s69, 0xa000
	s_add_u32 s66, s64, s54
	s_addc_u32 s67, s65, s55
	global_load_lds_dwordx4 v247, s[66:67]
	s_add_u32 m0, s69, 0xc000
	s_add_u32 s66, s64, s60
	s_addc_u32 s67, s65, s61
	global_load_lds_dwordx4 v247, s[66:67]
	s_add_u32 m0, s69, 0xe000
	s_add_u32 s66, s64, s62
	s_addc_u32 s67, s65, s63
	global_load_lds_dwordx4 v247, s[66:67]
	s_branch .Lg6_entry
.Lg6_top:
	s_waitcnt lgkmcnt(0)
	s_waitcnt vmcnt(0)
	s_barrier
	v_xor_b32_e32 v180, 0x10000, v180
	v_xor_b32_e32 v249, 0x10000, v249
	v_xor_b32_e32 v248, 0x10000, v248
	v_xor_b32_e32 v250, 0x10000, v250
	s_xor_b32 s69, s69, 0x10000
	ds_read_b128 v[182:185], v180
	ds_read_b128 v[186:189], v180 offset:2048
	ds_read_b128 v[190:193], v180 offset:4096
	ds_read_b128 v[194:197], v180 offset:6144
	ds_read_b128 v[214:217], v249 offset:32768
	ds_read_b128 v[218:221], v249 offset:34816
	ds_read_b128 v[222:225], v249 offset:36864
	ds_read_b128 v[226:229], v249 offset:38912
	v_mfma_f32_16x16x32_bf16 v[60:63], v[198:201], v[230:233], v[60:63]
	v_mfma_f32_16x16x32_bf16 v[56:59], v[198:201], v[234:237], v[56:59]
	s_mov_b32 m0, s69
	s_add_u32 s66, s64, s44
	s_addc_u32 s67, s65, s45
	global_load_lds_dwordx4 v246, s[66:67]
	v_mfma_f32_16x16x32_bf16 v[52:55], v[198:201], v[238:241], v[52:55]
	v_mfma_f32_16x16x32_bf16 v[48:51], v[198:201], v[242:245], v[48:51]
	s_add_u32 m0, s69, 0x2000
	s_add_u32 s66, s64, s46
	s_addc_u32 s67, s65, s47
	global_load_lds_dwordx4 v246, s[66:67]
	v_mfma_f32_16x16x32_bf16 v[44:47], v[202:205], v[230:233], v[44:47]
	v_mfma_f32_16x16x32_bf16 v[40:43], v[202:205], v[234:237], v[40:43]
	s_add_u32 m0, s69, 0x4000
	s_add_u32 s66, s64, s48
	s_addc_u32 s67, s65, s49
	global_load_lds_dwordx4 v246, s[66:67]
	v_mfma_f32_16x16x32_bf16 v[36:39], v[202:205], v[238:241], v[36:39]
	v_mfma_f32_16x16x32_bf16 v[32:35], v[202:205], v[242:245], v[32:35]
	s_add_u32 m0, s69, 0x6000
	s_add_u32 s66, s64, s50
	s_addc_u32 s67, s65, s51
	global_load_lds_dwordx4 v246, s[66:67]
	v_mfma_f32_16x16x32_bf16 v[28:31], v[206:209], v[230:233], v[28:31]
	v_mfma_f32_16x16x32_bf16 v[24:27], v[206:209], v[234:237], v[24:27]
	s_add_u32 m0, s69, 0x8000
	s_add_u32 s66, s64, s52
	s_addc_u32 s67, s65, s53
	global_load_lds_dwordx4 v247, s[66:67]
	v_mfma_f32_16x16x32_bf16 v[20:23], v[206:209], v[238:241], v[20:23]
	v_mfma_f32_16x16x32_bf16 v[16:19], v[206:209], v[242:245], v[16:19]
	s_add_u32 m0, s69, 0xa000
	s_add_u32 s66, s64, s54
	s_addc_u32 s67, s65, s55
	global_load_lds_dwordx4 v247, s[66:67]
	v_mfma_f32_16x16x32_bf16 v[12:15], v[210:213], v[230:233], v[12:15]
	v_mfma_f32_16x16x32_bf16 v[0:3], v[210:213], v[234:237], v[0:3]
	s_add_u32 m0, s69, 0xc000
	s_add_u32 s66, s64, s60
	s_addc_u32 s67, s65, s61
	global_load_lds_dwordx4 v247, s[66:67]
	v_mfma_f32_16x16x32_bf16 v[8:11], v[210:213], v[238:241], v[8:11]
	v_mfma_f32_16x16x32_bf16 v[4:7], v[210:213], v[242:245], v[4:7]
	s_add_u32 m0, s69, 0xe000
	s_add_u32 s66, s64, s62
	s_addc_u32 s67, s65, s63
	global_load_lds_dwordx4 v247, s[66:67]

.LBB0_746:
	s_ashr_i32 s20, s60, 2
	v_mov_b32_e32 v6, v181
	s_and_b32 s6, s60, 7
	s_and_b32 s51, s20, -8
	s_or_b32 s46, s51, s6
	v_lshrrev_b32_e32 v7, 4, v6
	v_lshlrev_b32_e32 v1, 6, v6
	v_xor_b32_e32 v0, v7, v6
	v_and_b32_e32 v8, 0x3c0, v1
	v_lshlrev_b32_e32 v1, 8, v6
	s_ashr_i32 s47, s46, 31
	v_lshlrev_b32_e32 v0, 3, v0
	v_and_b32_e32 v1, 0xfffff800, v1
	s_and_b32 s50, s55, 7
	s_bfe_u32 s6, s60, 0x20003
	s_lshl_b64 s[20:21], s[46:47], 20
	v_and_or_b32 v0, v0, 56, v1
	s_add_u32 s20, s3, s20
	v_ashrrev_i32_e32 v1, 31, v0
	s_addc_u32 s21, s52, s21
	v_lshlrev_b64 v[0:1], 1, v[0:1]
	v_lshl_add_u32 v134, v6, 4, 0
	v_lshl_add_u64 v[2:3], s[20:21], 0, v[0:1]
	v_readfirstlane_b32 s20, v134
	v_add_u32_e32 v9, 0x2000, v134
	s_mov_b32 m0, s20
	v_readfirstlane_b32 s20, v9
	v_add_u32_e32 v9, 0x4000, v134
	s_waitcnt vmcnt(63) expcnt(7) lgkmcnt(15)
	s_barrier
	global_load_lds_dwordx4 v[2:3], off
	v_lshl_add_u64 v[4:5], v[2:3], 0, s[8:9]
	s_mov_b32 m0, s20
	v_readfirstlane_b32 s20, v9
	global_load_lds_dwordx4 v[4:5], off
	v_lshl_add_u64 v[4:5], v[2:3], 0, s[10:11]
	s_mov_b32 m0, s20
	s_lshl_b32 s47, s6, 20
	global_load_lds_dwordx4 v[4:5], off
	v_add_u32_e32 v4, 0x6000, v134
	s_add_u32 s48, s53, s47
	v_readfirstlane_b32 s20, v4
	v_add_u32_e32 v4, 0x8000, v134
	s_addc_u32 s49, s54, 0
	v_lshl_add_u64 v[2:3], v[2:3], 0, s[12:13]
	s_mov_b32 m0, s20
	v_readfirstlane_b32 s20, v4
	v_add_u32_e32 v9, 0xa000, v134
	global_load_lds_dwordx4 v[2:3], off
	v_lshl_add_u64 v[2:3], s[48:49], 0, v[0:1]
	s_mov_b32 m0, s20
	v_readfirstlane_b32 s20, v9
	v_add_u32_e32 v9, 0xc000, v134
	global_load_lds_dwordx4 v[2:3], off
	v_lshl_add_u64 v[4:5], v[2:3], 0, s[8:9]
	s_mov_b32 m0, s20
	v_readfirstlane_b32 s20, v9
	global_load_lds_dwordx4 v[4:5], off
	v_lshl_add_u64 v[4:5], v[2:3], 0, s[10:11]
	s_mov_b32 m0, s20
	v_lshl_add_u64 v[2:3], v[2:3], 0, s[12:13]
	global_load_lds_dwordx4 v[4:5], off
	v_add_u32_e32 v4, 0xe000, v134
	v_mov_b32_e32 v36, 0
	v_readfirstlane_b32 s20, v4
	s_mov_b32 m0, s20
	v_ashrrev_i32_e32 v4, 6, v6
	global_load_lds_dwordx4 v[2:3], off
	s_or_b32 s20, s51, s50
	v_lshrrev_b32_e32 v5, 30, v4
	s_ashr_i32 s21, s20, 31
	v_add_u32_e32 v5, v4, v5
	s_lshl_b64 s[20:21], s[20:21], 20
	v_bfe_u32 v2, v6, 4, 2
	v_bfe_u32 v3, v6, 1, 3
	v_and_b32_e32 v6, 0x7fffc, v5
	s_add_u32 s20, s34, s20
	v_sub_u32_e32 v4, v4, v6
	s_addc_u32 s21, s35, s21
	v_lshlrev_b32_e32 v136, 13, v4
	v_bitop3_b32 v4, v7, v3, 3 bitop3:0x6c
	v_bitop3_b32 v2, v2, v3, 4 bitop3:0x36
	v_lshl_add_u64 v[130:131], s[20:21], 0, v[0:1]
	s_add_u32 s20, s34, s47
	v_lshlrev_b32_e32 v5, 12, v5
	v_lshlrev_b32_e32 v4, 3, v4
	v_lshlrev_b32_e32 v2, 3, v2
	s_addc_u32 s21, s35, 0
	v_and_b32_e32 v135, 0xffffc000, v5
	v_lshl_add_u64 v[132:133], s[20:21], 0, v[0:1]
	s_mov_b64 s[48:49], 0
	v_lshlrev_b32_e32 v137, 1, v8
	v_lshlrev_b32_e32 v138, 1, v4
	v_lshlrev_b32_e32 v139, 1, v2
	s_mov_b32 s61, 0
	s_mov_b32 s47, 0
	v_mov_b32_e32 v37, v36
	v_mov_b32_e32 v38, v36
	v_mov_b32_e32 v39, v36
	v_mov_b32_e32 v40, v36
	v_mov_b32_e32 v41, v36
	v_mov_b32_e32 v42, v36
	v_mov_b32_e32 v43, v36
	v_mov_b32_e32 v0, v36
	v_mov_b32_e32 v1, v36
	v_mov_b32_e32 v2, v36
	v_mov_b32_e32 v3, v36
	v_mov_b32_e32 v4, v36
	v_mov_b32_e32 v5, v36
	v_mov_b32_e32 v6, v36
	v_mov_b32_e32 v7, v36
	v_mov_b32_e32 v8, v36
	v_mov_b32_e32 v9, v36
	v_mov_b32_e32 v10, v36
	v_mov_b32_e32 v11, v36
	v_mov_b32_e32 v12, v36
	v_mov_b32_e32 v13, v36
	v_mov_b32_e32 v14, v36
	v_mov_b32_e32 v15, v36
	v_mov_b32_e32 v16, v36
	v_mov_b32_e32 v17, v36
	v_mov_b32_e32 v18, v36
	v_mov_b32_e32 v19, v36
	v_mov_b32_e32 v20, v36
	v_mov_b32_e32 v21, v36
	v_mov_b32_e32 v22, v36
	v_mov_b32_e32 v23, v36
	v_mov_b32_e32 v24, v36
	v_mov_b32_e32 v25, v36
	v_mov_b32_e32 v26, v36
	v_mov_b32_e32 v27, v36
	v_mov_b32_e32 v28, v36
	v_mov_b32_e32 v29, v36
	v_mov_b32_e32 v30, v36
	v_mov_b32_e32 v31, v36
	v_mov_b32_e32 v32, v36
	v_mov_b32_e32 v33, v36
	v_mov_b32_e32 v34, v36
	v_mov_b32_e32 v35, v36
	v_mov_b32_e32 v44, v36
	v_mov_b32_e32 v45, v36
	v_mov_b32_e32 v46, v36
	v_mov_b32_e32 v47, v36
	v_mov_b32_e32 v48, v36
	v_mov_b32_e32 v49, v36
	v_mov_b32_e32 v50, v36
	v_mov_b32_e32 v51, v36
	v_mov_b32_e32 v52, v36
	v_mov_b32_e32 v53, v36
	v_mov_b32_e32 v54, v36
	v_mov_b32_e32 v55, v36
	v_mov_b32_e32 v56, v36
	v_mov_b32_e32 v57, v36
	v_mov_b32_e32 v58, v36
	v_mov_b32_e32 v59, v36
	v_mov_b32_e32 v60, v36
	v_mov_b32_e32 v61, v36
	v_mov_b32_e32 v62, v36
	v_mov_b32_e32 v63, v36
	v_mov_b32_e32 v64, v36
	v_mov_b32_e32 v65, v36
	v_mov_b32_e32 v66, v36
	v_mov_b32_e32 v67, v36
	v_mov_b32_e32 v68, v36
	v_mov_b32_e32 v69, v36
	v_mov_b32_e32 v70, v36
	v_mov_b32_e32 v71, v36
	v_mov_b32_e32 v72, v36
	v_mov_b32_e32 v73, v36
	v_mov_b32_e32 v74, v36
	v_mov_b32_e32 v75, v36
	v_mov_b32_e32 v76, v36
	v_mov_b32_e32 v77, v36
	v_mov_b32_e32 v78, v36
	v_mov_b32_e32 v79, v36
	v_mov_b32_e32 v80, v36
	v_mov_b32_e32 v81, v36
	v_mov_b32_e32 v82, v36
	v_mov_b32_e32 v83, v36
	v_mov_b32_e32 v84, v36
	v_mov_b32_e32 v85, v36
	v_mov_b32_e32 v86, v36
	v_mov_b32_e32 v87, v36
	v_mov_b32_e32 v88, v36
	v_mov_b32_e32 v89, v36
	v_mov_b32_e32 v90, v36
	v_mov_b32_e32 v91, v36
	v_mov_b32_e32 v92, v36
	v_mov_b32_e32 v93, v36
	v_mov_b32_e32 v94, v36
	v_mov_b32_e32 v95, v36
	v_mov_b32_e32 v96, v36
	v_mov_b32_e32 v97, v36
	v_mov_b32_e32 v98, v36
	v_mov_b32_e32 v99, v36
	v_mov_b32_e32 v100, v36
	v_mov_b32_e32 v101, v36
	v_mov_b32_e32 v102, v36
	v_mov_b32_e32 v103, v36
	v_mov_b32_e32 v104, v36
	v_mov_b32_e32 v105, v36
	v_mov_b32_e32 v106, v36
	v_mov_b32_e32 v107, v36
	v_mov_b32_e32 v108, v36
	v_mov_b32_e32 v109, v36
	v_mov_b32_e32 v110, v36
	v_mov_b32_e32 v111, v36
	v_mov_b32_e32 v112, v36
	v_mov_b32_e32 v113, v36
	v_mov_b32_e32 v114, v36
	v_mov_b32_e32 v115, v36
	v_mov_b32_e32 v116, v36
	v_mov_b32_e32 v117, v36
	v_mov_b32_e32 v118, v36
	v_mov_b32_e32 v119, v36
	v_mov_b32_e32 v120, v36
	v_mov_b32_e32 v121, v36
	v_mov_b32_e32 v122, v36
	v_mov_b32_e32 v123, v36
	v_mov_b32_e32 v124, v36
	v_mov_b32_e32 v125, v36
	v_mov_b32_e32 v126, v36
	v_mov_b32_e32 v127, v36
	s_waitcnt vmcnt(0) lgkmcnt(0)
	s_barrier
	v_add3_u32 v141, v135, v137, v138
	v_add3_u32 v210, v136, v137, v138
	v_add3_u32 v180, v135, v137, v139
	v_add3_u32 v211, v136, v137, v139
	v_readfirstlane_b32 s61, v134
	ds_read_b128 v[142:145], v141
	ds_read_b128 v[146:149], v141 offset:2048
	ds_read_b128 v[150:153], v141 offset:4096
	ds_read_b128 v[154:157], v141 offset:6144
	ds_read_b128 v[174:177], v210 offset:32768
	ds_read_b128 v[182:185], v210 offset:34816
	ds_read_b128 v[186:189], v210 offset:36864
	ds_read_b128 v[190:193], v210 offset:38912
	s_mov_b32 s47, 0
	s_mov_b64 s[48:49], s[34:35]
	v_subrev_u32_e32 v178, s34, v130
	v_subrev_u32_e32 v179, s34, v132
	s_add_u32 s61, s61, 0x10000
	s_mov_b32 m0, s61
	s_add_u32 s50, s48, s14
	s_addc_u32 s51, s49, s15
	global_load_lds_dwordx4 v178, s[50:51]
	s_add_u32 m0, s61, 0x2000
	s_add_u32 s50, s48, s16
	s_addc_u32 s51, s49, s17
	global_load_lds_dwordx4 v178, s[50:51]
	s_add_u32 m0, s61, 0x4000
	s_add_u32 s50, s48, s18
	s_addc_u32 s51, s49, s19
	global_load_lds_dwordx4 v178, s[50:51]
	s_add_u32 m0, s61, 0x6000
	s_add_u32 s50, s48, s22
	s_addc_u32 s51, s49, s23
	global_load_lds_dwordx4 v178, s[50:51]
	s_add_u32 m0, s61, 0x8000
	s_add_u32 s50, s48, s36
	s_addc_u32 s51, s49, s37
	global_load_lds_dwordx4 v179, s[50:51]
	s_add_u32 m0, s61, 0xa000
	s_add_u32 s50, s48, s40
	s_addc_u32 s51, s49, s41
	global_load_lds_dwordx4 v179, s[50:51]
	s_add_u32 m0, s61, 0xc000
	s_add_u32 s50, s48, s42
	s_addc_u32 s51, s49, s43
	global_load_lds_dwordx4 v179, s[50:51]
	s_add_u32 m0, s61, 0xe000
	s_add_u32 s50, s48, s44
	s_addc_u32 s51, s49, s45
	global_load_lds_dwordx4 v179, s[50:51]
	s_branch .Lg7_entry
.Lg7_top:
	s_waitcnt lgkmcnt(0)
	s_waitcnt vmcnt(0)
	s_barrier
	v_xor_b32_e32 v141, 0x10000, v141
	v_xor_b32_e32 v210, 0x10000, v210
	v_xor_b32_e32 v180, 0x10000, v180
	v_xor_b32_e32 v211, 0x10000, v211
	s_xor_b32 s61, s61, 0x10000
	ds_read_b128 v[142:145], v141
	ds_read_b128 v[146:149], v141 offset:2048
	ds_read_b128 v[150:153], v141 offset:4096
	ds_read_b128 v[154:157], v141 offset:6144
	ds_read_b128 v[174:177], v210 offset:32768
	ds_read_b128 v[182:185], v210 offset:34816
	ds_read_b128 v[186:189], v210 offset:36864
	ds_read_b128 v[190:193], v210 offset:38912
	v_mfma_f32_16x16x32_bf16 v[60:63], v[158:161], v[194:197], v[60:63]
	v_mfma_f32_16x16x32_bf16 v[56:59], v[158:161], v[198:201], v[56:59]
	s_mov_b32 m0, s61
	s_add_u32 s50, s48, s14
	s_addc_u32 s51, s49, s15
	global_load_lds_dwordx4 v178, s[50:51]
	v_mfma_f32_16x16x32_bf16 v[52:55], v[158:161], v[202:205], v[52:55]
	v_mfma_f32_16x16x32_bf16 v[48:51], v[158:161], v[206:209], v[48:51]
	s_add_u32 m0, s61, 0x2000
	s_add_u32 s50, s48, s16
	s_addc_u32 s51, s49, s17
	global_load_lds_dwordx4 v178, s[50:51]
	v_mfma_f32_16x16x32_bf16 v[44:47], v[162:165], v[194:197], v[44:47]
	v_mfma_f32_16x16x32_bf16 v[32:35], v[162:165], v[198:201], v[32:35]
	s_add_u32 m0, s61, 0x4000
	s_add_u32 s50, s48, s18
	s_addc_u32 s51, s49, s19
	global_load_lds_dwordx4 v178, s[50:51]
	v_mfma_f32_16x16x32_bf16 v[28:31], v[162:165], v[202:205], v[28:31]
	v_mfma_f32_16x16x32_bf16 v[24:27], v[162:165], v[206:209], v[24:27]
	s_add_u32 m0, s61, 0x6000
	s_add_u32 s50, s48, s22
	s_addc_u32 s51, s49, s23
	global_load_lds_dwordx4 v178, s[50:51]
	v_mfma_f32_16x16x32_bf16 v[20:23], v[166:169], v[194:197], v[20:23]
	v_mfma_f32_16x16x32_bf16 v[16:19], v[166:169], v[198:201], v[16:19]
	s_add_u32 m0, s61, 0x8000
	s_add_u32 s50, s48, s36
	s_addc_u32 s51, s49, s37
	global_load_lds_dwordx4 v179, s[50:51]
	v_mfma_f32_16x16x32_bf16 v[12:15], v[166:169], v[202:205], v[12:15]
	v_mfma_f32_16x16x32_bf16 v[8:11], v[166:169], v[206:209], v[8:11]
	s_add_u32 m0, s61, 0xa000
	s_add_u32 s50, s48, s40
	s_addc_u32 s51, s49, s41
	global_load_lds_dwordx4 v179, s[50:51]
	v_mfma_f32_16x16x32_bf16 v[4:7], v[170:173], v[194:197], v[4:7]
	v_mfma_f32_16x16x32_bf16 v[0:3], v[170:173], v[198:201], v[0:3]
	s_add_u32 m0, s61, 0xc000
	s_add_u32 s50, s48, s42
	s_addc_u32 s51, s49, s43
	global_load_lds_dwordx4 v179, s[50:51]
	v_mfma_f32_16x16x32_bf16 v[40:43], v[170:173], v[202:205], v[40:43]
	v_mfma_f32_16x16x32_bf16 v[36:39], v[170:173], v[206:209], v[36:39]
	s_add_u32 m0, s61, 0xe000
	s_add_u32 s50, s48, s44
	s_addc_u32 s51, s49, s45
	global_load_lds_dwordx4 v179, s[50:51]

.LBB0_933:
	s_mul_hi_i32 s21, s70, 0x2e8ba2e9
	s_lshr_b32 s56, s21, 31
	s_ashr_i32 s71, s21, 4
	s_add_i32 s71, s71, s56
	s_and_b32 s20, s70, 7
	s_lshl_b32 s62, s71, 3
	s_or_b32 s58, s62, s20
	s_ashr_i32 s20, s70, 3
	s_mul_hi_i32 s21, s20, 0x2e8ba2e9
	v_mov_b32_e32 v6, v181
	s_lshr_b32 s56, s21, 31
	s_ashr_i32 s21, s21, 1
	s_add_i32 s21, s21, s56
	v_lshrrev_b32_e32 v7, 4, v6
	v_lshlrev_b32_e32 v1, 6, v6
	v_xor_b32_e32 v0, v7, v6
	v_and_b32_e32 v8, 0x3c0, v1
	v_lshlrev_b32_e32 v1, 7, v6
	s_mul_i32 s21, s21, 11
	s_ashr_i32 s59, s58, 31
	v_lshlrev_b32_e32 v0, 3, v0
	v_and_b32_e32 v1, 0xfffffc00, v1
	s_and_b32 s64, s69, 7
	s_sub_i32 s56, s20, s21
	s_lshl_b64 s[20:21], s[58:59], 19
	v_and_or_b32 v0, v0, 56, v1
	s_add_u32 s20, s3, s20
	v_ashrrev_i32_e32 v1, 31, v0
	s_addc_u32 s21, s66, s21
	v_lshlrev_b64 v[0:1], 1, v[0:1]
	v_lshl_add_u32 v130, v6, 4, 0
	v_lshl_add_u64 v[2:3], s[20:21], 0, v[0:1]
	v_readfirstlane_b32 s20, v130
	v_add_u32_e32 v9, 0x2000, v130
	s_mov_b32 m0, s20
	v_readfirstlane_b32 s20, v9
	v_add_u32_e32 v9, 0x4000, v130
	s_waitcnt vmcnt(63) expcnt(7) lgkmcnt(15)
	s_barrier
	global_load_lds_dwordx4 v[2:3], off
	v_lshl_add_u64 v[4:5], v[2:3], 0, s[14:15]
	s_mov_b32 m0, s20
	v_readfirstlane_b32 s20, v9
	global_load_lds_dwordx4 v[4:5], off
	v_lshl_add_u64 v[4:5], v[2:3], 0, s[16:17]
	s_mov_b32 m0, s20
	s_ashr_i32 s57, s56, 31
	global_load_lds_dwordx4 v[4:5], off
	v_add_u32_e32 v4, 0x6000, v130
	s_lshl_b64 s[60:61], s[56:57], 19
	v_readfirstlane_b32 s20, v4
	v_lshl_add_u64 v[2:3], v[2:3], 0, s[18:19]
	s_mov_b32 m0, s20
	s_add_u32 s60, s34, s60
	global_load_lds_dwordx4 v[2:3], off
	v_add_u32_e32 v2, 0x8000, v130
	s_addc_u32 s61, s35, s61
	v_readfirstlane_b32 s20, v2
	v_add_u32_e32 v4, 0xa000, v130
	v_lshl_add_u64 v[140:141], s[60:61], 0, v[0:1]
	s_mov_b32 m0, s20
	v_readfirstlane_b32 s20, v4
	v_add_u32_e32 v4, 0xc000, v130
	global_load_lds_dwordx4 v[140:141], off
	v_lshl_add_u64 v[2:3], v[140:141], 0, s[14:15]
	s_mov_b32 m0, s20
	v_readfirstlane_b32 s20, v4
	v_add_u32_e32 v4, 0xe000, v130
	global_load_lds_dwordx4 v[2:3], off
	v_lshl_add_u64 v[2:3], v[140:141], 0, s[16:17]
	s_mov_b32 m0, s20
	v_readfirstlane_b32 s20, v4
	global_load_lds_dwordx4 v[2:3], off
	v_lshl_add_u64 v[2:3], v[140:141], 0, s[18:19]
	s_mov_b32 m0, s20
	v_ashrrev_i32_e32 v4, 6, v6
	global_load_lds_dwordx4 v[2:3], off
	v_lshrrev_b32_e32 v5, 30, v4
	v_add_u32_e32 v5, v4, v5
	s_or_b32 s20, s62, s64
	v_bfe_u32 v2, v6, 4, 2
	v_bfe_u32 v3, v6, 1, 3
	v_and_b32_e32 v6, 0x7fffc, v5
	s_ashr_i32 s21, s20, 31
	v_sub_u32_e32 v4, v4, v6
	s_lshl_b64 s[20:21], s[20:21], 19
	v_lshlrev_b32_e32 v150, 13, v4
	v_bitop3_b32 v4, v7, v3, 3 bitop3:0x6c
	v_bitop3_b32 v2, v2, v3, 4 bitop3:0x36
	s_add_u32 s20, s34, s20
	v_lshlrev_b32_e32 v5, 12, v5
	v_lshlrev_b32_e32 v4, 3, v4
	v_lshlrev_b32_e32 v2, 3, v2
	s_addc_u32 s21, s35, s21
	v_and_b32_e32 v149, 0xffffc000, v5
	v_lshl_add_u64 v[142:143], s[20:21], 0, v[0:1]
	s_mov_b64 s[60:61], 0
	v_lshlrev_b32_e32 v151, 1, v8
	v_lshlrev_b32_e32 v152, 1, v4
	v_lshlrev_b32_e32 v153, 1, v2
	s_mov_b32 s59, 0
	s_mov_b32 s57, 0
	v_mov_b32_e32 v40, 0
	v_mov_b32_e32 v41, v131
	v_mov_b32_e32 v42, v131
	v_mov_b32_e32 v43, v131
	v_mov_b32_e32 v48, 0
	v_mov_b32_e32 v49, v131
	v_mov_b32_e32 v50, v131
	v_mov_b32_e32 v51, v131
	v_mov_b32_e32 v0, 0
	v_mov_b32_e32 v1, v131
	v_mov_b32_e32 v2, v131
	v_mov_b32_e32 v3, v131
	v_mov_b32_e32 v4, 0
	v_mov_b32_e32 v5, v131
	v_mov_b32_e32 v6, v131
	v_mov_b32_e32 v7, v131
	v_mov_b32_e32 v8, 0
	v_mov_b32_e32 v9, v131
	v_mov_b32_e32 v10, v131
	v_mov_b32_e32 v11, v131
	v_mov_b32_e32 v12, 0
	v_mov_b32_e32 v13, v131
	v_mov_b32_e32 v14, v131
	v_mov_b32_e32 v15, v131
	v_mov_b32_e32 v16, 0
	v_mov_b32_e32 v17, v131
	v_mov_b32_e32 v18, v131
	v_mov_b32_e32 v19, v131
	v_mov_b32_e32 v20, 0
	v_mov_b32_e32 v21, v131
	v_mov_b32_e32 v22, v131
	v_mov_b32_e32 v23, v131
	v_mov_b32_e32 v24, 0
	v_mov_b32_e32 v25, v131
	v_mov_b32_e32 v26, v131
	v_mov_b32_e32 v27, v131
	v_mov_b32_e32 v28, 0
	v_mov_b32_e32 v29, v131
	v_mov_b32_e32 v30, v131
	v_mov_b32_e32 v31, v131
	v_mov_b32_e32 v32, 0
	v_mov_b32_e32 v33, v131
	v_mov_b32_e32 v34, v131
	v_mov_b32_e32 v35, v131
	v_mov_b32_e32 v36, 0
	v_mov_b32_e32 v37, v131
	v_mov_b32_e32 v38, v131
	v_mov_b32_e32 v39, v131
	v_mov_b32_e32 v44, 0
	v_mov_b32_e32 v45, v131
	v_mov_b32_e32 v46, v131
	v_mov_b32_e32 v47, v131
	v_mov_b32_e32 v52, 0
	v_mov_b32_e32 v53, v131
	v_mov_b32_e32 v54, v131
	v_mov_b32_e32 v55, v131
	v_mov_b32_e32 v56, 0
	v_mov_b32_e32 v57, v131
	v_mov_b32_e32 v58, v131
	v_mov_b32_e32 v59, v131
	v_mov_b32_e32 v60, 0
	v_mov_b32_e32 v61, v131
	v_mov_b32_e32 v62, v131
	v_mov_b32_e32 v63, v131
	v_mov_b32_e32 v64, 0
	v_mov_b32_e32 v65, v131
	v_mov_b32_e32 v66, v131
	v_mov_b32_e32 v67, v131
	v_mov_b32_e32 v68, 0
	v_mov_b32_e32 v69, v131
	v_mov_b32_e32 v70, v131
	v_mov_b32_e32 v71, v131
	v_mov_b32_e32 v72, 0
	v_mov_b32_e32 v73, v131
	v_mov_b32_e32 v74, v131
	v_mov_b32_e32 v75, v131
	v_mov_b32_e32 v76, 0
	v_mov_b32_e32 v77, v131
	v_mov_b32_e32 v78, v131
	v_mov_b32_e32 v79, v131
	v_mov_b32_e32 v80, 0
	v_mov_b32_e32 v81, v131
	v_mov_b32_e32 v82, v131
	v_mov_b32_e32 v83, v131
	v_mov_b32_e32 v84, 0
	v_mov_b32_e32 v85, v131
	v_mov_b32_e32 v86, v131
	v_mov_b32_e32 v87, v131
	v_mov_b32_e32 v88, 0
	v_mov_b32_e32 v89, v131
	v_mov_b32_e32 v90, v131
	v_mov_b32_e32 v91, v131
	v_mov_b32_e32 v92, 0
	v_mov_b32_e32 v93, v131
	v_mov_b32_e32 v94, v131
	v_mov_b32_e32 v95, v131
	v_mov_b32_e32 v96, 0
	v_mov_b32_e32 v97, v131
	v_mov_b32_e32 v98, v131
	v_mov_b32_e32 v99, v131
	v_mov_b32_e32 v100, 0
	v_mov_b32_e32 v101, v131
	v_mov_b32_e32 v102, v131
	v_mov_b32_e32 v103, v131
	v_mov_b32_e32 v104, 0
	v_mov_b32_e32 v105, v131
	v_mov_b32_e32 v106, v131
	v_mov_b32_e32 v107, v131
	v_mov_b32_e32 v108, 0
	v_mov_b32_e32 v109, v131
	v_mov_b32_e32 v110, v131
	v_mov_b32_e32 v111, v131
	v_mov_b32_e32 v112, 0
	v_mov_b32_e32 v113, v131
	v_mov_b32_e32 v114, v131
	v_mov_b32_e32 v115, v131
	v_mov_b32_e32 v116, 0
	v_mov_b32_e32 v117, v131
	v_mov_b32_e32 v118, v131
	v_mov_b32_e32 v119, v131
	v_mov_b32_e32 v120, 0
	v_mov_b32_e32 v121, v131
	v_mov_b32_e32 v122, v131
	v_mov_b32_e32 v123, v131
	v_mov_b32_e32 v124, 0
	v_mov_b32_e32 v125, v131
	v_mov_b32_e32 v126, v131
	v_mov_b32_e32 v127, v131
	s_waitcnt vmcnt(0) lgkmcnt(0)
	s_barrier
	v_add3_u32 v180, v149, v151, v152
	v_add3_u32 v223, v150, v151, v152
	v_add3_u32 v222, v149, v151, v153
	v_add3_u32 v224, v150, v151, v153
	v_readfirstlane_b32 s59, v130
	ds_read_b128 v[154:157], v180
	ds_read_b128 v[158:161], v180 offset:2048
	ds_read_b128 v[162:165], v180 offset:4096
	ds_read_b128 v[166:169], v180 offset:6144
	ds_read_b128 v[190:193], v223 offset:32768
	ds_read_b128 v[194:197], v223 offset:34816
	ds_read_b128 v[198:201], v223 offset:36864
	ds_read_b128 v[202:205], v223 offset:38912
	s_mov_b32 s57, 0
	s_mov_b64 s[60:61], s[34:35]
	v_subrev_u32_e32 v178, s34, v142
	v_subrev_u32_e32 v179, s34, v140
	s_add_u32 s59, s59, 0x10000
	s_mov_b32 m0, s59
	s_add_u32 s62, s60, s22
	s_addc_u32 s63, s61, s23
	global_load_lds_dwordx4 v178, s[62:63]
	s_add_u32 m0, s59, 0x2000
	s_add_u32 s62, s60, s36
	s_addc_u32 s63, s61, s37
	global_load_lds_dwordx4 v178, s[62:63]
	s_add_u32 m0, s59, 0x4000
	s_add_u32 s62, s60, s38
	s_addc_u32 s63, s61, s39
	global_load_lds_dwordx4 v178, s[62:63]
	s_add_u32 m0, s59, 0x6000
	s_add_u32 s62, s60, s40
	s_addc_u32 s63, s61, s41
	global_load_lds_dwordx4 v178, s[62:63]
	s_add_u32 m0, s59, 0x8000
	s_add_u32 s62, s60, s42
	s_addc_u32 s63, s61, s43
	global_load_lds_dwordx4 v179, s[62:63]
	s_add_u32 m0, s59, 0xa000
	s_add_u32 s62, s60, s44
	s_addc_u32 s63, s61, s45
	global_load_lds_dwordx4 v179, s[62:63]
	s_add_u32 m0, s59, 0xc000
	s_add_u32 s62, s60, s46
	s_addc_u32 s63, s61, s47
	global_load_lds_dwordx4 v179, s[62:63]
	s_add_u32 m0, s59, 0xe000
	s_add_u32 s62, s60, s48
	s_addc_u32 s63, s61, s49
	global_load_lds_dwordx4 v179, s[62:63]
	s_branch .Lg8_entry
.Lg8_top:
	s_waitcnt lgkmcnt(0)
	s_waitcnt vmcnt(0)
	s_barrier
	v_xor_b32_e32 v180, 0x10000, v180
	v_xor_b32_e32 v223, 0x10000, v223
	v_xor_b32_e32 v222, 0x10000, v222
	v_xor_b32_e32 v224, 0x10000, v224
	s_xor_b32 s59, s59, 0x10000
	ds_read_b128 v[154:157], v180
	ds_read_b128 v[158:161], v180 offset:2048
	ds_read_b128 v[162:165], v180 offset:4096
	ds_read_b128 v[166:169], v180 offset:6144
	ds_read_b128 v[190:193], v223 offset:32768
	ds_read_b128 v[194:197], v223 offset:34816
	ds_read_b128 v[198:201], v223 offset:36864
	ds_read_b128 v[202:205], v223 offset:38912
	v_mfma_f32_16x16x32_bf16 v[60:63], v[170:173], v[206:209], v[60:63]
	v_mfma_f32_16x16x32_bf16 v[56:59], v[170:173], v[210:213], v[56:59]
	s_mov_b32 m0, s59
	s_add_u32 s62, s60, s22
	s_addc_u32 s63, s61, s23
	global_load_lds_dwordx4 v178, s[62:63]
	v_mfma_f32_16x16x32_bf16 v[52:55], v[170:173], v[214:217], v[52:55]
	v_mfma_f32_16x16x32_bf16 v[44:47], v[170:173], v[218:221], v[44:47]
	s_add_u32 m0, s59, 0x2000
	s_add_u32 s62, s60, s36
	s_addc_u32 s63, s61, s37
	global_load_lds_dwordx4 v178, s[62:63]
	v_mfma_f32_16x16x32_bf16 v[36:39], v[174:177], v[206:209], v[36:39]
	v_mfma_f32_16x16x32_bf16 v[32:35], v[174:177], v[210:213], v[32:35]
	s_add_u32 m0, s59, 0x4000
	s_add_u32 s62, s60, s38
	s_addc_u32 s63, s61, s39
	global_load_lds_dwordx4 v178, s[62:63]
	v_mfma_f32_16x16x32_bf16 v[28:31], v[174:177], v[214:217], v[28:31]
	v_mfma_f32_16x16x32_bf16 v[24:27], v[174:177], v[218:221], v[24:27]
	s_add_u32 m0, s59, 0x6000
	s_add_u32 s62, s60, s40
	s_addc_u32 s63, s61, s41
	global_load_lds_dwordx4 v178, s[62:63]
	v_mfma_f32_16x16x32_bf16 v[20:23], v[182:185], v[206:209], v[20:23]
	v_mfma_f32_16x16x32_bf16 v[16:19], v[182:185], v[210:213], v[16:19]
	s_add_u32 m0, s59, 0x8000
	s_add_u32 s62, s60, s42
	s_addc_u32 s63, s61, s43
	global_load_lds_dwordx4 v179, s[62:63]
	v_mfma_f32_16x16x32_bf16 v[12:15], v[182:185], v[214:217], v[12:15]
	v_mfma_f32_16x16x32_bf16 v[8:11], v[182:185], v[218:221], v[8:11]
	s_add_u32 m0, s59, 0xa000
	s_add_u32 s62, s60, s44
	s_addc_u32 s63, s61, s45
	global_load_lds_dwordx4 v179, s[62:63]
	v_mfma_f32_16x16x32_bf16 v[4:7], v[186:189], v[206:209], v[4:7]
	v_mfma_f32_16x16x32_bf16 v[0:3], v[186:189], v[210:213], v[0:3]
	s_add_u32 m0, s59, 0xc000
	s_add_u32 s62, s60, s46
	s_addc_u32 s63, s61, s47
	global_load_lds_dwordx4 v179, s[62:63]
	v_mfma_f32_16x16x32_bf16 v[48:51], v[186:189], v[214:217], v[48:51]
	v_mfma_f32_16x16x32_bf16 v[40:43], v[186:189], v[218:221], v[40:43]
	s_add_u32 m0, s59, 0xe000
	s_add_u32 s62, s60, s48
	s_addc_u32 s63, s61, s49
	global_load_lds_dwordx4 v179, s[62:63]

.LBB0_1331:
	s_ashr_i32 s20, s58, 2
	v_mov_b32_e32 v6, v181
	s_and_b32 s4, s58, 7
	s_and_b32 s47, s20, -8
	s_or_b32 s42, s47, s4
	v_lshrrev_b32_e32 v7, 4, v6
	v_lshlrev_b32_e32 v1, 6, v6
	v_xor_b32_e32 v0, v7, v6
	v_and_b32_e32 v8, 0x3c0, v1
	v_lshlrev_b32_e32 v1, 8, v6
	s_ashr_i32 s43, s42, 31
	v_lshlrev_b32_e32 v0, 3, v0
	v_and_b32_e32 v1, 0xfffff800, v1
	s_and_b32 s46, s57, 7
	s_bfe_u32 s4, s58, 0x20003
	s_lshl_b64 s[20:21], s[42:43], 20
	v_and_or_b32 v0, v0, 56, v1
	s_add_u32 s20, s3, s20
	v_ashrrev_i32_e32 v1, 31, v0
	s_addc_u32 s21, s48, s21
	v_lshlrev_b64 v[0:1], 1, v[0:1]
	v_lshl_add_u32 v134, v6, 4, 0
	v_lshl_add_u64 v[2:3], s[20:21], 0, v[0:1]
	v_readfirstlane_b32 s20, v134
	v_add_u32_e32 v9, 0x2000, v134
	s_mov_b32 m0, s20
	v_readfirstlane_b32 s20, v9
	v_add_u32_e32 v9, 0x4000, v134
	s_waitcnt vmcnt(63) expcnt(7) lgkmcnt(15)
	s_barrier
	global_load_lds_dwordx4 v[2:3], off
	v_lshl_add_u64 v[4:5], v[2:3], 0, s[6:7]
	s_mov_b32 m0, s20
	v_readfirstlane_b32 s20, v9
	global_load_lds_dwordx4 v[4:5], off
	v_lshl_add_u64 v[4:5], v[2:3], 0, s[8:9]
	s_mov_b32 m0, s20
	s_lshl_b32 s43, s4, 20
	global_load_lds_dwordx4 v[4:5], off
	v_add_u32_e32 v4, 0x6000, v134
	s_add_u32 s44, s49, s43
	v_readfirstlane_b32 s20, v4
	v_add_u32_e32 v4, 0x8000, v134
	s_addc_u32 s45, s56, 0
	v_lshl_add_u64 v[2:3], v[2:3], 0, s[10:11]
	s_mov_b32 m0, s20
	v_readfirstlane_b32 s20, v4
	v_add_u32_e32 v9, 0xa000, v134
	global_load_lds_dwordx4 v[2:3], off
	v_lshl_add_u64 v[2:3], s[44:45], 0, v[0:1]
	s_mov_b32 m0, s20
	v_readfirstlane_b32 s20, v9
	v_add_u32_e32 v9, 0xc000, v134
	global_load_lds_dwordx4 v[2:3], off
	v_lshl_add_u64 v[4:5], v[2:3], 0, s[6:7]
	s_mov_b32 m0, s20
	v_readfirstlane_b32 s20, v9
	global_load_lds_dwordx4 v[4:5], off
	v_lshl_add_u64 v[4:5], v[2:3], 0, s[8:9]
	s_mov_b32 m0, s20
	v_lshl_add_u64 v[2:3], v[2:3], 0, s[10:11]
	global_load_lds_dwordx4 v[4:5], off
	v_add_u32_e32 v4, 0xe000, v134
	v_mov_b32_e32 v36, 0
	v_readfirstlane_b32 s20, v4
	s_mov_b32 m0, s20
	v_ashrrev_i32_e32 v4, 6, v6
	global_load_lds_dwordx4 v[2:3], off
	s_or_b32 s20, s47, s46
	v_lshrrev_b32_e32 v5, 30, v4
	s_ashr_i32 s21, s20, 31
	v_add_u32_e32 v5, v4, v5
	s_lshl_b64 s[20:21], s[20:21], 20
	v_bfe_u32 v2, v6, 4, 2
	v_bfe_u32 v3, v6, 1, 3
	v_and_b32_e32 v6, 0x7fffc, v5
	s_add_u32 s20, s34, s20
	v_sub_u32_e32 v4, v4, v6
	s_addc_u32 s21, s35, s21
	v_lshlrev_b32_e32 v136, 13, v4
	v_bitop3_b32 v4, v7, v3, 3 bitop3:0x6c
	v_bitop3_b32 v2, v2, v3, 4 bitop3:0x36
	v_lshl_add_u64 v[130:131], s[20:21], 0, v[0:1]
	s_add_u32 s20, s34, s43
	v_lshlrev_b32_e32 v5, 12, v5
	v_lshlrev_b32_e32 v4, 3, v4
	v_lshlrev_b32_e32 v2, 3, v2
	s_addc_u32 s21, s35, 0
	v_and_b32_e32 v135, 0xffffc000, v5
	v_lshl_add_u64 v[132:133], s[20:21], 0, v[0:1]
	s_mov_b64 s[44:45], 0
	v_lshlrev_b32_e32 v137, 1, v8
	v_lshlrev_b32_e32 v138, 1, v4
	v_lshlrev_b32_e32 v139, 1, v2
	s_mov_b32 s59, 0
	s_mov_b32 s43, 0
	v_mov_b32_e32 v37, v36
	v_mov_b32_e32 v38, v36
	v_mov_b32_e32 v39, v36
	v_mov_b32_e32 v40, v36
	v_mov_b32_e32 v41, v36
	v_mov_b32_e32 v42, v36
	v_mov_b32_e32 v43, v36
	v_mov_b32_e32 v0, v36
	v_mov_b32_e32 v1, v36
	v_mov_b32_e32 v2, v36
	v_mov_b32_e32 v3, v36
	v_mov_b32_e32 v4, v36
	v_mov_b32_e32 v5, v36
	v_mov_b32_e32 v6, v36
	v_mov_b32_e32 v7, v36
	v_mov_b32_e32 v8, v36
	v_mov_b32_e32 v9, v36
	v_mov_b32_e32 v10, v36
	v_mov_b32_e32 v11, v36
	v_mov_b32_e32 v12, v36
	v_mov_b32_e32 v13, v36
	v_mov_b32_e32 v14, v36
	v_mov_b32_e32 v15, v36
	v_mov_b32_e32 v16, v36
	v_mov_b32_e32 v17, v36
	v_mov_b32_e32 v18, v36
	v_mov_b32_e32 v19, v36
	v_mov_b32_e32 v20, v36
	v_mov_b32_e32 v21, v36
	v_mov_b32_e32 v22, v36
	v_mov_b32_e32 v23, v36
	v_mov_b32_e32 v24, v36
	v_mov_b32_e32 v25, v36
	v_mov_b32_e32 v26, v36
	v_mov_b32_e32 v27, v36
	v_mov_b32_e32 v28, v36
	v_mov_b32_e32 v29, v36
	v_mov_b32_e32 v30, v36
	v_mov_b32_e32 v31, v36
	v_mov_b32_e32 v32, v36
	v_mov_b32_e32 v33, v36
	v_mov_b32_e32 v34, v36
	v_mov_b32_e32 v35, v36
	v_mov_b32_e32 v44, v36
	v_mov_b32_e32 v45, v36
	v_mov_b32_e32 v46, v36
	v_mov_b32_e32 v47, v36
	v_mov_b32_e32 v48, v36
	v_mov_b32_e32 v49, v36
	v_mov_b32_e32 v50, v36
	v_mov_b32_e32 v51, v36
	v_mov_b32_e32 v52, v36
	v_mov_b32_e32 v53, v36
	v_mov_b32_e32 v54, v36
	v_mov_b32_e32 v55, v36
	v_mov_b32_e32 v56, v36
	v_mov_b32_e32 v57, v36
	v_mov_b32_e32 v58, v36
	v_mov_b32_e32 v59, v36
	v_mov_b32_e32 v60, v36
	v_mov_b32_e32 v61, v36
	v_mov_b32_e32 v62, v36
	v_mov_b32_e32 v63, v36
	v_mov_b32_e32 v64, v36
	v_mov_b32_e32 v65, v36
	v_mov_b32_e32 v66, v36
	v_mov_b32_e32 v67, v36
	v_mov_b32_e32 v68, v36
	v_mov_b32_e32 v69, v36
	v_mov_b32_e32 v70, v36
	v_mov_b32_e32 v71, v36
	v_mov_b32_e32 v72, v36
	v_mov_b32_e32 v73, v36
	v_mov_b32_e32 v74, v36
	v_mov_b32_e32 v75, v36
	v_mov_b32_e32 v76, v36
	v_mov_b32_e32 v77, v36
	v_mov_b32_e32 v78, v36
	v_mov_b32_e32 v79, v36
	v_mov_b32_e32 v80, v36
	v_mov_b32_e32 v81, v36
	v_mov_b32_e32 v82, v36
	v_mov_b32_e32 v83, v36
	v_mov_b32_e32 v84, v36
	v_mov_b32_e32 v85, v36
	v_mov_b32_e32 v86, v36
	v_mov_b32_e32 v87, v36
	v_mov_b32_e32 v88, v36
	v_mov_b32_e32 v89, v36
	v_mov_b32_e32 v90, v36
	v_mov_b32_e32 v91, v36
	v_mov_b32_e32 v92, v36
	v_mov_b32_e32 v93, v36
	v_mov_b32_e32 v94, v36
	v_mov_b32_e32 v95, v36
	v_mov_b32_e32 v96, v36
	v_mov_b32_e32 v97, v36
	v_mov_b32_e32 v98, v36
	v_mov_b32_e32 v99, v36
	v_mov_b32_e32 v100, v36
	v_mov_b32_e32 v101, v36
	v_mov_b32_e32 v102, v36
	v_mov_b32_e32 v103, v36
	v_mov_b32_e32 v104, v36
	v_mov_b32_e32 v105, v36
	v_mov_b32_e32 v106, v36
	v_mov_b32_e32 v107, v36
	v_mov_b32_e32 v108, v36
	v_mov_b32_e32 v109, v36
	v_mov_b32_e32 v110, v36
	v_mov_b32_e32 v111, v36
	v_mov_b32_e32 v112, v36
	v_mov_b32_e32 v113, v36
	v_mov_b32_e32 v114, v36
	v_mov_b32_e32 v115, v36
	v_mov_b32_e32 v116, v36
	v_mov_b32_e32 v117, v36
	v_mov_b32_e32 v118, v36
	v_mov_b32_e32 v119, v36
	v_mov_b32_e32 v120, v36
	v_mov_b32_e32 v121, v36
	v_mov_b32_e32 v122, v36
	v_mov_b32_e32 v123, v36
	v_mov_b32_e32 v124, v36
	v_mov_b32_e32 v125, v36
	v_mov_b32_e32 v126, v36
	v_mov_b32_e32 v127, v36
	s_waitcnt vmcnt(0) lgkmcnt(0)
	s_barrier
	v_add3_u32 v141, v135, v137, v138
	v_add3_u32 v210, v136, v137, v138
	v_add3_u32 v180, v135, v137, v139
	v_add3_u32 v211, v136, v137, v139
	v_readfirstlane_b32 s59, v134
	ds_read_b128 v[142:145], v141
	ds_read_b128 v[146:149], v141 offset:2048
	ds_read_b128 v[150:153], v141 offset:4096
	ds_read_b128 v[154:157], v141 offset:6144
	ds_read_b128 v[174:177], v210 offset:32768
	ds_read_b128 v[182:185], v210 offset:34816
	ds_read_b128 v[186:189], v210 offset:36864
	ds_read_b128 v[190:193], v210 offset:38912
	s_mov_b32 s43, 0
	s_mov_b64 s[44:45], s[34:35]
	v_subrev_u32_e32 v178, s34, v130
	v_subrev_u32_e32 v179, s34, v132
	s_add_u32 s59, s59, 0x10000
	s_mov_b32 m0, s59
	s_add_u32 s46, s44, s12
	s_addc_u32 s47, s45, s13
	global_load_lds_dwordx4 v178, s[46:47]
	s_add_u32 m0, s59, 0x2000
	s_add_u32 s46, s44, s14
	s_addc_u32 s47, s45, s15
	global_load_lds_dwordx4 v178, s[46:47]
	s_add_u32 m0, s59, 0x4000
	s_add_u32 s46, s44, s16
	s_addc_u32 s47, s45, s17
	global_load_lds_dwordx4 v178, s[46:47]
	s_add_u32 m0, s59, 0x6000
	s_add_u32 s46, s44, s18
	s_addc_u32 s47, s45, s19
	global_load_lds_dwordx4 v178, s[46:47]
	s_add_u32 m0, s59, 0x8000
	s_add_u32 s46, s44, s22
	s_addc_u32 s47, s45, s23
	global_load_lds_dwordx4 v179, s[46:47]
	s_add_u32 m0, s59, 0xa000
	s_add_u32 s46, s44, s36
	s_addc_u32 s47, s45, s37
	global_load_lds_dwordx4 v179, s[46:47]
	s_add_u32 m0, s59, 0xc000
	s_add_u32 s46, s44, s38
	s_addc_u32 s47, s45, s39
	global_load_lds_dwordx4 v179, s[46:47]
	s_add_u32 m0, s59, 0xe000
	s_add_u32 s46, s44, s40
	s_addc_u32 s47, s45, s41
	global_load_lds_dwordx4 v179, s[46:47]
	s_branch .Lg9_entry
.Lg9_top:
	s_waitcnt lgkmcnt(0)
	s_waitcnt vmcnt(0)
	s_barrier
	v_xor_b32_e32 v141, 0x10000, v141
	v_xor_b32_e32 v210, 0x10000, v210
	v_xor_b32_e32 v180, 0x10000, v180
	v_xor_b32_e32 v211, 0x10000, v211
	s_xor_b32 s59, s59, 0x10000
	ds_read_b128 v[142:145], v141
	ds_read_b128 v[146:149], v141 offset:2048
	ds_read_b128 v[150:153], v141 offset:4096
	ds_read_b128 v[154:157], v141 offset:6144
	ds_read_b128 v[174:177], v210 offset:32768
	ds_read_b128 v[182:185], v210 offset:34816
	ds_read_b128 v[186:189], v210 offset:36864
	ds_read_b128 v[190:193], v210 offset:38912
	v_mfma_f32_16x16x32_bf16 v[60:63], v[158:161], v[194:197], v[60:63]
	v_mfma_f32_16x16x32_bf16 v[56:59], v[158:161], v[198:201], v[56:59]
	s_mov_b32 m0, s59
	s_add_u32 s46, s44, s12
	s_addc_u32 s47, s45, s13
	global_load_lds_dwordx4 v178, s[46:47]
	v_mfma_f32_16x16x32_bf16 v[52:55], v[158:161], v[202:205], v[52:55]
	v_mfma_f32_16x16x32_bf16 v[48:51], v[158:161], v[206:209], v[48:51]
	s_add_u32 m0, s59, 0x2000
	s_add_u32 s46, s44, s14
	s_addc_u32 s47, s45, s15
	global_load_lds_dwordx4 v178, s[46:47]
	v_mfma_f32_16x16x32_bf16 v[44:47], v[162:165], v[194:197], v[44:47]
	v_mfma_f32_16x16x32_bf16 v[32:35], v[162:165], v[198:201], v[32:35]
	s_add_u32 m0, s59, 0x4000
	s_add_u32 s46, s44, s16
	s_addc_u32 s47, s45, s17
	global_load_lds_dwordx4 v178, s[46:47]
	v_mfma_f32_16x16x32_bf16 v[28:31], v[162:165], v[202:205], v[28:31]
	v_mfma_f32_16x16x32_bf16 v[24:27], v[162:165], v[206:209], v[24:27]
	s_add_u32 m0, s59, 0x6000
	s_add_u32 s46, s44, s18
	s_addc_u32 s47, s45, s19
	global_load_lds_dwordx4 v178, s[46:47]
	v_mfma_f32_16x16x32_bf16 v[20:23], v[166:169], v[194:197], v[20:23]
	v_mfma_f32_16x16x32_bf16 v[16:19], v[166:169], v[198:201], v[16:19]
	s_add_u32 m0, s59, 0x8000
	s_add_u32 s46, s44, s22
	s_addc_u32 s47, s45, s23
	global_load_lds_dwordx4 v179, s[46:47]
	v_mfma_f32_16x16x32_bf16 v[12:15], v[166:169], v[202:205], v[12:15]
	v_mfma_f32_16x16x32_bf16 v[8:11], v[166:169], v[206:209], v[8:11]
	s_add_u32 m0, s59, 0xa000
	s_add_u32 s46, s44, s36
	s_addc_u32 s47, s45, s37
	global_load_lds_dwordx4 v179, s[46:47]
	v_mfma_f32_16x16x32_bf16 v[4:7], v[170:173], v[194:197], v[4:7]
	v_mfma_f32_16x16x32_bf16 v[0:3], v[170:173], v[198:201], v[0:3]
	s_add_u32 m0, s59, 0xc000
	s_add_u32 s46, s44, s38
	s_addc_u32 s47, s45, s39
	global_load_lds_dwordx4 v179, s[46:47]
	v_mfma_f32_16x16x32_bf16 v[40:43], v[170:173], v[202:205], v[40:43]
	v_mfma_f32_16x16x32_bf16 v[36:39], v[170:173], v[206:209], v[36:39]
	s_add_u32 m0, s59, 0xe000
	s_add_u32 s46, s44, s40
	s_addc_u32 s47, s45, s41
	global_load_lds_dwordx4 v179, s[46:47]

.LBB0_1488:
	v_mov_b32_e32 v6, v181
	s_ashr_i32 s51, s50, 6
	v_lshrrev_b32_e32 v7, 4, v6
	v_lshlrev_b32_e32 v1, 6, v6
	v_xor_b32_e32 v0, v7, v6
	v_and_b32_e32 v8, 0x3c0, v1
	v_lshlrev_b32_e32 v1, 7, v6
	s_bfe_u32 s52, s50, 0x20006
	s_and_b32 s56, s49, 63
	s_and_b32 s53, s50, 63
	s_and_b32 s20, s51, -4
	v_lshlrev_b32_e32 v0, 3, v0
	v_and_b32_e32 v1, 0xfffffc00, v1
	s_lshl_b32 s46, s56, 19
	s_or_b32 s42, s20, s52
	s_lshl_b32 s20, s53, 19
	v_and_or_b32 v0, v0, 56, v1
	s_add_u32 s20, s3, s20
	v_ashrrev_i32_e32 v1, 31, v0
	s_addc_u32 s21, s48, 0
	v_lshlrev_b64 v[0:1], 1, v[0:1]
	v_lshl_add_u32 v129, v6, 4, 0
	v_lshl_add_u64 v[2:3], s[20:21], 0, v[0:1]
	v_readfirstlane_b32 s20, v129
	v_add_u32_e32 v9, 0x2000, v129
	s_mov_b32 m0, s20
	v_readfirstlane_b32 s20, v9
	v_add_u32_e32 v9, 0x4000, v129
	s_waitcnt vmcnt(63) expcnt(7) lgkmcnt(15)
	s_barrier
	global_load_lds_dwordx4 v[2:3], off
	v_lshl_add_u64 v[4:5], v[2:3], 0, s[8:9]
	s_mov_b32 m0, s20
	v_readfirstlane_b32 s20, v9
	global_load_lds_dwordx4 v[4:5], off
	v_lshl_add_u64 v[4:5], v[2:3], 0, s[10:11]
	s_mov_b32 m0, s20
	s_ashr_i32 s43, s42, 31
	global_load_lds_dwordx4 v[4:5], off
	v_add_u32_e32 v4, 0x6000, v129
	s_lshl_b64 s[44:45], s[42:43], 19
	v_readfirstlane_b32 s20, v4
	v_lshl_add_u64 v[2:3], v[2:3], 0, s[12:13]
	s_mov_b32 m0, s20
	s_add_u32 s44, s34, s44
	global_load_lds_dwordx4 v[2:3], off
	v_add_u32_e32 v2, 0x8000, v129
	s_addc_u32 s45, s35, s45
	v_readfirstlane_b32 s20, v2
	v_add_u32_e32 v4, 0xa000, v129
	v_lshl_add_u64 v[134:135], s[44:45], 0, v[0:1]
	s_mov_b32 m0, s20
	v_readfirstlane_b32 s20, v4
	v_add_u32_e32 v4, 0xc000, v129
	global_load_lds_dwordx4 v[134:135], off
	v_lshl_add_u64 v[2:3], v[134:135], 0, s[8:9]
	s_mov_b32 m0, s20
	v_readfirstlane_b32 s20, v4
	v_add_u32_e32 v4, 0xe000, v129
	global_load_lds_dwordx4 v[2:3], off
	v_lshl_add_u64 v[2:3], v[134:135], 0, s[10:11]
	s_mov_b32 m0, s20
	v_readfirstlane_b32 s20, v4
	global_load_lds_dwordx4 v[2:3], off
	v_lshl_add_u64 v[2:3], v[134:135], 0, s[12:13]
	s_mov_b32 m0, s20
	v_ashrrev_i32_e32 v4, 6, v6
	global_load_lds_dwordx4 v[2:3], off
	v_lshrrev_b32_e32 v5, 30, v4
	v_add_u32_e32 v5, v4, v5
	v_bfe_u32 v2, v6, 4, 2
	v_bfe_u32 v3, v6, 1, 3
	v_and_b32_e32 v6, 0x7fffc, v5
	v_sub_u32_e32 v4, v4, v6
	v_lshlrev_b32_e32 v139, 13, v4
	v_bitop3_b32 v4, v7, v3, 3 bitop3:0x6c
	v_bitop3_b32 v2, v2, v3, 4 bitop3:0x36
	s_add_u32 s20, s34, s46
	v_lshlrev_b32_e32 v5, 12, v5
	v_lshlrev_b32_e32 v4, 3, v4
	v_lshlrev_b32_e32 v2, 3, v2
	s_addc_u32 s21, s35, 0
	v_and_b32_e32 v138, 0xffffc000, v5
	v_lshl_add_u64 v[136:137], s[20:21], 0, v[0:1]
	s_mov_b64 s[44:45], 0
	s_waitcnt lgkmcnt(0)
	v_lshlrev_b32_e32 v140, 1, v8
	v_lshlrev_b32_e32 v141, 1, v4
	v_lshlrev_b32_e32 v142, 1, v2
	s_mov_b32 s57, 0
	s_mov_b32 s43, 0
	v_mov_b32_e32 v8, v128
	v_mov_b32_e32 v9, v128
	v_mov_b32_e32 v10, v128
	v_mov_b32_e32 v11, v128
	v_mov_b32_e32 v20, v128
	v_mov_b32_e32 v21, v128
	v_mov_b32_e32 v22, v128
	v_mov_b32_e32 v23, v128
	v_mov_b32_e32 v0, v128
	v_mov_b32_e32 v1, v128
	v_mov_b32_e32 v2, v128
	v_mov_b32_e32 v3, v128
	v_mov_b32_e32 v4, v128
	v_mov_b32_e32 v5, v128
	v_mov_b32_e32 v6, v128
	v_mov_b32_e32 v7, v128
	v_mov_b32_e32 v12, v128
	v_mov_b32_e32 v13, v128
	v_mov_b32_e32 v14, v128
	v_mov_b32_e32 v15, v128
	v_mov_b32_e32 v24, v128
	v_mov_b32_e32 v25, v128
	v_mov_b32_e32 v26, v128
	v_mov_b32_e32 v27, v128
	v_mov_b32_e32 v16, v128
	v_mov_b32_e32 v17, v128
	v_mov_b32_e32 v18, v128
	v_mov_b32_e32 v19, v128
	v_mov_b32_e32 v28, v128
	v_mov_b32_e32 v29, v128
	v_mov_b32_e32 v30, v128
	v_mov_b32_e32 v31, v128
	v_mov_b32_e32 v32, v128
	v_mov_b32_e32 v33, v128
	v_mov_b32_e32 v34, v128
	v_mov_b32_e32 v35, v128
	v_mov_b32_e32 v40, v128
	v_mov_b32_e32 v41, v128
	v_mov_b32_e32 v42, v128
	v_mov_b32_e32 v43, v128
	v_mov_b32_e32 v36, v128
	v_mov_b32_e32 v37, v128
	v_mov_b32_e32 v38, v128
	v_mov_b32_e32 v39, v128
	v_mov_b32_e32 v44, v128
	v_mov_b32_e32 v45, v128
	v_mov_b32_e32 v46, v128
	v_mov_b32_e32 v47, v128
	v_mov_b32_e32 v48, v128
	v_mov_b32_e32 v49, v128
	v_mov_b32_e32 v50, v128
	v_mov_b32_e32 v51, v128
	v_mov_b32_e32 v56, v128
	v_mov_b32_e32 v57, v128
	v_mov_b32_e32 v58, v128
	v_mov_b32_e32 v59, v128
	v_mov_b32_e32 v52, v128
	v_mov_b32_e32 v53, v128
	v_mov_b32_e32 v54, v128
	v_mov_b32_e32 v55, v128
	v_mov_b32_e32 v60, v128
	v_mov_b32_e32 v61, v128
	v_mov_b32_e32 v62, v128
	v_mov_b32_e32 v63, v128
	v_mov_b32_e32 v64, v128
	v_mov_b32_e32 v65, v128
	v_mov_b32_e32 v66, v128
	v_mov_b32_e32 v67, v128
	v_mov_b32_e32 v72, v128
	v_mov_b32_e32 v73, v128
	v_mov_b32_e32 v74, v128
	v_mov_b32_e32 v75, v128
	v_mov_b32_e32 v68, v128
	v_mov_b32_e32 v69, v128
	v_mov_b32_e32 v70, v128
	v_mov_b32_e32 v71, v128
	v_mov_b32_e32 v76, v128
	v_mov_b32_e32 v77, v128
	v_mov_b32_e32 v78, v128
	v_mov_b32_e32 v79, v128
	v_mov_b32_e32 v80, v128
	v_mov_b32_e32 v81, v128
	v_mov_b32_e32 v82, v128
	v_mov_b32_e32 v83, v128
	v_mov_b32_e32 v88, v128
	v_mov_b32_e32 v89, v128
	v_mov_b32_e32 v90, v128
	v_mov_b32_e32 v91, v128
	v_mov_b32_e32 v84, v128
	v_mov_b32_e32 v85, v128
	v_mov_b32_e32 v86, v128
	v_mov_b32_e32 v87, v128
	v_mov_b32_e32 v92, v128
	v_mov_b32_e32 v93, v128
	v_mov_b32_e32 v94, v128
	v_mov_b32_e32 v95, v128
	v_mov_b32_e32 v96, v128
	v_mov_b32_e32 v97, v128
	v_mov_b32_e32 v98, v128
	v_mov_b32_e32 v99, v128
	v_mov_b32_e32 v104, v128
	v_mov_b32_e32 v105, v128
	v_mov_b32_e32 v106, v128
	v_mov_b32_e32 v107, v128
	v_mov_b32_e32 v100, v128
	v_mov_b32_e32 v101, v128
	v_mov_b32_e32 v102, v128
	v_mov_b32_e32 v103, v128
	v_mov_b32_e32 v108, v128
	v_mov_b32_e32 v109, v128
	v_mov_b32_e32 v110, v128
	v_mov_b32_e32 v111, v128
	v_mov_b32_e32 v112, v128
	v_mov_b32_e32 v113, v128
	v_mov_b32_e32 v114, v128
	v_mov_b32_e32 v115, v128
	v_mov_b32_e32 v120, v128
	v_mov_b32_e32 v121, v128
	v_mov_b32_e32 v122, v128
	v_mov_b32_e32 v123, v128
	v_mov_b32_e32 v116, v128
	v_mov_b32_e32 v117, v128
	v_mov_b32_e32 v118, v128
	v_mov_b32_e32 v119, v128
	v_mov_b32_e32 v124, v128
	v_mov_b32_e32 v125, v128
	v_mov_b32_e32 v126, v128
	v_mov_b32_e32 v127, v128
	s_waitcnt vmcnt(0) lgkmcnt(0)
	s_barrier
	v_add3_u32 v143, v138, v140, v141
	v_add3_u32 v180, v139, v140, v141
	v_add3_u32 v155, v138, v140, v142
	v_add3_u32 v222, v139, v140, v142
	v_readfirstlane_b32 s57, v129
	ds_read_b128 v[156:159], v143
	ds_read_b128 v[160:163], v143 offset:2048
	ds_read_b128 v[164:167], v143 offset:4096
	ds_read_b128 v[168:171], v143 offset:6144
	ds_read_b128 v[190:193], v180 offset:32768
	ds_read_b128 v[194:197], v180 offset:34816
	ds_read_b128 v[198:201], v180 offset:36864
	ds_read_b128 v[202:205], v180 offset:38912
	s_mov_b32 s43, 0
	s_mov_b64 s[44:45], s[34:35]
	v_subrev_u32_e32 v144, s34, v136
	v_subrev_u32_e32 v145, s34, v134
	s_add_u32 s57, s57, 0x10000
	s_mov_b32 m0, s57
	s_add_u32 s46, s44, s14
	s_addc_u32 s47, s45, s15
	global_load_lds_dwordx4 v144, s[46:47]
	s_add_u32 m0, s57, 0x2000
	s_add_u32 s46, s44, s16
	s_addc_u32 s47, s45, s17
	global_load_lds_dwordx4 v144, s[46:47]
	s_add_u32 m0, s57, 0x4000
	s_add_u32 s46, s44, s18
	s_addc_u32 s47, s45, s19
	global_load_lds_dwordx4 v144, s[46:47]
	s_add_u32 m0, s57, 0x6000
	s_add_u32 s46, s44, s22
	s_addc_u32 s47, s45, s23
	global_load_lds_dwordx4 v144, s[46:47]
	s_add_u32 m0, s57, 0x8000
	s_add_u32 s46, s44, s30
	s_addc_u32 s47, s45, s31
	global_load_lds_dwordx4 v145, s[46:47]
	s_add_u32 m0, s57, 0xa000
	s_add_u32 s46, s44, s36
	s_addc_u32 s47, s45, s37
	global_load_lds_dwordx4 v145, s[46:47]
	s_add_u32 m0, s57, 0xc000
	s_add_u32 s46, s44, s38
	s_addc_u32 s47, s45, s39
	global_load_lds_dwordx4 v145, s[46:47]
	s_add_u32 m0, s57, 0xe000
	s_add_u32 s46, s44, s40
	s_addc_u32 s47, s45, s41
	global_load_lds_dwordx4 v145, s[46:47]
	s_branch .Lg10_entry
.Lg10_top:
	s_waitcnt lgkmcnt(0)
	s_waitcnt vmcnt(0)
	s_barrier
	v_xor_b32_e32 v143, 0x10000, v143
	v_xor_b32_e32 v180, 0x10000, v180
	v_xor_b32_e32 v155, 0x10000, v155
	v_xor_b32_e32 v222, 0x10000, v222
	s_xor_b32 s57, s57, 0x10000
	ds_read_b128 v[156:159], v143
	ds_read_b128 v[160:163], v143 offset:2048
	ds_read_b128 v[164:167], v143 offset:4096
	ds_read_b128 v[168:171], v143 offset:6144
	ds_read_b128 v[190:193], v180 offset:32768
	ds_read_b128 v[194:197], v180 offset:34816
	ds_read_b128 v[198:201], v180 offset:36864
	ds_read_b128 v[202:205], v180 offset:38912
	v_mfma_f32_16x16x32_bf16 v[60:63], v[172:175], v[206:209], v[60:63]
	v_mfma_f32_16x16x32_bf16 v[52:55], v[172:175], v[210:213], v[52:55]
	s_mov_b32 m0, s57
	s_add_u32 s46, s44, s14
	s_addc_u32 s47, s45, s15
	global_load_lds_dwordx4 v144, s[46:47]
	v_mfma_f32_16x16x32_bf16 v[56:59], v[172:175], v[214:217], v[56:59]
	v_mfma_f32_16x16x32_bf16 v[48:51], v[172:175], v[218:221], v[48:51]
	s_add_u32 m0, s57, 0x2000
	s_add_u32 s46, s44, s16
	s_addc_u32 s47, s45, s17
	global_load_lds_dwordx4 v144, s[46:47]
	v_mfma_f32_16x16x32_bf16 v[44:47], v[176:179], v[206:209], v[44:47]
	v_mfma_f32_16x16x32_bf16 v[36:39], v[176:179], v[210:213], v[36:39]
	s_add_u32 m0, s57, 0x4000
	s_add_u32 s46, s44, s18
	s_addc_u32 s47, s45, s19
	global_load_lds_dwordx4 v144, s[46:47]
	v_mfma_f32_16x16x32_bf16 v[40:43], v[176:179], v[214:217], v[40:43]
	v_mfma_f32_16x16x32_bf16 v[32:35], v[176:179], v[218:221], v[32:35]
	s_add_u32 m0, s57, 0x6000
	s_add_u32 s46, s44, s22
	s_addc_u32 s47, s45, s23
	global_load_lds_dwordx4 v144, s[46:47]
	v_mfma_f32_16x16x32_bf16 v[28:31], v[182:185], v[206:209], v[28:31]
	v_mfma_f32_16x16x32_bf16 v[16:19], v[182:185], v[210:213], v[16:19]
	s_add_u32 m0, s57, 0x8000
	s_add_u32 s46, s44, s30
	s_addc_u32 s47, s45, s31
	global_load_lds_dwordx4 v145, s[46:47]
	v_mfma_f32_16x16x32_bf16 v[24:27], v[182:185], v[214:217], v[24:27]
	v_mfma_f32_16x16x32_bf16 v[12:15], v[182:185], v[218:221], v[12:15]
	s_add_u32 m0, s57, 0xa000
	s_add_u32 s46, s44, s36
	s_addc_u32 s47, s45, s37
	global_load_lds_dwordx4 v145, s[46:47]
	v_mfma_f32_16x16x32_bf16 v[4:7], v[186:189], v[206:209], v[4:7]
	v_mfma_f32_16x16x32_bf16 v[0:3], v[186:189], v[210:213], v[0:3]
	s_add_u32 m0, s57, 0xc000
	s_add_u32 s46, s44, s38
	s_addc_u32 s47, s45, s39
	global_load_lds_dwordx4 v145, s[46:47]
	v_mfma_f32_16x16x32_bf16 v[20:23], v[186:189], v[214:217], v[20:23]
	v_mfma_f32_16x16x32_bf16 v[8:11], v[186:189], v[218:221], v[8:11]
	s_add_u32 m0, s57, 0xe000
	s_add_u32 s46, s44, s40
	s_addc_u32 s47, s45, s41
	global_load_lds_dwordx4 v145, s[46:47]

.LBB0_1494:
	v_lshl_add_u32 v136, s42, 2, v147
	s_lshl_b32 s46, s56, 8
	v_cmp_lt_i32_e32 vcc, 63, v136
	s_and_saveexec_b64 s[20:21], vcc
	s_xor_b64 s[42:43], exec, s[20:21]
	s_cbranch_execz .LBB0_1502
	v_subrev_u32_e32 v136, 64, v136
	v_add_u32_e32 v129, s46, v151
	v_lshlrev_b32_e32 v129, 8, v129
	v_lshl_add_u32 v129, v136, 3, v129
	v_lshl_add_u32 v164, s53, 1, v146
	v_ashrrev_i32_e32 v165, 31, v164
	v_lshlrev_b64 v[164:165], 19, v[164:165]
	v_lshl_add_u64 v[164:165], v[130:131], 0, v[164:165]
	v_lshl_or_b32 v166, v136, 6, v148
	v_mov_b32_e32 v167, 0
	v_lshlrev_b64 v[166:167], 8, v[166:167]
	v_lshl_add_u64 v[156:157], v[164:165], 0, v[166:167]
	s_mov_b64 s[44:45], 0x1000
	v_lshl_add_u64 v[158:159], v[156:157], 0, s[44:45]
	v_lshl_add_u64 v[160:161], v[158:159], 0, s[44:45]
	v_lshl_add_u64 v[162:163], v[160:161], 0, s[44:45]
	v_mov_b32_e32 v168, 0xc0135761
	v_mov_b32_e32 v169, 0xc0135761
	v_mov_b32_e32 v170, 0xbdd2d3e7
	v_mov_b32_e32 v171, 0xbdd2d3e7
	v_mov_b32_e32 v172, 0x3f800000
	v_mov_b32_e32 v173, 0x3f800000
	v_pk_mul_f32 v[174:175], v[124:125], v[124:125]
	v_pk_mul_f32 v[176:177], v[126:127], v[126:127]
	v_pk_fma_f32 v[174:175], v[174:175], v[170:171], v[168:169]
	v_pk_fma_f32 v[176:177], v[176:177], v[170:171], v[168:169]
	v_pk_mul_f32 v[174:175], v[124:125], v[174:175]
	v_pk_mul_f32 v[176:177], v[126:127], v[176:177]
	v_exp_f32_e32 v174, v174
	v_exp_f32_e32 v175, v175
	v_exp_f32_e32 v176, v176
	v_exp_f32_e32 v177, v177
	v_pk_add_f32 v[174:175], v[174:175], v[172:173]
	v_pk_add_f32 v[176:177], v[176:177], v[172:173]
	v_rcp_f32_e32 v174, v174
	v_rcp_f32_e32 v175, v175
	v_rcp_f32_e32 v176, v176
	v_rcp_f32_e32 v177, v177
	v_pk_mul_f32 v[174:175], v[124:125], v[174:175]
	v_pk_mul_f32 v[176:177], v[126:127], v[176:177]
	v_cvt_pk_bf16_f32 v178, v174, v175
	v_cvt_pk_bf16_f32 v179, v176, v177
	global_store_dwordx2 v[156:157], v[178:179], off
	ds_write_b16 v150, v178
	ds_write_b16_d16_hi v150, v178 offset:144
	ds_write_b16 v150, v179 offset:288
	ds_write_b16_d16_hi v150, v179 offset:432
	v_pk_mul_f32 v[174:175], v[116:117], v[116:117]
	v_pk_mul_f32 v[176:177], v[118:119], v[118:119]
	v_pk_fma_f32 v[174:175], v[174:175], v[170:171], v[168:169]
	v_pk_fma_f32 v[176:177], v[176:177], v[170:171], v[168:169]
	v_pk_mul_f32 v[174:175], v[116:117], v[174:175]
	v_pk_mul_f32 v[176:177], v[118:119], v[176:177]
	v_exp_f32_e32 v174, v174
	v_exp_f32_e32 v175, v175
	v_exp_f32_e32 v176, v176
	v_exp_f32_e32 v177, v177
	v_pk_add_f32 v[174:175], v[174:175], v[172:173]
	v_pk_add_f32 v[176:177], v[176:177], v[172:173]
	v_rcp_f32_e32 v174, v174
	v_rcp_f32_e32 v175, v175
	v_rcp_f32_e32 v176, v176
	v_rcp_f32_e32 v177, v177
	v_pk_mul_f32 v[174:175], v[116:117], v[174:175]
	v_pk_mul_f32 v[176:177], v[118:119], v[176:177]
	v_cvt_pk_bf16_f32 v182, v174, v175
	v_cvt_pk_bf16_f32 v183, v176, v177
	global_store_dwordx2 v[158:159], v[182:183], off
	ds_write_b16 v150, v182 offset:32
	ds_write_b16_d16_hi v150, v182 offset:176
	ds_write_b16 v150, v183 offset:320
	ds_write_b16_d16_hi v150, v183 offset:464
	v_pk_mul_f32 v[174:175], v[120:121], v[120:121]
	v_pk_mul_f32 v[176:177], v[122:123], v[122:123]
	v_pk_fma_f32 v[174:175], v[174:175], v[170:171], v[168:169]
	v_pk_fma_f32 v[176:177], v[176:177], v[170:171], v[168:169]
	v_pk_mul_f32 v[174:175], v[120:121], v[174:175]
	v_pk_mul_f32 v[176:177], v[122:123], v[176:177]
	v_exp_f32_e32 v174, v174
	v_exp_f32_e32 v175, v175
	v_exp_f32_e32 v176, v176
	v_exp_f32_e32 v177, v177
	v_pk_add_f32 v[174:175], v[174:175], v[172:173]
	v_pk_add_f32 v[176:177], v[176:177], v[172:173]
	v_rcp_f32_e32 v174, v174
	v_rcp_f32_e32 v175, v175
	v_rcp_f32_e32 v176, v176
	v_rcp_f32_e32 v177, v177
	v_pk_mul_f32 v[174:175], v[120:121], v[174:175]
	v_pk_mul_f32 v[176:177], v[122:123], v[176:177]
	v_cvt_pk_bf16_f32 v178, v174, v175
	v_cvt_pk_bf16_f32 v179, v176, v177
	global_store_dwordx2 v[160:161], v[178:179], off
	ds_write_b16 v150, v178 offset:64
	ds_write_b16_d16_hi v150, v178 offset:208
	ds_write_b16 v150, v179 offset:352
	ds_write_b16_d16_hi v150, v179 offset:496
	v_pk_mul_f32 v[174:175], v[112:113], v[112:113]
	v_pk_mul_f32 v[176:177], v[114:115], v[114:115]
	v_pk_fma_f32 v[174:175], v[174:175], v[170:171], v[168:169]
	v_pk_fma_f32 v[176:177], v[176:177], v[170:171], v[168:169]
	v_pk_mul_f32 v[174:175], v[112:113], v[174:175]
	v_pk_mul_f32 v[176:177], v[114:115], v[176:177]
	v_exp_f32_e32 v174, v174
	v_exp_f32_e32 v175, v175
	v_exp_f32_e32 v176, v176
	v_exp_f32_e32 v177, v177
	v_pk_add_f32 v[174:175], v[174:175], v[172:173]
	v_pk_add_f32 v[176:177], v[176:177], v[172:173]
	v_rcp_f32_e32 v174, v174
	v_rcp_f32_e32 v175, v175
	v_rcp_f32_e32 v176, v176
	v_rcp_f32_e32 v177, v177
	v_pk_mul_f32 v[174:175], v[112:113], v[174:175]
	v_pk_mul_f32 v[176:177], v[114:115], v[176:177]
	v_cvt_pk_bf16_f32 v182, v174, v175
	v_cvt_pk_bf16_f32 v183, v176, v177
	global_store_dwordx2 v[162:163], v[182:183], off
	ds_write_b16 v150, v182 offset:96
	ds_write_b16_d16_hi v150, v182 offset:240
	ds_write_b16 v150, v183 offset:384
	ds_write_b16_d16_hi v150, v183 offset:528
	v_pk_mul_f32 v[174:175], v[108:109], v[108:109]
	v_pk_mul_f32 v[176:177], v[110:111], v[110:111]
	v_pk_fma_f32 v[174:175], v[174:175], v[170:171], v[168:169]
	v_pk_fma_f32 v[176:177], v[176:177], v[170:171], v[168:169]
	v_pk_mul_f32 v[174:175], v[108:109], v[174:175]
	v_pk_mul_f32 v[176:177], v[110:111], v[176:177]
	v_exp_f32_e32 v174, v174
	v_exp_f32_e32 v175, v175
	v_exp_f32_e32 v176, v176
	v_exp_f32_e32 v177, v177
	v_pk_add_f32 v[174:175], v[174:175], v[172:173]
	v_pk_add_f32 v[176:177], v[176:177], v[172:173]
	v_rcp_f32_e32 v174, v174
	v_rcp_f32_e32 v175, v175
	v_rcp_f32_e32 v176, v176
	v_rcp_f32_e32 v177, v177
	v_pk_mul_f32 v[174:175], v[108:109], v[174:175]
	v_pk_mul_f32 v[176:177], v[110:111], v[176:177]
	v_cvt_pk_bf16_f32 v178, v174, v175
	v_cvt_pk_bf16_f32 v179, v176, v177
	global_store_dwordx2 v[156:157], v[178:179], off offset:32
	ds_write_b16 v150, v178 offset:2304
	ds_write_b16_d16_hi v150, v178 offset:2448
	ds_write_b16 v150, v179 offset:2592
	ds_write_b16_d16_hi v150, v179 offset:2736
	v_pk_mul_f32 v[174:175], v[100:101], v[100:101]
	v_pk_mul_f32 v[176:177], v[102:103], v[102:103]
	v_pk_fma_f32 v[174:175], v[174:175], v[170:171], v[168:169]
	v_pk_fma_f32 v[176:177], v[176:177], v[170:171], v[168:169]
	v_pk_mul_f32 v[174:175], v[100:101], v[174:175]
	v_pk_mul_f32 v[176:177], v[102:103], v[176:177]
	v_exp_f32_e32 v174, v174
	v_exp_f32_e32 v175, v175
	v_exp_f32_e32 v176, v176
	v_exp_f32_e32 v177, v177
	v_pk_add_f32 v[174:175], v[174:175], v[172:173]
	v_pk_add_f32 v[176:177], v[176:177], v[172:173]
	v_rcp_f32_e32 v174, v174
	v_rcp_f32_e32 v175, v175
	v_rcp_f32_e32 v176, v176
	v_rcp_f32_e32 v177, v177
	v_pk_mul_f32 v[174:175], v[100:101], v[174:175]
	v_pk_mul_f32 v[176:177], v[102:103], v[176:177]
	v_cvt_pk_bf16_f32 v182, v174, v175
	v_cvt_pk_bf16_f32 v183, v176, v177
	global_store_dwordx2 v[158:159], v[182:183], off offset:32
	ds_write_b16 v150, v182 offset:2336
	ds_write_b16_d16_hi v150, v182 offset:2480
	ds_write_b16 v150, v183 offset:2624
	ds_write_b16_d16_hi v150, v183 offset:2768
	v_pk_mul_f32 v[174:175], v[104:105], v[104:105]
	v_pk_mul_f32 v[176:177], v[106:107], v[106:107]
	v_pk_fma_f32 v[174:175], v[174:175], v[170:171], v[168:169]
	v_pk_fma_f32 v[176:177], v[176:177], v[170:171], v[168:169]
	v_pk_mul_f32 v[174:175], v[104:105], v[174:175]
	v_pk_mul_f32 v[176:177], v[106:107], v[176:177]
	v_exp_f32_e32 v174, v174
	v_exp_f32_e32 v175, v175
	v_exp_f32_e32 v176, v176
	v_exp_f32_e32 v177, v177
	v_pk_add_f32 v[174:175], v[174:175], v[172:173]
	v_pk_add_f32 v[176:177], v[176:177], v[172:173]
	v_rcp_f32_e32 v174, v174
	v_rcp_f32_e32 v175, v175
	v_rcp_f32_e32 v176, v176
	v_rcp_f32_e32 v177, v177
	v_pk_mul_f32 v[174:175], v[104:105], v[174:175]
	v_pk_mul_f32 v[176:177], v[106:107], v[176:177]
	v_cvt_pk_bf16_f32 v178, v174, v175
	v_cvt_pk_bf16_f32 v179, v176, v177
	global_store_dwordx2 v[160:161], v[178:179], off offset:32
	ds_write_b16 v150, v178 offset:2368
	ds_write_b16_d16_hi v150, v178 offset:2512
	ds_write_b16 v150, v179 offset:2656
	ds_write_b16_d16_hi v150, v179 offset:2800
	v_pk_mul_f32 v[174:175], v[96:97], v[96:97]
	v_pk_mul_f32 v[176:177], v[98:99], v[98:99]
	v_pk_fma_f32 v[174:175], v[174:175], v[170:171], v[168:169]
	v_pk_fma_f32 v[176:177], v[176:177], v[170:171], v[168:169]
	v_pk_mul_f32 v[174:175], v[96:97], v[174:175]
	v_pk_mul_f32 v[176:177], v[98:99], v[176:177]
	v_exp_f32_e32 v174, v174
	v_exp_f32_e32 v175, v175
	v_exp_f32_e32 v176, v176
	v_exp_f32_e32 v177, v177
	v_pk_add_f32 v[174:175], v[174:175], v[172:173]
	v_pk_add_f32 v[176:177], v[176:177], v[172:173]
	v_rcp_f32_e32 v174, v174
	v_rcp_f32_e32 v175, v175
	v_rcp_f32_e32 v176, v176
	v_rcp_f32_e32 v177, v177
	v_pk_mul_f32 v[174:175], v[96:97], v[174:175]
	v_pk_mul_f32 v[176:177], v[98:99], v[176:177]
	v_cvt_pk_bf16_f32 v182, v174, v175
	v_cvt_pk_bf16_f32 v183, v176, v177
	global_store_dwordx2 v[162:163], v[182:183], off offset:32
	ds_write_b16 v150, v182 offset:2400
	ds_write_b16_d16_hi v150, v182 offset:2544
	ds_write_b16 v150, v183 offset:2688
	ds_write_b16_d16_hi v150, v183 offset:2832
	v_pk_mul_f32 v[174:175], v[92:93], v[92:93]
	v_pk_mul_f32 v[176:177], v[94:95], v[94:95]
	v_pk_fma_f32 v[174:175], v[174:175], v[170:171], v[168:169]
	v_pk_fma_f32 v[176:177], v[176:177], v[170:171], v[168:169]
	v_pk_mul_f32 v[174:175], v[92:93], v[174:175]
	v_pk_mul_f32 v[176:177], v[94:95], v[176:177]
	v_exp_f32_e32 v174, v174
	v_exp_f32_e32 v175, v175
	v_exp_f32_e32 v176, v176
	v_exp_f32_e32 v177, v177
	v_pk_add_f32 v[174:175], v[174:175], v[172:173]
	v_pk_add_f32 v[176:177], v[176:177], v[172:173]
	v_rcp_f32_e32 v174, v174
	v_rcp_f32_e32 v175, v175
	v_rcp_f32_e32 v176, v176
	v_rcp_f32_e32 v177, v177
	v_pk_mul_f32 v[174:175], v[92:93], v[174:175]
	v_pk_mul_f32 v[176:177], v[94:95], v[176:177]
	v_cvt_pk_bf16_f32 v178, v174, v175
	v_cvt_pk_bf16_f32 v179, v176, v177
	global_store_dwordx2 v[156:157], v[178:179], off offset:64
	ds_write_b16 v150, v178 offset:4608
	ds_write_b16_d16_hi v150, v178 offset:4752
	ds_write_b16 v150, v179 offset:4896
	ds_write_b16_d16_hi v150, v179 offset:5040
	v_pk_mul_f32 v[174:175], v[84:85], v[84:85]
	v_pk_mul_f32 v[176:177], v[86:87], v[86:87]
	v_pk_fma_f32 v[174:175], v[174:175], v[170:171], v[168:169]
	v_pk_fma_f32 v[176:177], v[176:177], v[170:171], v[168:169]
	v_pk_mul_f32 v[174:175], v[84:85], v[174:175]
	v_pk_mul_f32 v[176:177], v[86:87], v[176:177]
	v_exp_f32_e32 v174, v174
	v_exp_f32_e32 v175, v175
	v_exp_f32_e32 v176, v176
	v_exp_f32_e32 v177, v177
	v_pk_add_f32 v[174:175], v[174:175], v[172:173]
	v_pk_add_f32 v[176:177], v[176:177], v[172:173]
	v_rcp_f32_e32 v174, v174
	v_rcp_f32_e32 v175, v175
	v_rcp_f32_e32 v176, v176
	v_rcp_f32_e32 v177, v177
	v_pk_mul_f32 v[174:175], v[84:85], v[174:175]
	v_pk_mul_f32 v[176:177], v[86:87], v[176:177]
	v_cvt_pk_bf16_f32 v182, v174, v175
	v_cvt_pk_bf16_f32 v183, v176, v177
	global_store_dwordx2 v[158:159], v[182:183], off offset:64
	ds_write_b16 v150, v182 offset:4640
	ds_write_b16_d16_hi v150, v182 offset:4784
	ds_write_b16 v150, v183 offset:4928
	ds_write_b16_d16_hi v150, v183 offset:5072
	v_pk_mul_f32 v[174:175], v[88:89], v[88:89]
	v_pk_mul_f32 v[176:177], v[90:91], v[90:91]
	v_pk_fma_f32 v[174:175], v[174:175], v[170:171], v[168:169]
	v_pk_fma_f32 v[176:177], v[176:177], v[170:171], v[168:169]
	v_pk_mul_f32 v[174:175], v[88:89], v[174:175]
	v_pk_mul_f32 v[176:177], v[90:91], v[176:177]
	v_exp_f32_e32 v174, v174
	v_exp_f32_e32 v175, v175
	v_exp_f32_e32 v176, v176
	v_exp_f32_e32 v177, v177
	v_pk_add_f32 v[174:175], v[174:175], v[172:173]
	v_pk_add_f32 v[176:177], v[176:177], v[172:173]
	v_rcp_f32_e32 v174, v174
	v_rcp_f32_e32 v175, v175
	v_rcp_f32_e32 v176, v176
	v_rcp_f32_e32 v177, v177
	v_pk_mul_f32 v[174:175], v[88:89], v[174:175]
	v_pk_mul_f32 v[176:177], v[90:91], v[176:177]
	v_cvt_pk_bf16_f32 v178, v174, v175
	v_cvt_pk_bf16_f32 v179, v176, v177
	global_store_dwordx2 v[160:161], v[178:179], off offset:64
	ds_write_b16 v150, v178 offset:4672
	ds_write_b16_d16_hi v150, v178 offset:4816
	ds_write_b16 v150, v179 offset:4960
	ds_write_b16_d16_hi v150, v179 offset:5104
	v_pk_mul_f32 v[174:175], v[80:81], v[80:81]
	v_pk_mul_f32 v[176:177], v[82:83], v[82:83]
	v_pk_fma_f32 v[174:175], v[174:175], v[170:171], v[168:169]
	v_pk_fma_f32 v[176:177], v[176:177], v[170:171], v[168:169]
	v_pk_mul_f32 v[174:175], v[80:81], v[174:175]
	v_pk_mul_f32 v[176:177], v[82:83], v[176:177]
	v_exp_f32_e32 v174, v174
	v_exp_f32_e32 v175, v175
	v_exp_f32_e32 v176, v176
	v_exp_f32_e32 v177, v177
	v_pk_add_f32 v[174:175], v[174:175], v[172:173]
	v_pk_add_f32 v[176:177], v[176:177], v[172:173]
	v_rcp_f32_e32 v174, v174
	v_rcp_f32_e32 v175, v175
	v_rcp_f32_e32 v176, v176
	v_rcp_f32_e32 v177, v177
	v_pk_mul_f32 v[174:175], v[80:81], v[174:175]
	v_pk_mul_f32 v[176:177], v[82:83], v[176:177]
	v_cvt_pk_bf16_f32 v182, v174, v175
	v_cvt_pk_bf16_f32 v183, v176, v177
	global_store_dwordx2 v[162:163], v[182:183], off offset:64
	ds_write_b16 v150, v182 offset:4704
	ds_write_b16_d16_hi v150, v182 offset:4848
	ds_write_b16 v150, v183 offset:4992
	ds_write_b16_d16_hi v150, v183 offset:5136
	v_pk_mul_f32 v[174:175], v[76:77], v[76:77]
	v_pk_mul_f32 v[176:177], v[78:79], v[78:79]
	v_pk_fma_f32 v[174:175], v[174:175], v[170:171], v[168:169]
	v_pk_fma_f32 v[176:177], v[176:177], v[170:171], v[168:169]
	v_pk_mul_f32 v[174:175], v[76:77], v[174:175]
	v_pk_mul_f32 v[176:177], v[78:79], v[176:177]
	v_exp_f32_e32 v174, v174
	v_exp_f32_e32 v175, v175
	v_exp_f32_e32 v176, v176
	v_exp_f32_e32 v177, v177
	v_pk_add_f32 v[174:175], v[174:175], v[172:173]
	v_pk_add_f32 v[176:177], v[176:177], v[172:173]
	v_rcp_f32_e32 v174, v174
	v_rcp_f32_e32 v175, v175
	v_rcp_f32_e32 v176, v176
	v_rcp_f32_e32 v177, v177
	v_pk_mul_f32 v[174:175], v[76:77], v[174:175]
	v_pk_mul_f32 v[176:177], v[78:79], v[176:177]
	v_cvt_pk_bf16_f32 v178, v174, v175
	v_cvt_pk_bf16_f32 v179, v176, v177
	global_store_dwordx2 v[156:157], v[178:179], off offset:96
	ds_write_b16 v150, v178 offset:6912
	ds_write_b16_d16_hi v150, v178 offset:7056
	ds_write_b16 v150, v179 offset:7200
	ds_write_b16_d16_hi v150, v179 offset:7344
	v_pk_mul_f32 v[174:175], v[68:69], v[68:69]
	v_pk_mul_f32 v[176:177], v[70:71], v[70:71]
	v_pk_fma_f32 v[174:175], v[174:175], v[170:171], v[168:169]
	v_pk_fma_f32 v[176:177], v[176:177], v[170:171], v[168:169]
	v_pk_mul_f32 v[174:175], v[68:69], v[174:175]
	v_pk_mul_f32 v[176:177], v[70:71], v[176:177]
	v_exp_f32_e32 v174, v174
	v_exp_f32_e32 v175, v175
	v_exp_f32_e32 v176, v176
	v_exp_f32_e32 v177, v177
	v_pk_add_f32 v[174:175], v[174:175], v[172:173]
	v_pk_add_f32 v[176:177], v[176:177], v[172:173]
	v_rcp_f32_e32 v174, v174
	v_rcp_f32_e32 v175, v175
	v_rcp_f32_e32 v176, v176
	v_rcp_f32_e32 v177, v177
	v_pk_mul_f32 v[174:175], v[68:69], v[174:175]
	v_pk_mul_f32 v[176:177], v[70:71], v[176:177]
	v_cvt_pk_bf16_f32 v182, v174, v175
	v_cvt_pk_bf16_f32 v183, v176, v177
	global_store_dwordx2 v[158:159], v[182:183], off offset:96
	ds_write_b16 v150, v182 offset:6944
	ds_write_b16_d16_hi v150, v182 offset:7088
	ds_write_b16 v150, v183 offset:7232
	ds_write_b16_d16_hi v150, v183 offset:7376
	v_pk_mul_f32 v[174:175], v[72:73], v[72:73]
	v_pk_mul_f32 v[176:177], v[74:75], v[74:75]
	v_pk_fma_f32 v[174:175], v[174:175], v[170:171], v[168:169]
	v_pk_fma_f32 v[176:177], v[176:177], v[170:171], v[168:169]
	v_pk_mul_f32 v[174:175], v[72:73], v[174:175]
	v_pk_mul_f32 v[176:177], v[74:75], v[176:177]
	v_exp_f32_e32 v174, v174
	v_exp_f32_e32 v175, v175
	v_exp_f32_e32 v176, v176
	v_exp_f32_e32 v177, v177
	v_pk_add_f32 v[174:175], v[174:175], v[172:173]
	v_pk_add_f32 v[176:177], v[176:177], v[172:173]
	v_rcp_f32_e32 v174, v174
	v_rcp_f32_e32 v175, v175
	v_rcp_f32_e32 v176, v176
	v_rcp_f32_e32 v177, v177
	v_pk_mul_f32 v[174:175], v[72:73], v[174:175]
	v_pk_mul_f32 v[176:177], v[74:75], v[176:177]
	v_cvt_pk_bf16_f32 v178, v174, v175
	v_cvt_pk_bf16_f32 v179, v176, v177
	global_store_dwordx2 v[160:161], v[178:179], off offset:96
	ds_write_b16 v150, v178 offset:6976
	ds_write_b16_d16_hi v150, v178 offset:7120
	ds_write_b16 v150, v179 offset:7264
	ds_write_b16_d16_hi v150, v179 offset:7408
	v_pk_mul_f32 v[174:175], v[64:65], v[64:65]
	v_pk_mul_f32 v[176:177], v[66:67], v[66:67]
	v_pk_fma_f32 v[174:175], v[174:175], v[170:171], v[168:169]
	v_pk_fma_f32 v[176:177], v[176:177], v[170:171], v[168:169]
	v_pk_mul_f32 v[174:175], v[64:65], v[174:175]
	v_pk_mul_f32 v[176:177], v[66:67], v[176:177]
	v_exp_f32_e32 v174, v174
	v_exp_f32_e32 v175, v175
	v_exp_f32_e32 v176, v176
	v_exp_f32_e32 v177, v177
	v_pk_add_f32 v[174:175], v[174:175], v[172:173]
	v_pk_add_f32 v[176:177], v[176:177], v[172:173]
	v_rcp_f32_e32 v174, v174
	v_rcp_f32_e32 v175, v175
	v_rcp_f32_e32 v176, v176
	v_rcp_f32_e32 v177, v177
	v_pk_mul_f32 v[174:175], v[64:65], v[174:175]
	v_pk_mul_f32 v[176:177], v[66:67], v[176:177]
	v_cvt_pk_bf16_f32 v182, v174, v175
	v_cvt_pk_bf16_f32 v183, v176, v177
	global_store_dwordx2 v[162:163], v[182:183], off offset:96
	ds_write_b16 v150, v182 offset:7008
	ds_write_b16_d16_hi v150, v182 offset:7152
	ds_write_b16 v150, v183 offset:7296
	ds_write_b16_d16_hi v150, v183 offset:7440
	v_pk_mul_f32 v[174:175], v[60:61], v[60:61]
	v_pk_mul_f32 v[176:177], v[62:63], v[62:63]
	v_pk_fma_f32 v[174:175], v[174:175], v[170:171], v[168:169]
	v_pk_fma_f32 v[176:177], v[176:177], v[170:171], v[168:169]
	v_pk_mul_f32 v[174:175], v[60:61], v[174:175]
	v_pk_mul_f32 v[176:177], v[62:63], v[176:177]
	v_exp_f32_e32 v174, v174
	v_exp_f32_e32 v175, v175
	v_exp_f32_e32 v176, v176
	v_exp_f32_e32 v177, v177
	v_pk_add_f32 v[174:175], v[174:175], v[172:173]
	v_pk_add_f32 v[176:177], v[176:177], v[172:173]
	v_rcp_f32_e32 v174, v174
	v_rcp_f32_e32 v175, v175
	v_rcp_f32_e32 v176, v176
	v_rcp_f32_e32 v177, v177
	v_pk_mul_f32 v[174:175], v[60:61], v[174:175]
	v_pk_mul_f32 v[176:177], v[62:63], v[176:177]
	v_cvt_pk_bf16_f32 v178, v174, v175
	v_cvt_pk_bf16_f32 v179, v176, v177
	global_store_dwordx2 v[156:157], v[178:179], off offset:128
	ds_write_b16 v150, v178 offset:9216
	ds_write_b16_d16_hi v150, v178 offset:9360
	ds_write_b16 v150, v179 offset:9504
	ds_write_b16_d16_hi v150, v179 offset:9648
	v_pk_mul_f32 v[174:175], v[52:53], v[52:53]
	v_pk_mul_f32 v[176:177], v[54:55], v[54:55]
	v_pk_fma_f32 v[174:175], v[174:175], v[170:171], v[168:169]
	v_pk_fma_f32 v[176:177], v[176:177], v[170:171], v[168:169]
	v_pk_mul_f32 v[174:175], v[52:53], v[174:175]
	v_pk_mul_f32 v[176:177], v[54:55], v[176:177]
	v_exp_f32_e32 v174, v174
	v_exp_f32_e32 v175, v175
	v_exp_f32_e32 v176, v176
	v_exp_f32_e32 v177, v177
	v_pk_add_f32 v[174:175], v[174:175], v[172:173]
	v_pk_add_f32 v[176:177], v[176:177], v[172:173]
	v_rcp_f32_e32 v174, v174
	v_rcp_f32_e32 v175, v175
	v_rcp_f32_e32 v176, v176
	v_rcp_f32_e32 v177, v177
	v_pk_mul_f32 v[174:175], v[52:53], v[174:175]
	v_pk_mul_f32 v[176:177], v[54:55], v[176:177]
	v_cvt_pk_bf16_f32 v182, v174, v175
	v_cvt_pk_bf16_f32 v183, v176, v177
	global_store_dwordx2 v[158:159], v[182:183], off offset:128
	ds_write_b16 v150, v182 offset:9248
	ds_write_b16_d16_hi v150, v182 offset:9392
	ds_write_b16 v150, v183 offset:9536
	ds_write_b16_d16_hi v150, v183 offset:9680
	v_pk_mul_f32 v[174:175], v[56:57], v[56:57]
	v_pk_mul_f32 v[176:177], v[58:59], v[58:59]
	v_pk_fma_f32 v[174:175], v[174:175], v[170:171], v[168:169]
	v_pk_fma_f32 v[176:177], v[176:177], v[170:171], v[168:169]
	v_pk_mul_f32 v[174:175], v[56:57], v[174:175]
	v_pk_mul_f32 v[176:177], v[58:59], v[176:177]
	v_exp_f32_e32 v174, v174
	v_exp_f32_e32 v175, v175
	v_exp_f32_e32 v176, v176
	v_exp_f32_e32 v177, v177
	v_pk_add_f32 v[174:175], v[174:175], v[172:173]
	v_pk_add_f32 v[176:177], v[176:177], v[172:173]
	v_rcp_f32_e32 v174, v174
	v_rcp_f32_e32 v175, v175
	v_rcp_f32_e32 v176, v176
	v_rcp_f32_e32 v177, v177
	v_pk_mul_f32 v[174:175], v[56:57], v[174:175]
	v_pk_mul_f32 v[176:177], v[58:59], v[176:177]
	v_cvt_pk_bf16_f32 v178, v174, v175
	v_cvt_pk_bf16_f32 v179, v176, v177
	global_store_dwordx2 v[160:161], v[178:179], off offset:128
	ds_write_b16 v150, v178 offset:9280
	ds_write_b16_d16_hi v150, v178 offset:9424
	ds_write_b16 v150, v179 offset:9568
	ds_write_b16_d16_hi v150, v179 offset:9712
	v_pk_mul_f32 v[174:175], v[48:49], v[48:49]
	v_pk_mul_f32 v[176:177], v[50:51], v[50:51]
	v_pk_fma_f32 v[174:175], v[174:175], v[170:171], v[168:169]
	v_pk_fma_f32 v[176:177], v[176:177], v[170:171], v[168:169]
	v_pk_mul_f32 v[174:175], v[48:49], v[174:175]
	v_pk_mul_f32 v[176:177], v[50:51], v[176:177]
	v_exp_f32_e32 v174, v174
	v_exp_f32_e32 v175, v175
	v_exp_f32_e32 v176, v176
	v_exp_f32_e32 v177, v177
	v_pk_add_f32 v[174:175], v[174:175], v[172:173]
	v_pk_add_f32 v[176:177], v[176:177], v[172:173]
	v_rcp_f32_e32 v174, v174
	v_rcp_f32_e32 v175, v175
	v_rcp_f32_e32 v176, v176
	v_rcp_f32_e32 v177, v177
	v_pk_mul_f32 v[174:175], v[48:49], v[174:175]
	v_pk_mul_f32 v[176:177], v[50:51], v[176:177]
	v_cvt_pk_bf16_f32 v182, v174, v175
	v_cvt_pk_bf16_f32 v183, v176, v177
	global_store_dwordx2 v[162:163], v[182:183], off offset:128
	ds_write_b16 v150, v182 offset:9312
	ds_write_b16_d16_hi v150, v182 offset:9456
	ds_write_b16 v150, v183 offset:9600
	ds_write_b16_d16_hi v150, v183 offset:9744
	v_pk_mul_f32 v[174:175], v[44:45], v[44:45]
	v_pk_mul_f32 v[176:177], v[46:47], v[46:47]
	v_pk_fma_f32 v[174:175], v[174:175], v[170:171], v[168:169]
	v_pk_fma_f32 v[176:177], v[176:177], v[170:171], v[168:169]
	v_pk_mul_f32 v[174:175], v[44:45], v[174:175]
	v_pk_mul_f32 v[176:177], v[46:47], v[176:177]
	v_exp_f32_e32 v174, v174
	v_exp_f32_e32 v175, v175
	v_exp_f32_e32 v176, v176
	v_exp_f32_e32 v177, v177
	v_pk_add_f32 v[174:175], v[174:175], v[172:173]
	v_pk_add_f32 v[176:177], v[176:177], v[172:173]
	v_rcp_f32_e32 v174, v174
	v_rcp_f32_e32 v175, v175
	v_rcp_f32_e32 v176, v176
	v_rcp_f32_e32 v177, v177
	v_pk_mul_f32 v[174:175], v[44:45], v[174:175]
	v_pk_mul_f32 v[176:177], v[46:47], v[176:177]
	v_cvt_pk_bf16_f32 v178, v174, v175
	v_cvt_pk_bf16_f32 v179, v176, v177
	global_store_dwordx2 v[156:157], v[178:179], off offset:160
	ds_write_b16 v150, v178 offset:11520
	ds_write_b16_d16_hi v150, v178 offset:11664
	ds_write_b16 v150, v179 offset:11808
	ds_write_b16_d16_hi v150, v179 offset:11952
	v_pk_mul_f32 v[174:175], v[36:37], v[36:37]
	v_pk_mul_f32 v[176:177], v[38:39], v[38:39]
	v_pk_fma_f32 v[174:175], v[174:175], v[170:171], v[168:169]
	v_pk_fma_f32 v[176:177], v[176:177], v[170:171], v[168:169]
	v_pk_mul_f32 v[174:175], v[36:37], v[174:175]
	v_pk_mul_f32 v[176:177], v[38:39], v[176:177]
	v_exp_f32_e32 v174, v174
	v_exp_f32_e32 v175, v175
	v_exp_f32_e32 v176, v176
	v_exp_f32_e32 v177, v177
	v_pk_add_f32 v[174:175], v[174:175], v[172:173]
	v_pk_add_f32 v[176:177], v[176:177], v[172:173]
	v_rcp_f32_e32 v174, v174
	v_rcp_f32_e32 v175, v175
	v_rcp_f32_e32 v176, v176
	v_rcp_f32_e32 v177, v177
	v_pk_mul_f32 v[174:175], v[36:37], v[174:175]
	v_pk_mul_f32 v[176:177], v[38:39], v[176:177]
	v_cvt_pk_bf16_f32 v182, v174, v175
	v_cvt_pk_bf16_f32 v183, v176, v177
	global_store_dwordx2 v[158:159], v[182:183], off offset:160
	ds_write_b16 v150, v182 offset:11552
	ds_write_b16_d16_hi v150, v182 offset:11696
	ds_write_b16 v150, v183 offset:11840
	ds_write_b16_d16_hi v150, v183 offset:11984
	v_pk_mul_f32 v[174:175], v[40:41], v[40:41]
	v_pk_mul_f32 v[176:177], v[42:43], v[42:43]
	v_pk_fma_f32 v[174:175], v[174:175], v[170:171], v[168:169]
	v_pk_fma_f32 v[176:177], v[176:177], v[170:171], v[168:169]
	v_pk_mul_f32 v[174:175], v[40:41], v[174:175]
	v_pk_mul_f32 v[176:177], v[42:43], v[176:177]
	v_exp_f32_e32 v174, v174
	v_exp_f32_e32 v175, v175
	v_exp_f32_e32 v176, v176
	v_exp_f32_e32 v177, v177
	v_pk_add_f32 v[174:175], v[174:175], v[172:173]
	v_pk_add_f32 v[176:177], v[176:177], v[172:173]
	v_rcp_f32_e32 v174, v174
	v_rcp_f32_e32 v175, v175
	v_rcp_f32_e32 v176, v176
	v_rcp_f32_e32 v177, v177
	v_pk_mul_f32 v[174:175], v[40:41], v[174:175]
	v_pk_mul_f32 v[176:177], v[42:43], v[176:177]
	v_cvt_pk_bf16_f32 v178, v174, v175
	v_cvt_pk_bf16_f32 v179, v176, v177
	global_store_dwordx2 v[160:161], v[178:179], off offset:160
	ds_write_b16 v150, v178 offset:11584
	ds_write_b16_d16_hi v150, v178 offset:11728
	ds_write_b16 v150, v179 offset:11872
	ds_write_b16_d16_hi v150, v179 offset:12016
	v_pk_mul_f32 v[174:175], v[32:33], v[32:33]
	v_pk_mul_f32 v[176:177], v[34:35], v[34:35]
	v_pk_fma_f32 v[174:175], v[174:175], v[170:171], v[168:169]
	v_pk_fma_f32 v[176:177], v[176:177], v[170:171], v[168:169]
	v_pk_mul_f32 v[174:175], v[32:33], v[174:175]
	v_pk_mul_f32 v[176:177], v[34:35], v[176:177]
	v_exp_f32_e32 v174, v174
	v_exp_f32_e32 v175, v175
	v_exp_f32_e32 v176, v176
	v_exp_f32_e32 v177, v177
	v_pk_add_f32 v[174:175], v[174:175], v[172:173]
	v_pk_add_f32 v[176:177], v[176:177], v[172:173]
	v_rcp_f32_e32 v174, v174
	v_rcp_f32_e32 v175, v175
	v_rcp_f32_e32 v176, v176
	v_rcp_f32_e32 v177, v177
	v_pk_mul_f32 v[174:175], v[32:33], v[174:175]
	v_pk_mul_f32 v[176:177], v[34:35], v[176:177]
	v_cvt_pk_bf16_f32 v182, v174, v175
	v_cvt_pk_bf16_f32 v183, v176, v177
	global_store_dwordx2 v[162:163], v[182:183], off offset:160
	ds_write_b16 v150, v182 offset:11616
	ds_write_b16_d16_hi v150, v182 offset:11760
	ds_write_b16 v150, v183 offset:11904
	ds_write_b16_d16_hi v150, v183 offset:12048
	v_pk_mul_f32 v[174:175], v[28:29], v[28:29]
	v_pk_mul_f32 v[176:177], v[30:31], v[30:31]
	v_pk_fma_f32 v[174:175], v[174:175], v[170:171], v[168:169]
	v_pk_fma_f32 v[176:177], v[176:177], v[170:171], v[168:169]
	v_pk_mul_f32 v[174:175], v[28:29], v[174:175]
	v_pk_mul_f32 v[176:177], v[30:31], v[176:177]
	v_exp_f32_e32 v174, v174
	v_exp_f32_e32 v175, v175
	v_exp_f32_e32 v176, v176
	v_exp_f32_e32 v177, v177
	v_pk_add_f32 v[174:175], v[174:175], v[172:173]
	v_pk_add_f32 v[176:177], v[176:177], v[172:173]
	v_rcp_f32_e32 v174, v174
	v_rcp_f32_e32 v175, v175
	v_rcp_f32_e32 v176, v176
	v_rcp_f32_e32 v177, v177
	v_pk_mul_f32 v[174:175], v[28:29], v[174:175]
	v_pk_mul_f32 v[176:177], v[30:31], v[176:177]
	v_cvt_pk_bf16_f32 v178, v174, v175
	v_cvt_pk_bf16_f32 v179, v176, v177
	global_store_dwordx2 v[156:157], v[178:179], off offset:192
	ds_write_b16 v150, v178 offset:13824
	ds_write_b16_d16_hi v150, v178 offset:13968
	ds_write_b16 v150, v179 offset:14112
	ds_write_b16_d16_hi v150, v179 offset:14256
	v_pk_mul_f32 v[174:175], v[16:17], v[16:17]
	v_pk_mul_f32 v[176:177], v[18:19], v[18:19]
	v_pk_fma_f32 v[174:175], v[174:175], v[170:171], v[168:169]
	v_pk_fma_f32 v[176:177], v[176:177], v[170:171], v[168:169]
	v_pk_mul_f32 v[174:175], v[16:17], v[174:175]
	v_pk_mul_f32 v[176:177], v[18:19], v[176:177]
	v_exp_f32_e32 v174, v174
	v_exp_f32_e32 v175, v175
	v_exp_f32_e32 v176, v176
	v_exp_f32_e32 v177, v177
	v_pk_add_f32 v[174:175], v[174:175], v[172:173]
	v_pk_add_f32 v[176:177], v[176:177], v[172:173]
	v_rcp_f32_e32 v174, v174
	v_rcp_f32_e32 v175, v175
	v_rcp_f32_e32 v176, v176
	v_rcp_f32_e32 v177, v177
	v_pk_mul_f32 v[174:175], v[16:17], v[174:175]
	v_pk_mul_f32 v[176:177], v[18:19], v[176:177]
	v_cvt_pk_bf16_f32 v182, v174, v175
	v_cvt_pk_bf16_f32 v183, v176, v177
	global_store_dwordx2 v[158:159], v[182:183], off offset:192
	ds_write_b16 v150, v182 offset:13856
	ds_write_b16_d16_hi v150, v182 offset:14000
	ds_write_b16 v150, v183 offset:14144
	ds_write_b16_d16_hi v150, v183 offset:14288
	v_pk_mul_f32 v[174:175], v[24:25], v[24:25]
	v_pk_mul_f32 v[176:177], v[26:27], v[26:27]
	v_pk_fma_f32 v[174:175], v[174:175], v[170:171], v[168:169]
	v_pk_fma_f32 v[176:177], v[176:177], v[170:171], v[168:169]
	v_pk_mul_f32 v[174:175], v[24:25], v[174:175]
	v_pk_mul_f32 v[176:177], v[26:27], v[176:177]
	v_exp_f32_e32 v174, v174
	v_exp_f32_e32 v175, v175
	v_exp_f32_e32 v176, v176
	v_exp_f32_e32 v177, v177
	v_pk_add_f32 v[174:175], v[174:175], v[172:173]
	v_pk_add_f32 v[176:177], v[176:177], v[172:173]
	v_rcp_f32_e32 v174, v174
	v_rcp_f32_e32 v175, v175
	v_rcp_f32_e32 v176, v176
	v_rcp_f32_e32 v177, v177
	v_pk_mul_f32 v[174:175], v[24:25], v[174:175]
	v_pk_mul_f32 v[176:177], v[26:27], v[176:177]
	v_cvt_pk_bf16_f32 v178, v174, v175
	v_cvt_pk_bf16_f32 v179, v176, v177
	global_store_dwordx2 v[160:161], v[178:179], off offset:192
	ds_write_b16 v150, v178 offset:13888
	ds_write_b16_d16_hi v150, v178 offset:14032
	ds_write_b16 v150, v179 offset:14176
	ds_write_b16_d16_hi v150, v179 offset:14320
	v_pk_mul_f32 v[174:175], v[12:13], v[12:13]
	v_pk_mul_f32 v[176:177], v[14:15], v[14:15]
	v_pk_fma_f32 v[174:175], v[174:175], v[170:171], v[168:169]
	v_pk_fma_f32 v[176:177], v[176:177], v[170:171], v[168:169]
	v_pk_mul_f32 v[174:175], v[12:13], v[174:175]
	v_pk_mul_f32 v[176:177], v[14:15], v[176:177]
	v_exp_f32_e32 v174, v174
	v_exp_f32_e32 v175, v175
	v_exp_f32_e32 v176, v176
	v_exp_f32_e32 v177, v177
	v_pk_add_f32 v[174:175], v[174:175], v[172:173]
	v_pk_add_f32 v[176:177], v[176:177], v[172:173]
	v_rcp_f32_e32 v174, v174
	v_rcp_f32_e32 v175, v175
	v_rcp_f32_e32 v176, v176
	v_rcp_f32_e32 v177, v177
	v_pk_mul_f32 v[174:175], v[12:13], v[174:175]
	v_pk_mul_f32 v[176:177], v[14:15], v[176:177]
	v_cvt_pk_bf16_f32 v182, v174, v175
	v_cvt_pk_bf16_f32 v183, v176, v177
	global_store_dwordx2 v[162:163], v[182:183], off offset:192
	ds_write_b16 v150, v182 offset:13920
	ds_write_b16_d16_hi v150, v182 offset:14064
	ds_write_b16 v150, v183 offset:14208
	ds_write_b16_d16_hi v150, v183 offset:14352
	v_pk_mul_f32 v[174:175], v[4:5], v[4:5]
	v_pk_mul_f32 v[176:177], v[6:7], v[6:7]
	v_pk_fma_f32 v[174:175], v[174:175], v[170:171], v[168:169]
	v_pk_fma_f32 v[176:177], v[176:177], v[170:171], v[168:169]
	v_pk_mul_f32 v[174:175], v[4:5], v[174:175]
	v_pk_mul_f32 v[176:177], v[6:7], v[176:177]
	v_exp_f32_e32 v174, v174
	v_exp_f32_e32 v175, v175
	v_exp_f32_e32 v176, v176
	v_exp_f32_e32 v177, v177
	v_pk_add_f32 v[174:175], v[174:175], v[172:173]
	v_pk_add_f32 v[176:177], v[176:177], v[172:173]
	v_rcp_f32_e32 v174, v174
	v_rcp_f32_e32 v175, v175
	v_rcp_f32_e32 v176, v176
	v_rcp_f32_e32 v177, v177
	v_pk_mul_f32 v[174:175], v[4:5], v[174:175]
	v_pk_mul_f32 v[176:177], v[6:7], v[176:177]
	v_cvt_pk_bf16_f32 v178, v174, v175
	v_cvt_pk_bf16_f32 v179, v176, v177
	global_store_dwordx2 v[156:157], v[178:179], off offset:224
	ds_write_b16 v150, v178 offset:16128
	ds_write_b16_d16_hi v150, v178 offset:16272
	ds_write_b16 v150, v179 offset:16416
	ds_write_b16_d16_hi v150, v179 offset:16560
	v_pk_mul_f32 v[174:175], v[0:1], v[0:1]
	v_pk_mul_f32 v[176:177], v[2:3], v[2:3]
	v_pk_fma_f32 v[174:175], v[174:175], v[170:171], v[168:169]
	v_pk_fma_f32 v[176:177], v[176:177], v[170:171], v[168:169]
	v_pk_mul_f32 v[174:175], v[0:1], v[174:175]
	v_pk_mul_f32 v[176:177], v[2:3], v[176:177]
	v_exp_f32_e32 v174, v174
	v_exp_f32_e32 v175, v175
	v_exp_f32_e32 v176, v176
	v_exp_f32_e32 v177, v177
	v_pk_add_f32 v[174:175], v[174:175], v[172:173]
	v_pk_add_f32 v[176:177], v[176:177], v[172:173]
	v_rcp_f32_e32 v174, v174
	v_rcp_f32_e32 v175, v175
	v_rcp_f32_e32 v176, v176
	v_rcp_f32_e32 v177, v177
	v_pk_mul_f32 v[174:175], v[0:1], v[174:175]
	v_pk_mul_f32 v[176:177], v[2:3], v[176:177]
	v_cvt_pk_bf16_f32 v182, v174, v175
	v_cvt_pk_bf16_f32 v183, v176, v177
	global_store_dwordx2 v[158:159], v[182:183], off offset:224
	ds_write_b16 v150, v182 offset:16160
	ds_write_b16_d16_hi v150, v182 offset:16304
	ds_write_b16 v150, v183 offset:16448
	ds_write_b16_d16_hi v150, v183 offset:16592
	v_pk_mul_f32 v[174:175], v[20:21], v[20:21]
	v_pk_mul_f32 v[176:177], v[22:23], v[22:23]
	v_pk_fma_f32 v[174:175], v[174:175], v[170:171], v[168:169]
	v_pk_fma_f32 v[176:177], v[176:177], v[170:171], v[168:169]
	v_pk_mul_f32 v[174:175], v[20:21], v[174:175]
	v_pk_mul_f32 v[176:177], v[22:23], v[176:177]
	v_exp_f32_e32 v174, v174
	v_exp_f32_e32 v175, v175
	v_exp_f32_e32 v176, v176
	v_exp_f32_e32 v177, v177
	v_pk_add_f32 v[174:175], v[174:175], v[172:173]
	v_pk_add_f32 v[176:177], v[176:177], v[172:173]
	v_rcp_f32_e32 v174, v174
	v_rcp_f32_e32 v175, v175
	v_rcp_f32_e32 v176, v176
	v_rcp_f32_e32 v177, v177
	v_pk_mul_f32 v[174:175], v[20:21], v[174:175]
	v_pk_mul_f32 v[176:177], v[22:23], v[176:177]
	v_cvt_pk_bf16_f32 v178, v174, v175
	v_cvt_pk_bf16_f32 v179, v176, v177
	global_store_dwordx2 v[160:161], v[178:179], off offset:224
	ds_write_b16 v150, v178 offset:16192
	ds_write_b16_d16_hi v150, v178 offset:16336
	ds_write_b16 v150, v179 offset:16480
	ds_write_b16_d16_hi v150, v179 offset:16624
	v_pk_mul_f32 v[174:175], v[8:9], v[8:9]
	v_pk_mul_f32 v[176:177], v[10:11], v[10:11]
	v_pk_fma_f32 v[174:175], v[174:175], v[170:171], v[168:169]
	v_pk_fma_f32 v[176:177], v[176:177], v[170:171], v[168:169]
	v_pk_mul_f32 v[174:175], v[8:9], v[174:175]
	v_pk_mul_f32 v[176:177], v[10:11], v[176:177]
	v_exp_f32_e32 v174, v174
	v_exp_f32_e32 v175, v175
	v_exp_f32_e32 v176, v176
	v_exp_f32_e32 v177, v177
	v_pk_add_f32 v[174:175], v[174:175], v[172:173]
	v_pk_add_f32 v[176:177], v[176:177], v[172:173]
	v_rcp_f32_e32 v174, v174
	v_rcp_f32_e32 v175, v175
	v_rcp_f32_e32 v176, v176
	v_rcp_f32_e32 v177, v177
	v_pk_mul_f32 v[174:175], v[8:9], v[174:175]
	v_pk_mul_f32 v[176:177], v[10:11], v[176:177]
	v_cvt_pk_bf16_f32 v182, v174, v175
	v_cvt_pk_bf16_f32 v183, v176, v177
	global_store_dwordx2 v[162:163], v[182:183], off offset:224
	ds_write_b16 v150, v182 offset:16224
	ds_write_b16_d16_hi v150, v182 offset:16368
	ds_write_b16 v150, v183 offset:16512
	ds_write_b16_d16_hi v150, v183 offset:16656
	s_waitcnt lgkmcnt(0)
	ds_read_b128 v[184:187], v152
	ds_read_b128 v[188:191], v152 offset:1152
	ds_read_b128 v[192:195], v152 offset:2304
	ds_read_b128 v[196:199], v152 offset:3456
	ds_read_b128 v[200:203], v152 offset:4608
	ds_read_b128 v[204:207], v152 offset:5760
	ds_read_b128 v[208:211], v152 offset:6912
	ds_read_b128 v[212:215], v152 offset:8064
	s_waitcnt lgkmcnt(7)
	v_lshlrev_b32_e32 v134, 16, v184
	v_and_b32_e32 v135, 0xffff0000, v184
	v_lshlrev_b32_e32 v136, 16, v185
	v_and_b32_e32 v137, 0xffff0000, v185
	v_lshlrev_b32_e32 v138, 16, v186
	v_and_b32_e32 v139, 0xffff0000, v186
	v_lshlrev_b32_e32 v140, 16, v187
	v_and_b32_e32 v141, 0xffff0000, v187
	v_pk_mul_f32 v[142:143], v[134:135], v[134:135]
	v_pk_mul_f32 v[144:145], v[136:137], v[136:137]
	v_pk_mul_f32 v[248:249], v[138:139], v[138:139]
	v_pk_mul_f32 v[250:251], v[140:141], v[140:141]
	v_add_f32_e32 v184, v134, v135
	v_add_f32_e32 v185, v142, v143
	v_add_f32_e32 v158, v136, v137
	v_add_f32_e32 v159, v144, v145
	v_add_f32_e32 v160, v138, v139
	v_add_f32_e32 v161, v248, v249
	v_add_f32_e32 v162, v140, v141
	v_add_f32_e32 v163, v250, v251
	v_pk_add_f32 v[184:185], v[184:185], v[158:159]
	v_pk_add_f32 v[184:185], v[184:185], v[160:161]
	v_pk_add_f32 v[184:185], v[184:185], v[162:163]
	ds_read_b128 v[216:219], v152 offset:9216
	s_waitcnt lgkmcnt(7)
	v_lshlrev_b32_e32 v134, 16, v188
	v_and_b32_e32 v135, 0xffff0000, v188
	v_lshlrev_b32_e32 v136, 16, v189
	v_and_b32_e32 v137, 0xffff0000, v189
	v_lshlrev_b32_e32 v138, 16, v190
	v_and_b32_e32 v139, 0xffff0000, v190
	v_lshlrev_b32_e32 v140, 16, v191
	v_and_b32_e32 v141, 0xffff0000, v191
	v_pk_mul_f32 v[142:143], v[134:135], v[134:135]
	v_pk_mul_f32 v[144:145], v[136:137], v[136:137]
	v_pk_mul_f32 v[248:249], v[138:139], v[138:139]
	v_pk_mul_f32 v[250:251], v[140:141], v[140:141]
	v_add_f32_e32 v188, v134, v135
	v_add_f32_e32 v189, v142, v143
	v_add_f32_e32 v158, v136, v137
	v_add_f32_e32 v159, v144, v145
	v_add_f32_e32 v160, v138, v139
	v_add_f32_e32 v161, v248, v249
	v_add_f32_e32 v162, v140, v141
	v_add_f32_e32 v163, v250, v251
	v_pk_add_f32 v[188:189], v[188:189], v[158:159]
	v_pk_add_f32 v[188:189], v[188:189], v[160:161]
	v_pk_add_f32 v[188:189], v[188:189], v[162:163]
	ds_read_b128 v[220:223], v152 offset:10368
	s_nop 1
	v_add_f32_dpp v184, v184, v184 quad_perm:[1,0,3,2] row_mask:0xf bank_mask:0xf
	v_add_f32_dpp v185, v185, v185 quad_perm:[1,0,3,2] row_mask:0xf bank_mask:0xf
	v_add_f32_dpp v188, v188, v188 quad_perm:[1,0,3,2] row_mask:0xf bank_mask:0xf
	v_add_f32_dpp v189, v189, v189 quad_perm:[1,0,3,2] row_mask:0xf bank_mask:0xf
	v_add_f32_dpp v184, v184, v184 quad_perm:[2,3,0,1] row_mask:0xf bank_mask:0xf
	v_add_f32_dpp v185, v185, v185 quad_perm:[2,3,0,1] row_mask:0xf bank_mask:0xf
	v_add_f32_dpp v188, v188, v188 quad_perm:[2,3,0,1] row_mask:0xf bank_mask:0xf
	v_add_f32_dpp v189, v189, v189 quad_perm:[2,3,0,1] row_mask:0xf bank_mask:0xf
	v_add_f32_dpp v184, v184, v184 row_half_mirror row_mask:0xf bank_mask:0xf
	v_add_f32_dpp v185, v185, v185 row_half_mirror row_mask:0xf bank_mask:0xf
	v_add_f32_dpp v188, v188, v188 row_half_mirror row_mask:0xf bank_mask:0xf
	v_add_f32_dpp v189, v189, v189 row_half_mirror row_mask:0xf bank_mask:0xf
	s_waitcnt lgkmcnt(7)
	v_lshlrev_b32_e32 v134, 16, v192
	v_and_b32_e32 v135, 0xffff0000, v192
	v_lshlrev_b32_e32 v136, 16, v193
	v_and_b32_e32 v137, 0xffff0000, v193
	v_lshlrev_b32_e32 v138, 16, v194
	v_and_b32_e32 v139, 0xffff0000, v194
	v_lshlrev_b32_e32 v140, 16, v195
	v_and_b32_e32 v141, 0xffff0000, v195
	v_pk_mul_f32 v[142:143], v[134:135], v[134:135]
	v_pk_mul_f32 v[144:145], v[136:137], v[136:137]
	v_pk_mul_f32 v[248:249], v[138:139], v[138:139]
	v_pk_mul_f32 v[250:251], v[140:141], v[140:141]
	v_add_f32_e32 v192, v134, v135
	v_add_f32_e32 v193, v142, v143
	v_add_f32_e32 v158, v136, v137
	v_add_f32_e32 v159, v144, v145
	v_add_f32_e32 v160, v138, v139
	v_add_f32_e32 v161, v248, v249
	v_add_f32_e32 v162, v140, v141
	v_add_f32_e32 v163, v250, v251
	v_pk_add_f32 v[192:193], v[192:193], v[158:159]
	v_pk_add_f32 v[192:193], v[192:193], v[160:161]
	v_pk_add_f32 v[192:193], v[192:193], v[162:163]
	ds_read_b128 v[224:227], v152 offset:11520
	s_waitcnt lgkmcnt(7)
	v_lshlrev_b32_e32 v134, 16, v196
	v_and_b32_e32 v135, 0xffff0000, v196
	v_lshlrev_b32_e32 v136, 16, v197
	v_and_b32_e32 v137, 0xffff0000, v197
	v_lshlrev_b32_e32 v138, 16, v198
	v_and_b32_e32 v139, 0xffff0000, v198
	v_lshlrev_b32_e32 v140, 16, v199
	v_and_b32_e32 v141, 0xffff0000, v199
	v_pk_mul_f32 v[142:143], v[134:135], v[134:135]
	v_pk_mul_f32 v[144:145], v[136:137], v[136:137]
	v_pk_mul_f32 v[248:249], v[138:139], v[138:139]
	v_pk_mul_f32 v[250:251], v[140:141], v[140:141]
	v_add_f32_e32 v196, v134, v135
	v_add_f32_e32 v197, v142, v143
	v_add_f32_e32 v158, v136, v137
	v_add_f32_e32 v159, v144, v145
	v_add_f32_e32 v160, v138, v139
	v_add_f32_e32 v161, v248, v249
	v_add_f32_e32 v162, v140, v141
	v_add_f32_e32 v163, v250, v251
	v_pk_add_f32 v[196:197], v[196:197], v[158:159]
	v_pk_add_f32 v[196:197], v[196:197], v[160:161]
	v_pk_add_f32 v[196:197], v[196:197], v[162:163]
	ds_read_b128 v[228:231], v152 offset:12672
	s_nop 1
	v_add_f32_dpp v192, v192, v192 quad_perm:[1,0,3,2] row_mask:0xf bank_mask:0xf
	v_add_f32_dpp v193, v193, v193 quad_perm:[1,0,3,2] row_mask:0xf bank_mask:0xf
	v_add_f32_dpp v196, v196, v196 quad_perm:[1,0,3,2] row_mask:0xf bank_mask:0xf
	v_add_f32_dpp v197, v197, v197 quad_perm:[1,0,3,2] row_mask:0xf bank_mask:0xf
	v_add_f32_dpp v192, v192, v192 quad_perm:[2,3,0,1] row_mask:0xf bank_mask:0xf
	v_add_f32_dpp v193, v193, v193 quad_perm:[2,3,0,1] row_mask:0xf bank_mask:0xf
	v_add_f32_dpp v196, v196, v196 quad_perm:[2,3,0,1] row_mask:0xf bank_mask:0xf
	v_add_f32_dpp v197, v197, v197 quad_perm:[2,3,0,1] row_mask:0xf bank_mask:0xf
	v_add_f32_dpp v192, v192, v192 row_half_mirror row_mask:0xf bank_mask:0xf
	v_add_f32_dpp v193, v193, v193 row_half_mirror row_mask:0xf bank_mask:0xf
	v_add_f32_dpp v196, v196, v196 row_half_mirror row_mask:0xf bank_mask:0xf
	v_add_f32_dpp v197, v197, v197 row_half_mirror row_mask:0xf bank_mask:0xf
	s_waitcnt lgkmcnt(7)
	v_lshlrev_b32_e32 v134, 16, v200
	v_and_b32_e32 v135, 0xffff0000, v200
	v_lshlrev_b32_e32 v136, 16, v201
	v_and_b32_e32 v137, 0xffff0000, v201
	v_lshlrev_b32_e32 v138, 16, v202
	v_and_b32_e32 v139, 0xffff0000, v202
	v_lshlrev_b32_e32 v140, 16, v203
	v_and_b32_e32 v141, 0xffff0000, v203
	v_pk_mul_f32 v[142:143], v[134:135], v[134:135]
	v_pk_mul_f32 v[144:145], v[136:137], v[136:137]
	v_pk_mul_f32 v[248:249], v[138:139], v[138:139]
	v_pk_mul_f32 v[250:251], v[140:141], v[140:141]
	v_add_f32_e32 v200, v134, v135
	v_add_f32_e32 v201, v142, v143
	v_add_f32_e32 v158, v136, v137
	v_add_f32_e32 v159, v144, v145
	v_add_f32_e32 v160, v138, v139
	v_add_f32_e32 v161, v248, v249
	v_add_f32_e32 v162, v140, v141
	v_add_f32_e32 v163, v250, v251
	v_pk_add_f32 v[200:201], v[200:201], v[158:159]
	v_pk_add_f32 v[200:201], v[200:201], v[160:161]
	v_pk_add_f32 v[200:201], v[200:201], v[162:163]
	ds_read_b128 v[232:235], v152 offset:13824
	s_waitcnt lgkmcnt(7)
	v_lshlrev_b32_e32 v134, 16, v204
	v_and_b32_e32 v135, 0xffff0000, v204
	v_lshlrev_b32_e32 v136, 16, v205
	v_and_b32_e32 v137, 0xffff0000, v205
	v_lshlrev_b32_e32 v138, 16, v206
	v_and_b32_e32 v139, 0xffff0000, v206
	v_lshlrev_b32_e32 v140, 16, v207
	v_and_b32_e32 v141, 0xffff0000, v207
	v_pk_mul_f32 v[142:143], v[134:135], v[134:135]
	v_pk_mul_f32 v[144:145], v[136:137], v[136:137]
	v_pk_mul_f32 v[248:249], v[138:139], v[138:139]
	v_pk_mul_f32 v[250:251], v[140:141], v[140:141]
	v_add_f32_e32 v204, v134, v135
	v_add_f32_e32 v205, v142, v143
	v_add_f32_e32 v158, v136, v137
	v_add_f32_e32 v159, v144, v145
	v_add_f32_e32 v160, v138, v139
	v_add_f32_e32 v161, v248, v249
	v_add_f32_e32 v162, v140, v141
	v_add_f32_e32 v163, v250, v251
	v_pk_add_f32 v[204:205], v[204:205], v[158:159]
	v_pk_add_f32 v[204:205], v[204:205], v[160:161]
	v_pk_add_f32 v[204:205], v[204:205], v[162:163]
	ds_read_b128 v[236:239], v152 offset:14976
	s_nop 1
	v_add_f32_dpp v200, v200, v200 quad_perm:[1,0,3,2] row_mask:0xf bank_mask:0xf
	v_add_f32_dpp v201, v201, v201 quad_perm:[1,0,3,2] row_mask:0xf bank_mask:0xf
	v_add_f32_dpp v204, v204, v204 quad_perm:[1,0,3,2] row_mask:0xf bank_mask:0xf
	v_add_f32_dpp v205, v205, v205 quad_perm:[1,0,3,2] row_mask:0xf bank_mask:0xf
	v_add_f32_dpp v200, v200, v200 quad_perm:[2,3,0,1] row_mask:0xf bank_mask:0xf
	v_add_f32_dpp v201, v201, v201 quad_perm:[2,3,0,1] row_mask:0xf bank_mask:0xf
	v_add_f32_dpp v204, v204, v204 quad_perm:[2,3,0,1] row_mask:0xf bank_mask:0xf
	v_add_f32_dpp v205, v205, v205 quad_perm:[2,3,0,1] row_mask:0xf bank_mask:0xf
	v_add_f32_dpp v200, v200, v200 row_half_mirror row_mask:0xf bank_mask:0xf
	v_add_f32_dpp v201, v201, v201 row_half_mirror row_mask:0xf bank_mask:0xf
	v_add_f32_dpp v204, v204, v204 row_half_mirror row_mask:0xf bank_mask:0xf
	v_add_f32_dpp v205, v205, v205 row_half_mirror row_mask:0xf bank_mask:0xf
	s_waitcnt lgkmcnt(7)
	v_lshlrev_b32_e32 v134, 16, v208
	v_and_b32_e32 v135, 0xffff0000, v208
	v_lshlrev_b32_e32 v136, 16, v209
	v_and_b32_e32 v137, 0xffff0000, v209
	v_lshlrev_b32_e32 v138, 16, v210
	v_and_b32_e32 v139, 0xffff0000, v210
	v_lshlrev_b32_e32 v140, 16, v211
	v_and_b32_e32 v141, 0xffff0000, v211
	v_pk_mul_f32 v[142:143], v[134:135], v[134:135]
	v_pk_mul_f32 v[144:145], v[136:137], v[136:137]
	v_pk_mul_f32 v[248:249], v[138:139], v[138:139]
	v_pk_mul_f32 v[250:251], v[140:141], v[140:141]
	v_add_f32_e32 v208, v134, v135
	v_add_f32_e32 v209, v142, v143
	v_add_f32_e32 v158, v136, v137
	v_add_f32_e32 v159, v144, v145
	v_add_f32_e32 v160, v138, v139
	v_add_f32_e32 v161, v248, v249
	v_add_f32_e32 v162, v140, v141
	v_add_f32_e32 v163, v250, v251
	v_pk_add_f32 v[208:209], v[208:209], v[158:159]
	v_pk_add_f32 v[208:209], v[208:209], v[160:161]
	v_pk_add_f32 v[208:209], v[208:209], v[162:163]
	ds_read_b128 v[240:243], v152 offset:16128
	s_waitcnt lgkmcnt(7)
	v_lshlrev_b32_e32 v134, 16, v212
	v_and_b32_e32 v135, 0xffff0000, v212
	v_lshlrev_b32_e32 v136, 16, v213
	v_and_b32_e32 v137, 0xffff0000, v213
	v_lshlrev_b32_e32 v138, 16, v214
	v_and_b32_e32 v139, 0xffff0000, v214
	v_lshlrev_b32_e32 v140, 16, v215
	v_and_b32_e32 v141, 0xffff0000, v215
	v_pk_mul_f32 v[142:143], v[134:135], v[134:135]
	v_pk_mul_f32 v[144:145], v[136:137], v[136:137]
	v_pk_mul_f32 v[248:249], v[138:139], v[138:139]
	v_pk_mul_f32 v[250:251], v[140:141], v[140:141]
	v_add_f32_e32 v212, v134, v135
	v_add_f32_e32 v213, v142, v143
	v_add_f32_e32 v158, v136, v137
	v_add_f32_e32 v159, v144, v145
	v_add_f32_e32 v160, v138, v139
	v_add_f32_e32 v161, v248, v249
	v_add_f32_e32 v162, v140, v141
	v_add_f32_e32 v163, v250, v251
	v_pk_add_f32 v[212:213], v[212:213], v[158:159]
	v_pk_add_f32 v[212:213], v[212:213], v[160:161]
	v_pk_add_f32 v[212:213], v[212:213], v[162:163]
	ds_read_b128 v[244:247], v152 offset:17280
	s_nop 1
	v_add_f32_dpp v208, v208, v208 quad_perm:[1,0,3,2] row_mask:0xf bank_mask:0xf
	v_add_f32_dpp v209, v209, v209 quad_perm:[1,0,3,2] row_mask:0xf bank_mask:0xf
	v_add_f32_dpp v212, v212, v212 quad_perm:[1,0,3,2] row_mask:0xf bank_mask:0xf
	v_add_f32_dpp v213, v213, v213 quad_perm:[1,0,3,2] row_mask:0xf bank_mask:0xf
	v_add_f32_dpp v208, v208, v208 quad_perm:[2,3,0,1] row_mask:0xf bank_mask:0xf
	v_add_f32_dpp v209, v209, v209 quad_perm:[2,3,0,1] row_mask:0xf bank_mask:0xf
	v_add_f32_dpp v212, v212, v212 quad_perm:[2,3,0,1] row_mask:0xf bank_mask:0xf
	v_add_f32_dpp v213, v213, v213 quad_perm:[2,3,0,1] row_mask:0xf bank_mask:0xf
	v_add_f32_dpp v208, v208, v208 row_half_mirror row_mask:0xf bank_mask:0xf
	v_add_f32_dpp v209, v209, v209 row_half_mirror row_mask:0xf bank_mask:0xf
	v_add_f32_dpp v212, v212, v212 row_half_mirror row_mask:0xf bank_mask:0xf
	v_add_f32_dpp v213, v213, v213 row_half_mirror row_mask:0xf bank_mask:0xf
	s_waitcnt lgkmcnt(7)
	v_lshlrev_b32_e32 v134, 16, v216
	v_and_b32_e32 v135, 0xffff0000, v216
	v_lshlrev_b32_e32 v136, 16, v217
	v_and_b32_e32 v137, 0xffff0000, v217
	v_lshlrev_b32_e32 v138, 16, v218
	v_and_b32_e32 v139, 0xffff0000, v218
	v_lshlrev_b32_e32 v140, 16, v219
	v_and_b32_e32 v141, 0xffff0000, v219
	v_pk_mul_f32 v[142:143], v[134:135], v[134:135]
	v_pk_mul_f32 v[144:145], v[136:137], v[136:137]
	v_pk_mul_f32 v[248:249], v[138:139], v[138:139]
	v_pk_mul_f32 v[250:251], v[140:141], v[140:141]
	v_add_f32_e32 v216, v134, v135
	v_add_f32_e32 v217, v142, v143
	v_add_f32_e32 v158, v136, v137
	v_add_f32_e32 v159, v144, v145
	v_add_f32_e32 v160, v138, v139
	v_add_f32_e32 v161, v248, v249
	v_add_f32_e32 v162, v140, v141
	v_add_f32_e32 v163, v250, v251
	v_pk_add_f32 v[216:217], v[216:217], v[158:159]
	v_pk_add_f32 v[216:217], v[216:217], v[160:161]
	v_pk_add_f32 v[216:217], v[216:217], v[162:163]
	s_waitcnt lgkmcnt(6)
	v_lshlrev_b32_e32 v134, 16, v220
	v_and_b32_e32 v135, 0xffff0000, v220
	v_lshlrev_b32_e32 v136, 16, v221
	v_and_b32_e32 v137, 0xffff0000, v221
	v_lshlrev_b32_e32 v138, 16, v222
	v_and_b32_e32 v139, 0xffff0000, v222
	v_lshlrev_b32_e32 v140, 16, v223
	v_and_b32_e32 v141, 0xffff0000, v223
	v_pk_mul_f32 v[142:143], v[134:135], v[134:135]
	v_pk_mul_f32 v[144:145], v[136:137], v[136:137]
	v_pk_mul_f32 v[248:249], v[138:139], v[138:139]
	v_pk_mul_f32 v[250:251], v[140:141], v[140:141]
	v_add_f32_e32 v220, v134, v135
	v_add_f32_e32 v221, v142, v143
	v_add_f32_e32 v158, v136, v137
	v_add_f32_e32 v159, v144, v145
	v_add_f32_e32 v160, v138, v139
	v_add_f32_e32 v161, v248, v249
	v_add_f32_e32 v162, v140, v141
	v_add_f32_e32 v163, v250, v251
	v_pk_add_f32 v[220:221], v[220:221], v[158:159]
	v_pk_add_f32 v[220:221], v[220:221], v[160:161]
	v_pk_add_f32 v[220:221], v[220:221], v[162:163]
	s_nop 1
	v_add_f32_dpp v216, v216, v216 quad_perm:[1,0,3,2] row_mask:0xf bank_mask:0xf
	v_add_f32_dpp v217, v217, v217 quad_perm:[1,0,3,2] row_mask:0xf bank_mask:0xf
	v_add_f32_dpp v220, v220, v220 quad_perm:[1,0,3,2] row_mask:0xf bank_mask:0xf
	v_add_f32_dpp v221, v221, v221 quad_perm:[1,0,3,2] row_mask:0xf bank_mask:0xf
	v_add_f32_dpp v216, v216, v216 quad_perm:[2,3,0,1] row_mask:0xf bank_mask:0xf
	v_add_f32_dpp v217, v217, v217 quad_perm:[2,3,0,1] row_mask:0xf bank_mask:0xf
	v_add_f32_dpp v220, v220, v220 quad_perm:[2,3,0,1] row_mask:0xf bank_mask:0xf
	v_add_f32_dpp v221, v221, v221 quad_perm:[2,3,0,1] row_mask:0xf bank_mask:0xf
	v_add_f32_dpp v216, v216, v216 row_half_mirror row_mask:0xf bank_mask:0xf
	v_add_f32_dpp v217, v217, v217 row_half_mirror row_mask:0xf bank_mask:0xf
	v_add_f32_dpp v220, v220, v220 row_half_mirror row_mask:0xf bank_mask:0xf
	v_add_f32_dpp v221, v221, v221 row_half_mirror row_mask:0xf bank_mask:0xf
	s_waitcnt lgkmcnt(5)
	v_lshlrev_b32_e32 v134, 16, v224
	v_and_b32_e32 v135, 0xffff0000, v224
	v_lshlrev_b32_e32 v136, 16, v225
	v_and_b32_e32 v137, 0xffff0000, v225
	v_lshlrev_b32_e32 v138, 16, v226
	v_and_b32_e32 v139, 0xffff0000, v226
	v_lshlrev_b32_e32 v140, 16, v227
	v_and_b32_e32 v141, 0xffff0000, v227
	v_pk_mul_f32 v[142:143], v[134:135], v[134:135]
	v_pk_mul_f32 v[144:145], v[136:137], v[136:137]
	v_pk_mul_f32 v[248:249], v[138:139], v[138:139]
	v_pk_mul_f32 v[250:251], v[140:141], v[140:141]
	v_add_f32_e32 v224, v134, v135
	v_add_f32_e32 v225, v142, v143
	v_add_f32_e32 v158, v136, v137
	v_add_f32_e32 v159, v144, v145
	v_add_f32_e32 v160, v138, v139
	v_add_f32_e32 v161, v248, v249
	v_add_f32_e32 v162, v140, v141
	v_add_f32_e32 v163, v250, v251
	v_pk_add_f32 v[224:225], v[224:225], v[158:159]
	v_pk_add_f32 v[224:225], v[224:225], v[160:161]
	v_pk_add_f32 v[224:225], v[224:225], v[162:163]
	s_waitcnt lgkmcnt(4)
	v_lshlrev_b32_e32 v134, 16, v228
	v_and_b32_e32 v135, 0xffff0000, v228
	v_lshlrev_b32_e32 v136, 16, v229
	v_and_b32_e32 v137, 0xffff0000, v229
	v_lshlrev_b32_e32 v138, 16, v230
	v_and_b32_e32 v139, 0xffff0000, v230
	v_lshlrev_b32_e32 v140, 16, v231
	v_and_b32_e32 v141, 0xffff0000, v231
	v_pk_mul_f32 v[142:143], v[134:135], v[134:135]
	v_pk_mul_f32 v[144:145], v[136:137], v[136:137]
	v_pk_mul_f32 v[248:249], v[138:139], v[138:139]
	v_pk_mul_f32 v[250:251], v[140:141], v[140:141]
	v_add_f32_e32 v228, v134, v135
	v_add_f32_e32 v229, v142, v143
	v_add_f32_e32 v158, v136, v137
	v_add_f32_e32 v159, v144, v145
	v_add_f32_e32 v160, v138, v139
	v_add_f32_e32 v161, v248, v249
	v_add_f32_e32 v162, v140, v141
	v_add_f32_e32 v163, v250, v251
	v_pk_add_f32 v[228:229], v[228:229], v[158:159]
	v_pk_add_f32 v[228:229], v[228:229], v[160:161]
	v_pk_add_f32 v[228:229], v[228:229], v[162:163]
	s_nop 1
	v_add_f32_dpp v224, v224, v224 quad_perm:[1,0,3,2] row_mask:0xf bank_mask:0xf
	v_add_f32_dpp v225, v225, v225 quad_perm:[1,0,3,2] row_mask:0xf bank_mask:0xf
	v_add_f32_dpp v228, v228, v228 quad_perm:[1,0,3,2] row_mask:0xf bank_mask:0xf
	v_add_f32_dpp v229, v229, v229 quad_perm:[1,0,3,2] row_mask:0xf bank_mask:0xf
	v_add_f32_dpp v224, v224, v224 quad_perm:[2,3,0,1] row_mask:0xf bank_mask:0xf
	v_add_f32_dpp v225, v225, v225 quad_perm:[2,3,0,1] row_mask:0xf bank_mask:0xf
	v_add_f32_dpp v228, v228, v228 quad_perm:[2,3,0,1] row_mask:0xf bank_mask:0xf
	v_add_f32_dpp v229, v229, v229 quad_perm:[2,3,0,1] row_mask:0xf bank_mask:0xf
	v_add_f32_dpp v224, v224, v224 row_half_mirror row_mask:0xf bank_mask:0xf
	v_add_f32_dpp v225, v225, v225 row_half_mirror row_mask:0xf bank_mask:0xf
	v_add_f32_dpp v228, v228, v228 row_half_mirror row_mask:0xf bank_mask:0xf
	v_add_f32_dpp v229, v229, v229 row_half_mirror row_mask:0xf bank_mask:0xf
	s_waitcnt lgkmcnt(3)
	v_lshlrev_b32_e32 v134, 16, v232
	v_and_b32_e32 v135, 0xffff0000, v232
	v_lshlrev_b32_e32 v136, 16, v233
	v_and_b32_e32 v137, 0xffff0000, v233
	v_lshlrev_b32_e32 v138, 16, v234
	v_and_b32_e32 v139, 0xffff0000, v234
	v_lshlrev_b32_e32 v140, 16, v235
	v_and_b32_e32 v141, 0xffff0000, v235
	v_pk_mul_f32 v[142:143], v[134:135], v[134:135]
	v_pk_mul_f32 v[144:145], v[136:137], v[136:137]
	v_pk_mul_f32 v[248:249], v[138:139], v[138:139]
	v_pk_mul_f32 v[250:251], v[140:141], v[140:141]
	v_add_f32_e32 v232, v134, v135
	v_add_f32_e32 v233, v142, v143
	v_add_f32_e32 v158, v136, v137
	v_add_f32_e32 v159, v144, v145
	v_add_f32_e32 v160, v138, v139
	v_add_f32_e32 v161, v248, v249
	v_add_f32_e32 v162, v140, v141
	v_add_f32_e32 v163, v250, v251
	v_pk_add_f32 v[232:233], v[232:233], v[158:159]
	v_pk_add_f32 v[232:233], v[232:233], v[160:161]
	v_pk_add_f32 v[232:233], v[232:233], v[162:163]
	s_waitcnt lgkmcnt(2)
	v_lshlrev_b32_e32 v134, 16, v236
	v_and_b32_e32 v135, 0xffff0000, v236
	v_lshlrev_b32_e32 v136, 16, v237
	v_and_b32_e32 v137, 0xffff0000, v237
	v_lshlrev_b32_e32 v138, 16, v238
	v_and_b32_e32 v139, 0xffff0000, v238
	v_lshlrev_b32_e32 v140, 16, v239
	v_and_b32_e32 v141, 0xffff0000, v239
	v_pk_mul_f32 v[142:143], v[134:135], v[134:135]
	v_pk_mul_f32 v[144:145], v[136:137], v[136:137]
	v_pk_mul_f32 v[248:249], v[138:139], v[138:139]
	v_pk_mul_f32 v[250:251], v[140:141], v[140:141]
	v_add_f32_e32 v236, v134, v135
	v_add_f32_e32 v237, v142, v143
	v_add_f32_e32 v158, v136, v137
	v_add_f32_e32 v159, v144, v145
	v_add_f32_e32 v160, v138, v139
	v_add_f32_e32 v161, v248, v249
	v_add_f32_e32 v162, v140, v141
	v_add_f32_e32 v163, v250, v251
	v_pk_add_f32 v[236:237], v[236:237], v[158:159]
	v_pk_add_f32 v[236:237], v[236:237], v[160:161]
	v_pk_add_f32 v[236:237], v[236:237], v[162:163]
	s_nop 1
	v_add_f32_dpp v232, v232, v232 quad_perm:[1,0,3,2] row_mask:0xf bank_mask:0xf
	v_add_f32_dpp v233, v233, v233 quad_perm:[1,0,3,2] row_mask:0xf bank_mask:0xf
	v_add_f32_dpp v236, v236, v236 quad_perm:[1,0,3,2] row_mask:0xf bank_mask:0xf
	v_add_f32_dpp v237, v237, v237 quad_perm:[1,0,3,2] row_mask:0xf bank_mask:0xf
	v_add_f32_dpp v232, v232, v232 quad_perm:[2,3,0,1] row_mask:0xf bank_mask:0xf
	v_add_f32_dpp v233, v233, v233 quad_perm:[2,3,0,1] row_mask:0xf bank_mask:0xf
	v_add_f32_dpp v236, v236, v236 quad_perm:[2,3,0,1] row_mask:0xf bank_mask:0xf
	v_add_f32_dpp v237, v237, v237 quad_perm:[2,3,0,1] row_mask:0xf bank_mask:0xf
	v_add_f32_dpp v232, v232, v232 row_half_mirror row_mask:0xf bank_mask:0xf
	v_add_f32_dpp v233, v233, v233 row_half_mirror row_mask:0xf bank_mask:0xf
	v_add_f32_dpp v236, v236, v236 row_half_mirror row_mask:0xf bank_mask:0xf
	v_add_f32_dpp v237, v237, v237 row_half_mirror row_mask:0xf bank_mask:0xf
	s_waitcnt lgkmcnt(1)
	v_lshlrev_b32_e32 v134, 16, v240
	v_and_b32_e32 v135, 0xffff0000, v240
	v_lshlrev_b32_e32 v136, 16, v241
	v_and_b32_e32 v137, 0xffff0000, v241
	v_lshlrev_b32_e32 v138, 16, v242
	v_and_b32_e32 v139, 0xffff0000, v242
	v_lshlrev_b32_e32 v140, 16, v243
	v_and_b32_e32 v141, 0xffff0000, v243
	v_pk_mul_f32 v[142:143], v[134:135], v[134:135]
	v_pk_mul_f32 v[144:145], v[136:137], v[136:137]
	v_pk_mul_f32 v[248:249], v[138:139], v[138:139]
	v_pk_mul_f32 v[250:251], v[140:141], v[140:141]
	v_add_f32_e32 v240, v134, v135
	v_add_f32_e32 v241, v142, v143
	v_add_f32_e32 v158, v136, v137
	v_add_f32_e32 v159, v144, v145
	v_add_f32_e32 v160, v138, v139
	v_add_f32_e32 v161, v248, v249
	v_add_f32_e32 v162, v140, v141
	v_add_f32_e32 v163, v250, v251
	v_pk_add_f32 v[240:241], v[240:241], v[158:159]
	v_pk_add_f32 v[240:241], v[240:241], v[160:161]
	v_pk_add_f32 v[240:241], v[240:241], v[162:163]
	s_waitcnt lgkmcnt(0)
	v_lshlrev_b32_e32 v134, 16, v244
	v_and_b32_e32 v135, 0xffff0000, v244
	v_lshlrev_b32_e32 v136, 16, v245
	v_and_b32_e32 v137, 0xffff0000, v245
	v_lshlrev_b32_e32 v138, 16, v246
	v_and_b32_e32 v139, 0xffff0000, v246
	v_lshlrev_b32_e32 v140, 16, v247
	v_and_b32_e32 v141, 0xffff0000, v247
	v_pk_mul_f32 v[142:143], v[134:135], v[134:135]
	v_pk_mul_f32 v[144:145], v[136:137], v[136:137]
	v_pk_mul_f32 v[248:249], v[138:139], v[138:139]
	v_pk_mul_f32 v[250:251], v[140:141], v[140:141]
	v_add_f32_e32 v244, v134, v135
	v_add_f32_e32 v245, v142, v143
	v_add_f32_e32 v158, v136, v137
	v_add_f32_e32 v159, v144, v145
	v_add_f32_e32 v160, v138, v139
	v_add_f32_e32 v161, v248, v249
	v_add_f32_e32 v162, v140, v141
	v_add_f32_e32 v163, v250, v251
	v_pk_add_f32 v[244:245], v[244:245], v[158:159]
	v_pk_add_f32 v[244:245], v[244:245], v[160:161]
	v_pk_add_f32 v[244:245], v[244:245], v[162:163]
	s_nop 1
	v_add_f32_dpp v240, v240, v240 quad_perm:[1,0,3,2] row_mask:0xf bank_mask:0xf
	v_add_f32_dpp v241, v241, v241 quad_perm:[1,0,3,2] row_mask:0xf bank_mask:0xf
	v_add_f32_dpp v244, v244, v244 quad_perm:[1,0,3,2] row_mask:0xf bank_mask:0xf
	v_add_f32_dpp v245, v245, v245 quad_perm:[1,0,3,2] row_mask:0xf bank_mask:0xf
	v_add_f32_dpp v240, v240, v240 quad_perm:[2,3,0,1] row_mask:0xf bank_mask:0xf
	v_add_f32_dpp v241, v241, v241 quad_perm:[2,3,0,1] row_mask:0xf bank_mask:0xf
	v_add_f32_dpp v244, v244, v244 quad_perm:[2,3,0,1] row_mask:0xf bank_mask:0xf
	v_add_f32_dpp v245, v245, v245 quad_perm:[2,3,0,1] row_mask:0xf bank_mask:0xf
	v_add_f32_dpp v240, v240, v240 row_half_mirror row_mask:0xf bank_mask:0xf
	v_add_f32_dpp v241, v241, v241 row_half_mirror row_mask:0xf bank_mask:0xf
	v_add_f32_dpp v244, v244, v244 row_half_mirror row_mask:0xf bank_mask:0xf
	v_add_f32_dpp v245, v245, v245 row_half_mirror row_mask:0xf bank_mask:0xf
	s_and_saveexec_b64 s[44:45], s[0:1]
	global_store_dwordx2 v129, v[184:185], s[6:7]
	v_add_u32_e32 v129, 0x800, v129
	global_store_dwordx2 v129, v[188:189], s[6:7]
	v_add_u32_e32 v129, 0x800, v129
	global_store_dwordx2 v129, v[192:193], s[6:7]
	v_add_u32_e32 v129, 0x800, v129
	global_store_dwordx2 v129, v[196:197], s[6:7]
	v_add_u32_e32 v129, 0x800, v129
	global_store_dwordx2 v129, v[200:201], s[6:7]
	v_add_u32_e32 v129, 0x800, v129
	global_store_dwordx2 v129, v[204:205], s[6:7]
	v_add_u32_e32 v129, 0x800, v129
	global_store_dwordx2 v129, v[208:209], s[6:7]
	v_add_u32_e32 v129, 0x800, v129
	global_store_dwordx2 v129, v[212:213], s[6:7]
	v_add_u32_e32 v129, 0x800, v129
	global_store_dwordx2 v129, v[216:217], s[6:7]
	v_add_u32_e32 v129, 0x800, v129
	global_store_dwordx2 v129, v[220:221], s[6:7]
	v_add_u32_e32 v129, 0x800, v129
	global_store_dwordx2 v129, v[224:225], s[6:7]
	v_add_u32_e32 v129, 0x800, v129
	global_store_dwordx2 v129, v[228:229], s[6:7]
	v_add_u32_e32 v129, 0x800, v129
	global_store_dwordx2 v129, v[232:233], s[6:7]
	v_add_u32_e32 v129, 0x800, v129
	global_store_dwordx2 v129, v[236:237], s[6:7]
	v_add_u32_e32 v129, 0x800, v129
	global_store_dwordx2 v129, v[240:241], s[6:7]
	v_add_u32_e32 v129, 0x800, v129
	global_store_dwordx2 v129, v[244:245], s[6:7]
	s_or_b64 exec, exec, s[44:45]
	s_waitcnt lgkmcnt(0)

.LBB0_1636:
	s_ashr_i32 s20, s44, 2
	v_mov_b32_e32 v6, v181
	s_and_b32 s4, s44, 7
	s_and_b32 s39, s20, -8
	s_or_b32 s30, s39, s4
	v_lshrrev_b32_e32 v7, 4, v6
	v_lshlrev_b32_e32 v1, 6, v6
	v_xor_b32_e32 v0, v7, v6
	v_and_b32_e32 v8, 0x3c0, v1
	v_lshlrev_b32_e32 v1, 8, v6
	s_ashr_i32 s31, s30, 31
	v_lshlrev_b32_e32 v0, 3, v0
	v_and_b32_e32 v1, 0xfffff800, v1
	s_and_b32 s38, s43, 7
	s_bfe_u32 s4, s44, 0x20003
	s_lshl_b64 s[20:21], s[30:31], 20
	v_and_or_b32 v0, v0, 56, v1
	s_add_u32 s20, s3, s20
	v_ashrrev_i32_e32 v1, 31, v0
	s_addc_u32 s21, s40, s21
	v_lshlrev_b64 v[0:1], 1, v[0:1]
	v_lshl_add_u32 v134, v6, 4, 0
	v_lshl_add_u64 v[2:3], s[20:21], 0, v[0:1]
	v_readfirstlane_b32 s20, v134
	v_add_u32_e32 v9, 0x2000, v134
	s_mov_b32 m0, s20
	v_readfirstlane_b32 s20, v9
	v_add_u32_e32 v9, 0x4000, v134
	s_waitcnt vmcnt(63) expcnt(7) lgkmcnt(15)
	s_barrier
	global_load_lds_dwordx4 v[2:3], off
	v_lshl_add_u64 v[4:5], v[2:3], 0, s[6:7]
	s_mov_b32 m0, s20
	v_readfirstlane_b32 s20, v9
	global_load_lds_dwordx4 v[4:5], off
	v_lshl_add_u64 v[4:5], v[2:3], 0, s[8:9]
	s_mov_b32 m0, s20
	s_lshl_b32 s31, s4, 20
	global_load_lds_dwordx4 v[4:5], off
	v_add_u32_e32 v4, 0x6000, v134
	s_add_u32 s36, s41, s31
	v_readfirstlane_b32 s20, v4
	v_add_u32_e32 v4, 0x8000, v134
	s_addc_u32 s37, s42, 0
	v_lshl_add_u64 v[2:3], v[2:3], 0, s[10:11]
	s_mov_b32 m0, s20
	v_readfirstlane_b32 s20, v4
	v_add_u32_e32 v9, 0xa000, v134
	global_load_lds_dwordx4 v[2:3], off
	v_lshl_add_u64 v[2:3], s[36:37], 0, v[0:1]
	s_mov_b32 m0, s20
	v_readfirstlane_b32 s20, v9
	v_add_u32_e32 v9, 0xc000, v134
	global_load_lds_dwordx4 v[2:3], off
	v_lshl_add_u64 v[4:5], v[2:3], 0, s[6:7]
	s_mov_b32 m0, s20
	v_readfirstlane_b32 s20, v9
	global_load_lds_dwordx4 v[4:5], off
	v_lshl_add_u64 v[4:5], v[2:3], 0, s[8:9]
	s_mov_b32 m0, s20
	v_lshl_add_u64 v[2:3], v[2:3], 0, s[10:11]
	global_load_lds_dwordx4 v[4:5], off
	v_add_u32_e32 v4, 0xe000, v134
	v_mov_b32_e32 v36, 0
	v_readfirstlane_b32 s20, v4
	s_mov_b32 m0, s20
	v_ashrrev_i32_e32 v4, 6, v6
	global_load_lds_dwordx4 v[2:3], off
	s_or_b32 s20, s39, s38
	v_lshrrev_b32_e32 v5, 30, v4
	s_ashr_i32 s21, s20, 31
	v_add_u32_e32 v5, v4, v5
	s_lshl_b64 s[20:21], s[20:21], 20
	v_bfe_u32 v2, v6, 4, 2
	v_bfe_u32 v3, v6, 1, 3
	v_and_b32_e32 v6, 0x7fffc, v5
	s_add_u32 s20, s34, s20
	v_sub_u32_e32 v4, v4, v6
	s_addc_u32 s21, s35, s21
	v_lshlrev_b32_e32 v136, 13, v4
	v_bitop3_b32 v4, v7, v3, 3 bitop3:0x6c
	v_bitop3_b32 v2, v2, v3, 4 bitop3:0x36
	v_lshl_add_u64 v[130:131], s[20:21], 0, v[0:1]
	s_add_u32 s20, s34, s31
	v_lshlrev_b32_e32 v5, 12, v5
	v_lshlrev_b32_e32 v4, 3, v4
	v_lshlrev_b32_e32 v2, 3, v2
	s_addc_u32 s21, s35, 0
	v_and_b32_e32 v135, 0xffffc000, v5
	v_lshl_add_u64 v[132:133], s[20:21], 0, v[0:1]
	s_mov_b64 s[36:37], 0
	v_lshlrev_b32_e32 v137, 1, v8
	v_lshlrev_b32_e32 v138, 1, v4
	v_lshlrev_b32_e32 v139, 1, v2
	s_mov_b32 s45, 0
	s_mov_b32 s31, 0
	v_mov_b32_e32 v37, v36
	v_mov_b32_e32 v38, v36
	v_mov_b32_e32 v39, v36
	v_mov_b32_e32 v40, v36
	v_mov_b32_e32 v41, v36
	v_mov_b32_e32 v42, v36
	v_mov_b32_e32 v43, v36
	v_mov_b32_e32 v0, v36
	v_mov_b32_e32 v1, v36
	v_mov_b32_e32 v2, v36
	v_mov_b32_e32 v3, v36
	v_mov_b32_e32 v4, v36
	v_mov_b32_e32 v5, v36
	v_mov_b32_e32 v6, v36
	v_mov_b32_e32 v7, v36
	v_mov_b32_e32 v8, v36
	v_mov_b32_e32 v9, v36
	v_mov_b32_e32 v10, v36
	v_mov_b32_e32 v11, v36
	v_mov_b32_e32 v12, v36
	v_mov_b32_e32 v13, v36
	v_mov_b32_e32 v14, v36
	v_mov_b32_e32 v15, v36
	v_mov_b32_e32 v16, v36
	v_mov_b32_e32 v17, v36
	v_mov_b32_e32 v18, v36
	v_mov_b32_e32 v19, v36
	v_mov_b32_e32 v20, v36
	v_mov_b32_e32 v21, v36
	v_mov_b32_e32 v22, v36
	v_mov_b32_e32 v23, v36
	v_mov_b32_e32 v24, v36
	v_mov_b32_e32 v25, v36
	v_mov_b32_e32 v26, v36
	v_mov_b32_e32 v27, v36
	v_mov_b32_e32 v28, v36
	v_mov_b32_e32 v29, v36
	v_mov_b32_e32 v30, v36
	v_mov_b32_e32 v31, v36
	v_mov_b32_e32 v32, v36
	v_mov_b32_e32 v33, v36
	v_mov_b32_e32 v34, v36
	v_mov_b32_e32 v35, v36
	v_mov_b32_e32 v44, v36
	v_mov_b32_e32 v45, v36
	v_mov_b32_e32 v46, v36
	v_mov_b32_e32 v47, v36
	v_mov_b32_e32 v48, v36
	v_mov_b32_e32 v49, v36
	v_mov_b32_e32 v50, v36
	v_mov_b32_e32 v51, v36
	v_mov_b32_e32 v52, v36
	v_mov_b32_e32 v53, v36
	v_mov_b32_e32 v54, v36
	v_mov_b32_e32 v55, v36
	v_mov_b32_e32 v56, v36
	v_mov_b32_e32 v57, v36
	v_mov_b32_e32 v58, v36
	v_mov_b32_e32 v59, v36
	v_mov_b32_e32 v60, v36
	v_mov_b32_e32 v61, v36
	v_mov_b32_e32 v62, v36
	v_mov_b32_e32 v63, v36
	v_mov_b32_e32 v64, v36
	v_mov_b32_e32 v65, v36
	v_mov_b32_e32 v66, v36
	v_mov_b32_e32 v67, v36
	v_mov_b32_e32 v68, v36
	v_mov_b32_e32 v69, v36
	v_mov_b32_e32 v70, v36
	v_mov_b32_e32 v71, v36
	v_mov_b32_e32 v72, v36
	v_mov_b32_e32 v73, v36
	v_mov_b32_e32 v74, v36
	v_mov_b32_e32 v75, v36
	v_mov_b32_e32 v76, v36
	v_mov_b32_e32 v77, v36
	v_mov_b32_e32 v78, v36
	v_mov_b32_e32 v79, v36
	v_mov_b32_e32 v80, v36
	v_mov_b32_e32 v81, v36
	v_mov_b32_e32 v82, v36
	v_mov_b32_e32 v83, v36
	v_mov_b32_e32 v84, v36
	v_mov_b32_e32 v85, v36
	v_mov_b32_e32 v86, v36
	v_mov_b32_e32 v87, v36
	v_mov_b32_e32 v88, v36
	v_mov_b32_e32 v89, v36
	v_mov_b32_e32 v90, v36
	v_mov_b32_e32 v91, v36
	v_mov_b32_e32 v92, v36
	v_mov_b32_e32 v93, v36
	v_mov_b32_e32 v94, v36
	v_mov_b32_e32 v95, v36
	v_mov_b32_e32 v96, v36
	v_mov_b32_e32 v97, v36
	v_mov_b32_e32 v98, v36
	v_mov_b32_e32 v99, v36
	v_mov_b32_e32 v100, v36
	v_mov_b32_e32 v101, v36
	v_mov_b32_e32 v102, v36
	v_mov_b32_e32 v103, v36
	v_mov_b32_e32 v104, v36
	v_mov_b32_e32 v105, v36
	v_mov_b32_e32 v106, v36
	v_mov_b32_e32 v107, v36
	v_mov_b32_e32 v108, v36
	v_mov_b32_e32 v109, v36
	v_mov_b32_e32 v110, v36
	v_mov_b32_e32 v111, v36
	v_mov_b32_e32 v112, v36
	v_mov_b32_e32 v113, v36
	v_mov_b32_e32 v114, v36
	v_mov_b32_e32 v115, v36
	v_mov_b32_e32 v116, v36
	v_mov_b32_e32 v117, v36
	v_mov_b32_e32 v118, v36
	v_mov_b32_e32 v119, v36
	v_mov_b32_e32 v120, v36
	v_mov_b32_e32 v121, v36
	v_mov_b32_e32 v122, v36
	v_mov_b32_e32 v123, v36
	v_mov_b32_e32 v124, v36
	v_mov_b32_e32 v125, v36
	v_mov_b32_e32 v126, v36
	v_mov_b32_e32 v127, v36
	s_waitcnt vmcnt(0) lgkmcnt(0)
	s_barrier
	v_add3_u32 v141, v135, v137, v138
	v_add3_u32 v210, v136, v137, v138
	v_add3_u32 v180, v135, v137, v139
	v_add3_u32 v211, v136, v137, v139
	v_readfirstlane_b32 s45, v134
	ds_read_b128 v[142:145], v141
	ds_read_b128 v[146:149], v141 offset:2048
	ds_read_b128 v[150:153], v141 offset:4096
	ds_read_b128 v[154:157], v141 offset:6144
	ds_read_b128 v[174:177], v210 offset:32768
	ds_read_b128 v[182:185], v210 offset:34816
	ds_read_b128 v[186:189], v210 offset:36864
	ds_read_b128 v[190:193], v210 offset:38912
	s_mov_b32 s31, 0
	s_mov_b64 s[36:37], s[34:35]
	v_subrev_u32_e32 v178, s34, v130
	v_subrev_u32_e32 v179, s34, v132
	s_add_u32 s45, s45, 0x10000
	s_mov_b32 m0, s45
	s_add_u32 s38, s36, s12
	s_addc_u32 s39, s37, s13
	global_load_lds_dwordx4 v178, s[38:39]
	s_add_u32 m0, s45, 0x2000
	s_add_u32 s38, s36, s14
	s_addc_u32 s39, s37, s15
	global_load_lds_dwordx4 v178, s[38:39]
	s_add_u32 m0, s45, 0x4000
	s_add_u32 s38, s36, s16
	s_addc_u32 s39, s37, s17
	global_load_lds_dwordx4 v178, s[38:39]
	s_add_u32 m0, s45, 0x6000
	s_add_u32 s38, s36, s18
	s_addc_u32 s39, s37, s19
	global_load_lds_dwordx4 v178, s[38:39]
	s_add_u32 m0, s45, 0x8000
	s_add_u32 s38, s36, s22
	s_addc_u32 s39, s37, s23
	global_load_lds_dwordx4 v179, s[38:39]
	s_add_u32 m0, s45, 0xa000
	s_add_u32 s38, s36, s24
	s_addc_u32 s39, s37, s25
	global_load_lds_dwordx4 v179, s[38:39]
	s_add_u32 m0, s45, 0xc000
	s_add_u32 s38, s36, s26
	s_addc_u32 s39, s37, s27
	global_load_lds_dwordx4 v179, s[38:39]
	s_add_u32 m0, s45, 0xe000
	s_add_u32 s38, s36, s28
	s_addc_u32 s39, s37, s29
	global_load_lds_dwordx4 v179, s[38:39]
	s_branch .Lg11_entry
.Lg11_top:
	s_waitcnt lgkmcnt(0)
	s_waitcnt vmcnt(0)
	s_barrier
	v_xor_b32_e32 v141, 0x10000, v141
	v_xor_b32_e32 v210, 0x10000, v210
	v_xor_b32_e32 v180, 0x10000, v180
	v_xor_b32_e32 v211, 0x10000, v211
	s_xor_b32 s45, s45, 0x10000
	ds_read_b128 v[142:145], v141
	ds_read_b128 v[146:149], v141 offset:2048
	ds_read_b128 v[150:153], v141 offset:4096
	ds_read_b128 v[154:157], v141 offset:6144
	ds_read_b128 v[174:177], v210 offset:32768
	ds_read_b128 v[182:185], v210 offset:34816
	ds_read_b128 v[186:189], v210 offset:36864
	ds_read_b128 v[190:193], v210 offset:38912
	v_mfma_f32_16x16x32_bf16 v[60:63], v[158:161], v[194:197], v[60:63]
	v_mfma_f32_16x16x32_bf16 v[56:59], v[158:161], v[198:201], v[56:59]
	s_mov_b32 m0, s45
	s_add_u32 s38, s36, s12
	s_addc_u32 s39, s37, s13
	global_load_lds_dwordx4 v178, s[38:39]
	v_mfma_f32_16x16x32_bf16 v[52:55], v[158:161], v[202:205], v[52:55]
	v_mfma_f32_16x16x32_bf16 v[48:51], v[158:161], v[206:209], v[48:51]
	s_add_u32 m0, s45, 0x2000
	s_add_u32 s38, s36, s14
	s_addc_u32 s39, s37, s15
	global_load_lds_dwordx4 v178, s[38:39]
	v_mfma_f32_16x16x32_bf16 v[44:47], v[162:165], v[194:197], v[44:47]
	v_mfma_f32_16x16x32_bf16 v[32:35], v[162:165], v[198:201], v[32:35]
	s_add_u32 m0, s45, 0x4000
	s_add_u32 s38, s36, s16
	s_addc_u32 s39, s37, s17
	global_load_lds_dwordx4 v178, s[38:39]
	v_mfma_f32_16x16x32_bf16 v[28:31], v[162:165], v[202:205], v[28:31]
	v_mfma_f32_16x16x32_bf16 v[24:27], v[162:165], v[206:209], v[24:27]
	s_add_u32 m0, s45, 0x6000
	s_add_u32 s38, s36, s18
	s_addc_u32 s39, s37, s19
	global_load_lds_dwordx4 v178, s[38:39]
	v_mfma_f32_16x16x32_bf16 v[20:23], v[166:169], v[194:197], v[20:23]
	v_mfma_f32_16x16x32_bf16 v[16:19], v[166:169], v[198:201], v[16:19]
	s_add_u32 m0, s45, 0x8000
	s_add_u32 s38, s36, s22
	s_addc_u32 s39, s37, s23
	global_load_lds_dwordx4 v179, s[38:39]
	v_mfma_f32_16x16x32_bf16 v[12:15], v[166:169], v[202:205], v[12:15]
	v_mfma_f32_16x16x32_bf16 v[8:11], v[166:169], v[206:209], v[8:11]
	s_add_u32 m0, s45, 0xa000
	s_add_u32 s38, s36, s24
	s_addc_u32 s39, s37, s25
	global_load_lds_dwordx4 v179, s[38:39]
	v_mfma_f32_16x16x32_bf16 v[4:7], v[170:173], v[194:197], v[4:7]
	v_mfma_f32_16x16x32_bf16 v[0:3], v[170:173], v[198:201], v[0:3]
	s_add_u32 m0, s45, 0xc000
	s_add_u32 s38, s36, s26
	s_addc_u32 s39, s37, s27
	global_load_lds_dwordx4 v179, s[38:39]
	v_mfma_f32_16x16x32_bf16 v[40:43], v[170:173], v[202:205], v[40:43]
	v_mfma_f32_16x16x32_bf16 v[36:39], v[170:173], v[206:209], v[36:39]
	s_add_u32 m0, s45, 0xe000
	s_add_u32 s38, s36, s28
	s_addc_u32 s39, s37, s29
	global_load_lds_dwordx4 v179, s[38:39]
